# loop-edge edit: back-edge counter/pointer SALU block hoisted above the K-loop's final barrier in all ten GEMM loops (only the branch follows the barrier)
# baseline (speedup 1.0000x reference)
; #define PG8_STAGE(bufoff, gbase, voff) do { _Pragma("unroll") for (int _i = 0; _i < 2; ++_i) { \
;         const unsigned _m0 = ldsu + (unsigned)(bufoff) + ldsw + (unsigned)(_i * 8192); \
;         asm volatile("s_mov_b32 m0, %2\n\ts_nop 0\n\tglobal_load_lds_dwordx4 %0, %1" :: "v"((voff)[_i]), "s"((const char*)(gbase)), "s"(_m0) : "memory"); } } while (0)
; #define PG8_LDA(dst, b, h) do { _Pragma("unroll") for (int m = 0; m < 4; ++m) _Pragma("unroll") for (int k = 0; k < 2; ++k) dst[m][k] = *(const LAS bf16x8*)(lds + PG8_SA(b, h) + aoff + m * 2048 + k * 1024); } while (0)
; #define PG8_LDB(dst, b, h) do { _Pragma("unroll") for (int n = 0; n < 2; ++n) _Pragma("unroll") for (int k = 0; k < 2; ++k) dst[n][k] = *(const LAS bf16x8*)(lds + bbase[b][h] + n * 2048 + k * 1024); } while (0)
; #define PG8_WAIT_V(n) asm volatile("s_waitcnt vmcnt(" #n ")" ::: "memory")
; #define PG8_WAIT_L(n) asm volatile("s_waitcnt lgkmcnt(" #n ")" ::: "memory")
; #define PG8_BAR __builtin_amdgcn_s_barrier()
; #define PG8_SCHED __builtin_amdgcn_sched_barrier(0)
; template <class Epi>
; __device__ __forceinline__ void gemm_phase(LAS unsigned char* lds, const Gemm g, const StaticOrder& S, const Epi& E) {
;     ...
;             PG8_LDB(B0, 0, 0); PG8_SCHED; PG8_LDA(At, 0, 0); PG8_LDA(At2, 0, 1); PG8_STAGE(PG8_SB(1, 1), b1 + hstepB, voffB);
;             PG8_WAIT_V(8); PG8_WAIT_L(0); PG8_BAR; PG8_MMA2B(0, At, At2, B0); PG8_BAR; PG8_SCHED;
;             PG8_LDB(B0, 0, 1); PG8_STAGE(PG8_SB(0, 0), b2, voffB); PG8_STAGE(PG8_SA(0, 0), a2, voffA); PG8_STAGE(PG8_SA(0, 1), a2 + hstepA, voffA);
;             PG8_WAIT_V(8); PG8_WAIT_L(0); PG8_BAR; PG8_MMA2B(1, At, At2, B0); PG8_BAR; PG8_SCHED;
;             PG8_LDB(B0, 1, 0); PG8_SCHED; PG8_LDA(At, 1, 0); PG8_LDA(At2, 1, 1); PG8_STAGE(PG8_SB(0, 1), b2 + hstepB, voffB);
;             PG8_WAIT_V(8); PG8_WAIT_L(0); PG8_BAR; PG8_MMA2B(0, At, At2, B0); PG8_BAR; PG8_SCHED;
;             PG8_LDB(B0, 1, 1); PG8_STAGE(PG8_SB(1, 0), b3, voffB); PG8_STAGE(PG8_SA(1, 0), a3, voffA); PG8_STAGE(PG8_SA(1, 1), a3 + hstepA, voffA);
;             PG8_WAIT_V(8); PG8_WAIT_L(0); PG8_BAR; PG8_MMA2B(1, At, At2, B0); PG8_BAR; PG8_SCHED;
.LBB0_233:
	ds_read_b128 v[130:133], v142
	ds_read_b128 v[148:151], v142 offset:1024
	ds_read_b128 v[152:155], v142 offset:2048
	ds_read_b128 v[156:159], v142 offset:3072
	s_add_u32 s8, s4, 0x100
	s_addc_u32 s9, s5, 0
	s_cmp_eq_u32 s62, 12
	s_cselect_b32 s10, s58, s60
	s_cselect_b32 s11, s15, s61
	s_cselect_b32 s80, s59, s8
	s_cselect_b32 s81, s13, s9
	s_add_u32 s38, s10, 0x80
	s_addc_u32 s39, s11, 0
	ds_read_b128 v[166:169], v143
	ds_read_b128 v[178:181], v143 offset:1024
	ds_read_b128 v[182:185], v143 offset:2048
	ds_read_b128 v[186:189], v143 offset:3072
	ds_read_b128 v[190:193], v143 offset:4096
	ds_read_b128 v[194:197], v143 offset:5120
	ds_read_b128 v[198:201], v143 offset:6144
	ds_read_b128 v[202:205], v143 offset:7168
	ds_read_b128 v[214:217], v143 offset:16384
	ds_read_b128 v[218:221], v143 offset:17408
	ds_read_b128 v[222:225], v143 offset:18432
	ds_read_b128 v[226:229], v143 offset:19456
	ds_read_b128 v[230:233], v143 offset:20480
	ds_read_b128 v[234:237], v143 offset:21504
	ds_read_b128 v[238:241], v143 offset:22528
	ds_read_b128 v[242:245], v143 offset:23552
	s_add_u32 s4, s4, 0x40080
	s_addc_u32 s5, s5, 0
	s_mov_b32 m0, s84
	s_nop 0
	global_load_lds_dwordx4 v137, s[4:5]
	s_mov_b32 m0, s85
	s_nop 0
	global_load_lds_dwordx4 v139, s[4:5]
	s_waitcnt vmcnt(8)
	s_waitcnt lgkmcnt(0)
	s_barrier
	s_waitcnt lgkmcnt(14)
	v_mfma_f32_16x16x32_bf16 v[124:127], v[130:133], v[166:169], v[124:127]
	v_mfma_f32_16x16x32_bf16 v[120:123], v[152:155], v[166:169], v[120:123]
	s_waitcnt lgkmcnt(13)
	v_mfma_f32_16x16x32_bf16 v[108:111], v[130:133], v[182:185], v[108:111]
	v_mfma_f32_16x16x32_bf16 v[104:107], v[152:155], v[182:185], v[104:107]
	s_waitcnt lgkmcnt(11)
	v_mfma_f32_16x16x32_bf16 v[92:95], v[130:133], v[190:193], v[92:95]
	v_mfma_f32_16x16x32_bf16 v[88:91], v[152:155], v[190:193], v[88:91]
	s_waitcnt lgkmcnt(9)
	v_mfma_f32_16x16x32_bf16 v[76:79], v[130:133], v[198:201], v[76:79]
	v_mfma_f32_16x16x32_bf16 v[72:75], v[152:155], v[198:201], v[72:75]
	s_waitcnt lgkmcnt(7)
	v_mfma_f32_16x16x32_bf16 v[60:63], v[130:133], v[214:217], v[60:63]
	v_mfma_f32_16x16x32_bf16 v[56:59], v[152:155], v[214:217], v[56:59]
	s_waitcnt lgkmcnt(5)
	v_mfma_f32_16x16x32_bf16 v[44:47], v[130:133], v[222:225], v[44:47]
	v_mfma_f32_16x16x32_bf16 v[40:43], v[152:155], v[222:225], v[40:43]
	s_waitcnt lgkmcnt(3)
	v_mfma_f32_16x16x32_bf16 v[28:31], v[130:133], v[230:233], v[28:31]
	v_mfma_f32_16x16x32_bf16 v[24:27], v[152:155], v[230:233], v[24:27]
	s_waitcnt lgkmcnt(1)
	v_mfma_f32_16x16x32_bf16 v[12:15], v[130:133], v[238:241], v[12:15]
	v_mfma_f32_16x16x32_bf16 v[8:11], v[152:155], v[238:241], v[8:11]
	v_mfma_f32_16x16x32_bf16 v[124:127], v[148:151], v[178:181], v[124:127]
	v_mfma_f32_16x16x32_bf16 v[120:123], v[156:159], v[178:181], v[120:123]
	v_mfma_f32_16x16x32_bf16 v[108:111], v[148:151], v[186:189], v[108:111]
	v_mfma_f32_16x16x32_bf16 v[104:107], v[156:159], v[186:189], v[104:107]
	v_mfma_f32_16x16x32_bf16 v[92:95], v[148:151], v[194:197], v[92:95]
	v_mfma_f32_16x16x32_bf16 v[88:91], v[156:159], v[194:197], v[88:91]
	v_mfma_f32_16x16x32_bf16 v[76:79], v[148:151], v[202:205], v[76:79]
	v_mfma_f32_16x16x32_bf16 v[72:75], v[156:159], v[202:205], v[72:75]
	v_mfma_f32_16x16x32_bf16 v[60:63], v[148:151], v[218:221], v[60:63]
	v_mfma_f32_16x16x32_bf16 v[56:59], v[156:159], v[218:221], v[56:59]
	v_mfma_f32_16x16x32_bf16 v[44:47], v[148:151], v[226:229], v[44:47]
	v_mfma_f32_16x16x32_bf16 v[40:43], v[156:159], v[226:229], v[40:43]
	v_mfma_f32_16x16x32_bf16 v[28:31], v[148:151], v[234:237], v[28:31]
	v_mfma_f32_16x16x32_bf16 v[24:27], v[156:159], v[234:237], v[24:27]
	s_waitcnt lgkmcnt(0)
	v_mfma_f32_16x16x32_bf16 v[12:15], v[148:151], v[242:245], v[12:15]
	v_mfma_f32_16x16x32_bf16 v[8:11], v[156:159], v[242:245], v[8:11]
	s_barrier
	ds_read_b128 v[130:133], v144
	ds_read_b128 v[148:151], v144 offset:1024
	ds_read_b128 v[152:155], v144 offset:2048
	ds_read_b128 v[156:159], v144 offset:3072
	s_mov_b32 m0, s29
	s_nop 0
	global_load_lds_dwordx4 v137, s[80:81]
	s_mov_b32 m0, s37
	s_nop 0
	global_load_lds_dwordx4 v139, s[80:81]
	s_mov_b32 m0, s28
	s_nop 0
	global_load_lds_dwordx4 v136, s[10:11]
	s_mov_b32 m0, s47
	s_nop 0
	global_load_lds_dwordx4 v138, s[10:11]
	s_add_u32 s4, s10, 0x40000
	s_addc_u32 s5, s11, 0
	s_mov_b32 m0, s48
	s_nop 0
	global_load_lds_dwordx4 v136, s[4:5]
	s_mov_b32 m0, s49
	s_nop 0
	global_load_lds_dwordx4 v138, s[4:5]
	s_waitcnt vmcnt(8)
	s_waitcnt lgkmcnt(0)
	s_barrier
	s_waitcnt lgkmcnt(3)
	v_mfma_f32_16x16x32_bf16 v[116:119], v[130:133], v[166:169], v[116:119]
	s_waitcnt lgkmcnt(1)
	v_mfma_f32_16x16x32_bf16 v[112:115], v[152:155], v[166:169], v[112:115]
	v_mfma_f32_16x16x32_bf16 v[100:103], v[130:133], v[182:185], v[100:103]
	v_mfma_f32_16x16x32_bf16 v[96:99], v[152:155], v[182:185], v[96:99]
	v_mfma_f32_16x16x32_bf16 v[84:87], v[130:133], v[190:193], v[84:87]
	v_mfma_f32_16x16x32_bf16 v[80:83], v[152:155], v[190:193], v[80:83]
	v_mfma_f32_16x16x32_bf16 v[68:71], v[130:133], v[198:201], v[68:71]
	v_mfma_f32_16x16x32_bf16 v[64:67], v[152:155], v[198:201], v[64:67]
	v_mfma_f32_16x16x32_bf16 v[52:55], v[130:133], v[214:217], v[52:55]
	v_mfma_f32_16x16x32_bf16 v[48:51], v[152:155], v[214:217], v[48:51]
	v_mfma_f32_16x16x32_bf16 v[36:39], v[130:133], v[222:225], v[36:39]
	v_mfma_f32_16x16x32_bf16 v[32:35], v[152:155], v[222:225], v[32:35]
	v_mfma_f32_16x16x32_bf16 v[20:23], v[130:133], v[230:233], v[20:23]
	v_mfma_f32_16x16x32_bf16 v[16:19], v[152:155], v[230:233], v[16:19]
	v_mfma_f32_16x16x32_bf16 v[4:7], v[130:133], v[238:241], v[4:7]
	v_mfma_f32_16x16x32_bf16 v[0:3], v[152:155], v[238:241], v[0:3]
	v_mfma_f32_16x16x32_bf16 v[116:119], v[148:151], v[178:181], v[116:119]
	s_waitcnt lgkmcnt(0)
	v_mfma_f32_16x16x32_bf16 v[112:115], v[156:159], v[178:181], v[112:115]
	v_mfma_f32_16x16x32_bf16 v[100:103], v[148:151], v[186:189], v[100:103]
	v_mfma_f32_16x16x32_bf16 v[96:99], v[156:159], v[186:189], v[96:99]
	v_mfma_f32_16x16x32_bf16 v[84:87], v[148:151], v[194:197], v[84:87]
	v_mfma_f32_16x16x32_bf16 v[80:83], v[156:159], v[194:197], v[80:83]
	v_mfma_f32_16x16x32_bf16 v[68:71], v[148:151], v[202:205], v[68:71]
	v_mfma_f32_16x16x32_bf16 v[64:67], v[156:159], v[202:205], v[64:67]
	v_mfma_f32_16x16x32_bf16 v[52:55], v[148:151], v[218:221], v[52:55]
	v_mfma_f32_16x16x32_bf16 v[48:51], v[156:159], v[218:221], v[48:51]
	v_mfma_f32_16x16x32_bf16 v[36:39], v[148:151], v[226:229], v[36:39]
	v_mfma_f32_16x16x32_bf16 v[32:35], v[156:159], v[226:229], v[32:35]
	v_mfma_f32_16x16x32_bf16 v[20:23], v[148:151], v[234:237], v[20:23]
	v_mfma_f32_16x16x32_bf16 v[16:19], v[156:159], v[234:237], v[16:19]
	v_mfma_f32_16x16x32_bf16 v[4:7], v[148:151], v[242:245], v[4:7]
	v_mfma_f32_16x16x32_bf16 v[0:3], v[156:159], v[242:245], v[0:3]
	s_barrier
; #define PG8_STAGE(bufoff, gbase, voff) do { _Pragma("unroll") for (int _i = 0; _i < 2; ++_i) { \
;         const unsigned _m0 = ldsu + (unsigned)(bufoff) + ldsw + (unsigned)(_i * 8192); \
;         asm volatile("s_mov_b32 m0, %2\n\ts_nop 0\n\tglobal_load_lds_dwordx4 %0, %1" :: "v"((voff)[_i]), "s"((const char*)(gbase)), "s"(_m0) : "memory"); } } while (0)
; #define PG8_LDA(dst, b, h) do { _Pragma("unroll") for (int m = 0; m < 4; ++m) _Pragma("unroll") for (int k = 0; k < 2; ++k) dst[m][k] = *(const LAS bf16x8*)(lds + PG8_SA(b, h) + aoff + m * 2048 + k * 1024); } while (0)
; #define PG8_LDB(dst, b, h) do { _Pragma("unroll") for (int n = 0; n < 2; ++n) _Pragma("unroll") for (int k = 0; k < 2; ++k) dst[n][k] = *(const LAS bf16x8*)(lds + bbase[b][h] + n * 2048 + k * 1024); } while (0)
; #define PG8_WAIT_V(n) asm volatile("s_waitcnt vmcnt(" #n ")" ::: "memory")
; #define PG8_WAIT_L(n) asm volatile("s_waitcnt lgkmcnt(" #n ")" ::: "memory")
; #define PG8_BAR __builtin_amdgcn_s_barrier()
; #define PG8_SCHED __builtin_amdgcn_sched_barrier(0)
; template <class Epi>
; __device__ __forceinline__ void gemm_phase(LAS unsigned char* lds, const Gemm g, const StaticOrder& S, const Epi& E) {
;     ...
;             PG8_LDB(B0, 0, 0); PG8_SCHED; PG8_LDA(At, 0, 0); PG8_LDA(At2, 0, 1); PG8_STAGE(PG8_SB(1, 1), b1 + hstepB, voffB);
;             PG8_WAIT_V(8); PG8_WAIT_L(0); PG8_BAR; PG8_MMA2B(0, At, At2, B0); PG8_BAR; PG8_SCHED;
;             PG8_LDB(B0, 0, 1); PG8_STAGE(PG8_SB(0, 0), b2, voffB); PG8_STAGE(PG8_SA(0, 0), a2, voffA); PG8_STAGE(PG8_SA(0, 1), a2 + hstepA, voffA);
;             PG8_WAIT_V(8); PG8_WAIT_L(0); PG8_BAR; PG8_MMA2B(1, At, At2, B0); PG8_BAR; PG8_SCHED;
;             PG8_LDB(B0, 1, 0); PG8_SCHED; PG8_LDA(At, 1, 0); PG8_LDA(At2, 1, 1); PG8_STAGE(PG8_SB(0, 1), b2 + hstepB, voffB);
;             PG8_WAIT_V(8); PG8_WAIT_L(0); PG8_BAR; PG8_MMA2B(0, At, At2, B0); PG8_BAR; PG8_SCHED;
;             PG8_LDB(B0, 1, 1); PG8_STAGE(PG8_SB(1, 0), b3, voffB); PG8_STAGE(PG8_SA(1, 0), a3, voffA); PG8_STAGE(PG8_SA(1, 1), a3 + hstepA, voffA);
;             PG8_WAIT_V(8); PG8_WAIT_L(0); PG8_BAR; PG8_MMA2B(1, At, At2, B0); PG8_BAR; PG8_SCHED;
;         }
	ds_read_b128 v[130:133], v145
	ds_read_b128 v[148:151], v145 offset:1024
	ds_read_b128 v[152:155], v145 offset:2048
	ds_read_b128 v[156:159], v145 offset:3072
	ds_read_b128 v[166:169], v143 offset:32768
	ds_read_b128 v[178:181], v143 offset:33792
	ds_read_b128 v[182:185], v143 offset:34816
	ds_read_b128 v[186:189], v143 offset:35840
	ds_read_b128 v[190:193], v143 offset:36864
	ds_read_b128 v[194:197], v143 offset:37888
	ds_read_b128 v[198:201], v143 offset:38912
	ds_read_b128 v[202:205], v143 offset:39936
	ds_read_b128 v[214:217], v143 offset:49152
	ds_read_b128 v[218:221], v143 offset:50176
	ds_read_b128 v[222:225], v143 offset:51200
	ds_read_b128 v[226:229], v143 offset:52224
	ds_read_b128 v[230:233], v143 offset:53248
	ds_read_b128 v[234:237], v143 offset:54272
	ds_read_b128 v[238:241], v143 offset:55296
	ds_read_b128 v[242:245], v143 offset:56320
	s_add_u32 s4, s80, 0x40000
	s_addc_u32 s5, s81, 0
	s_mov_b32 m0, s50
	s_nop 0
	global_load_lds_dwordx4 v137, s[4:5]
	s_mov_b32 m0, s51
	s_nop 0
	global_load_lds_dwordx4 v139, s[4:5]
	s_waitcnt vmcnt(8)
	s_waitcnt lgkmcnt(0)
	s_barrier
	s_waitcnt lgkmcnt(14)
	v_mfma_f32_16x16x32_bf16 v[124:127], v[130:133], v[166:169], v[124:127]
	v_mfma_f32_16x16x32_bf16 v[120:123], v[152:155], v[166:169], v[120:123]
	s_waitcnt lgkmcnt(13)
	v_mfma_f32_16x16x32_bf16 v[108:111], v[130:133], v[182:185], v[108:111]
	v_mfma_f32_16x16x32_bf16 v[104:107], v[152:155], v[182:185], v[104:107]
	s_waitcnt lgkmcnt(11)
	v_mfma_f32_16x16x32_bf16 v[92:95], v[130:133], v[190:193], v[92:95]
	v_mfma_f32_16x16x32_bf16 v[88:91], v[152:155], v[190:193], v[88:91]
	s_waitcnt lgkmcnt(9)
	v_mfma_f32_16x16x32_bf16 v[76:79], v[130:133], v[198:201], v[76:79]
	v_mfma_f32_16x16x32_bf16 v[72:75], v[152:155], v[198:201], v[72:75]
	s_waitcnt lgkmcnt(7)
	v_mfma_f32_16x16x32_bf16 v[60:63], v[130:133], v[214:217], v[60:63]
	v_mfma_f32_16x16x32_bf16 v[56:59], v[152:155], v[214:217], v[56:59]
	s_waitcnt lgkmcnt(5)
	v_mfma_f32_16x16x32_bf16 v[44:47], v[130:133], v[222:225], v[44:47]
	v_mfma_f32_16x16x32_bf16 v[40:43], v[152:155], v[222:225], v[40:43]
	s_waitcnt lgkmcnt(3)
	v_mfma_f32_16x16x32_bf16 v[28:31], v[130:133], v[230:233], v[28:31]
	v_mfma_f32_16x16x32_bf16 v[24:27], v[152:155], v[230:233], v[24:27]
	s_waitcnt lgkmcnt(1)
	v_mfma_f32_16x16x32_bf16 v[12:15], v[130:133], v[238:241], v[12:15]
	v_mfma_f32_16x16x32_bf16 v[8:11], v[152:155], v[238:241], v[8:11]
	v_mfma_f32_16x16x32_bf16 v[124:127], v[148:151], v[178:181], v[124:127]
	v_mfma_f32_16x16x32_bf16 v[120:123], v[156:159], v[178:181], v[120:123]
	v_mfma_f32_16x16x32_bf16 v[108:111], v[148:151], v[186:189], v[108:111]
	v_mfma_f32_16x16x32_bf16 v[104:107], v[156:159], v[186:189], v[104:107]
	v_mfma_f32_16x16x32_bf16 v[92:95], v[148:151], v[194:197], v[92:95]
	v_mfma_f32_16x16x32_bf16 v[88:91], v[156:159], v[194:197], v[88:91]
	v_mfma_f32_16x16x32_bf16 v[76:79], v[148:151], v[202:205], v[76:79]
	v_mfma_f32_16x16x32_bf16 v[72:75], v[156:159], v[202:205], v[72:75]
	v_mfma_f32_16x16x32_bf16 v[60:63], v[148:151], v[218:221], v[60:63]
	v_mfma_f32_16x16x32_bf16 v[56:59], v[156:159], v[218:221], v[56:59]
	v_mfma_f32_16x16x32_bf16 v[44:47], v[148:151], v[226:229], v[44:47]
	v_mfma_f32_16x16x32_bf16 v[40:43], v[156:159], v[226:229], v[40:43]
	v_mfma_f32_16x16x32_bf16 v[28:31], v[148:151], v[234:237], v[28:31]
	v_mfma_f32_16x16x32_bf16 v[24:27], v[156:159], v[234:237], v[24:27]
	s_waitcnt lgkmcnt(0)
	v_mfma_f32_16x16x32_bf16 v[12:15], v[148:151], v[242:245], v[12:15]
	v_mfma_f32_16x16x32_bf16 v[8:11], v[156:159], v[242:245], v[8:11]
	s_barrier
	s_add_u32 s4, s80, 0x80
	ds_read_b128 v[130:133], v146
	ds_read_b128 v[148:151], v146 offset:1024
	ds_read_b128 v[152:155], v146 offset:2048
	ds_read_b128 v[156:159], v146 offset:3072
	s_addc_u32 s5, s81, 0
	s_mov_b32 m0, s52
	s_nop 0
	global_load_lds_dwordx4 v137, s[4:5]
	s_mov_b32 m0, s53
	s_nop 0
	global_load_lds_dwordx4 v139, s[4:5]
	s_mov_b32 m0, s54
	s_nop 0
	global_load_lds_dwordx4 v136, s[38:39]
	s_mov_b32 m0, s55
	s_nop 0
	global_load_lds_dwordx4 v138, s[38:39]
	s_add_u32 s4, s10, 0x40080
	s_addc_u32 s5, s11, 0
	s_mov_b32 m0, s82
	s_nop 0
	global_load_lds_dwordx4 v136, s[4:5]
	s_mov_b32 m0, s83
	s_nop 0
	global_load_lds_dwordx4 v138, s[4:5]
	s_waitcnt vmcnt(8)
	s_waitcnt lgkmcnt(0)
	s_barrier
	s_waitcnt lgkmcnt(3)
	v_mfma_f32_16x16x32_bf16 v[116:119], v[130:133], v[166:169], v[116:119]
	s_waitcnt lgkmcnt(1)
	v_mfma_f32_16x16x32_bf16 v[112:115], v[152:155], v[166:169], v[112:115]
	v_mfma_f32_16x16x32_bf16 v[100:103], v[130:133], v[182:185], v[100:103]
	v_mfma_f32_16x16x32_bf16 v[96:99], v[152:155], v[182:185], v[96:99]
	v_mfma_f32_16x16x32_bf16 v[84:87], v[130:133], v[190:193], v[84:87]
	v_mfma_f32_16x16x32_bf16 v[80:83], v[152:155], v[190:193], v[80:83]
	v_mfma_f32_16x16x32_bf16 v[68:71], v[130:133], v[198:201], v[68:71]
	v_mfma_f32_16x16x32_bf16 v[64:67], v[152:155], v[198:201], v[64:67]
	v_mfma_f32_16x16x32_bf16 v[52:55], v[130:133], v[214:217], v[52:55]
	v_mfma_f32_16x16x32_bf16 v[48:51], v[152:155], v[214:217], v[48:51]
	v_mfma_f32_16x16x32_bf16 v[36:39], v[130:133], v[222:225], v[36:39]
	v_mfma_f32_16x16x32_bf16 v[32:35], v[152:155], v[222:225], v[32:35]
	v_mfma_f32_16x16x32_bf16 v[20:23], v[130:133], v[230:233], v[20:23]
	v_mfma_f32_16x16x32_bf16 v[16:19], v[152:155], v[230:233], v[16:19]
	v_mfma_f32_16x16x32_bf16 v[4:7], v[130:133], v[238:241], v[4:7]
	v_mfma_f32_16x16x32_bf16 v[0:3], v[152:155], v[238:241], v[0:3]
	v_mfma_f32_16x16x32_bf16 v[116:119], v[148:151], v[178:181], v[116:119]
	s_waitcnt lgkmcnt(0)
	v_mfma_f32_16x16x32_bf16 v[112:115], v[156:159], v[178:181], v[112:115]
	v_mfma_f32_16x16x32_bf16 v[100:103], v[148:151], v[186:189], v[100:103]
	v_mfma_f32_16x16x32_bf16 v[96:99], v[156:159], v[186:189], v[96:99]
	v_mfma_f32_16x16x32_bf16 v[84:87], v[148:151], v[194:197], v[84:87]
	v_mfma_f32_16x16x32_bf16 v[80:83], v[156:159], v[194:197], v[80:83]
	v_mfma_f32_16x16x32_bf16 v[68:71], v[148:151], v[202:205], v[68:71]
	v_mfma_f32_16x16x32_bf16 v[64:67], v[156:159], v[202:205], v[64:67]
	v_mfma_f32_16x16x32_bf16 v[52:55], v[148:151], v[218:221], v[52:55]
	v_mfma_f32_16x16x32_bf16 v[48:51], v[156:159], v[218:221], v[48:51]
	v_mfma_f32_16x16x32_bf16 v[36:39], v[148:151], v[226:229], v[36:39]
	v_mfma_f32_16x16x32_bf16 v[32:35], v[156:159], v[226:229], v[32:35]
	v_mfma_f32_16x16x32_bf16 v[20:23], v[148:151], v[234:237], v[20:23]
	v_mfma_f32_16x16x32_bf16 v[16:19], v[156:159], v[234:237], v[16:19]
	v_mfma_f32_16x16x32_bf16 v[4:7], v[148:151], v[242:245], v[4:7]
	v_mfma_f32_16x16x32_bf16 v[0:3], v[156:159], v[242:245], v[0:3]
	s_add_i32 s62, s62, 2
	s_add_u32 s60, s60, 0x100
	s_addc_u32 s61, s61, 0
	s_cmp_gt_u32 s62, 13
	s_mov_b64 s[4:5], s[8:9]
	s_barrier
	s_cbranch_scc0 .LBB0_233
	s_and_b64 vcc, exec, s[2:3]
	s_cbranch_vccz .LBB0_236
	s_barrier

; #define PG8_STAGE(bufoff, gbase, voff) do { _Pragma("unroll") for (int _i = 0; _i < 2; ++_i) { \
;         const unsigned _m0 = ldsu + (unsigned)(bufoff) + ldsw + (unsigned)(_i * 8192); \
;         asm volatile("s_mov_b32 m0, %2\n\ts_nop 0\n\tglobal_load_lds_dwordx4 %0, %1" :: "v"((voff)[_i]), "s"((const char*)(gbase)), "s"(_m0) : "memory"); } } while (0)
; #define PG8_LDA(dst, b, h) do { _Pragma("unroll") for (int m = 0; m < 4; ++m) _Pragma("unroll") for (int k = 0; k < 2; ++k) dst[m][k] = *(const LAS bf16x8*)(lds + PG8_SA(b, h) + aoff + m * 2048 + k * 1024); } while (0)
; #define PG8_LDB(dst, b, h) do { _Pragma("unroll") for (int n = 0; n < 2; ++n) _Pragma("unroll") for (int k = 0; k < 2; ++k) dst[n][k] = *(const LAS bf16x8*)(lds + bbase[b][h] + n * 2048 + k * 1024); } while (0)
; #define PG8_WAIT_V(n) asm volatile("s_waitcnt vmcnt(" #n ")" ::: "memory")
; #define PG8_WAIT_L(n) asm volatile("s_waitcnt lgkmcnt(" #n ")" ::: "memory")
; #define PG8_BAR __builtin_amdgcn_s_barrier()
; #define PG8_SCHED __builtin_amdgcn_sched_barrier(0)
; template <class Epi>
; __device__ __forceinline__ void gemm_phase(LAS unsigned char* lds, const Gemm g, const StaticOrder& S, const Epi& E) {
;     ...
;             PG8_LDB(B0, 0, 0); PG8_SCHED; PG8_LDA(At, 0, 0); PG8_LDA(At2, 0, 1); PG8_STAGE(PG8_SB(1, 1), b1 + hstepB, voffB);
;             PG8_WAIT_V(8); PG8_WAIT_L(0); PG8_BAR; PG8_MMA2B(0, At, At2, B0); PG8_BAR; PG8_SCHED;
;             PG8_LDB(B0, 0, 1); PG8_STAGE(PG8_SB(0, 0), b2, voffB); PG8_STAGE(PG8_SA(0, 0), a2, voffA); PG8_STAGE(PG8_SA(0, 1), a2 + hstepA, voffA);
;             PG8_WAIT_V(8); PG8_WAIT_L(0); PG8_BAR; PG8_MMA2B(1, At, At2, B0); PG8_BAR; PG8_SCHED;
;             PG8_LDB(B0, 1, 0); PG8_SCHED; PG8_LDA(At, 1, 0); PG8_LDA(At2, 1, 1); PG8_STAGE(PG8_SB(0, 1), b2 + hstepB, voffB);
.LBB0_487:
	s_add_i32 s69, s68, 2
	s_add_u32 s6, s88, 0x80
	ds_read_b128 v[140:143], v134
	ds_read_b128 v[144:147], v134 offset:1024
	ds_read_b128 v[148:151], v134 offset:2048
	ds_read_b128 v[152:155], v134 offset:3072
	s_addc_u32 s7, s89, 0
	s_cmp_eq_u32 s62, s68
	s_cselect_b32 s80, s17, s95
	s_cselect_b32 s81, s15, s96
	s_cselect_b32 s90, s87, s6
	s_cselect_b32 s91, s86, s7
	s_add_u32 s82, s80, 0x80
	s_addc_u32 s83, s81, 0
	s_add_u32 s84, s90, 0x80
	s_addc_u32 s85, s91, 0
	ds_read_b128 v[156:159], v135
	ds_read_b128 v[166:169], v135 offset:1024
	ds_read_b128 v[178:181], v135 offset:2048
	ds_read_b128 v[182:185], v135 offset:3072
	ds_read_b128 v[186:189], v135 offset:4096
	ds_read_b128 v[190:193], v135 offset:5120
	ds_read_b128 v[194:197], v135 offset:6144
	ds_read_b128 v[198:201], v135 offset:7168
	ds_read_b128 v[202:205], v135 offset:16384
	ds_read_b128 v[214:217], v135 offset:17408
	ds_read_b128 v[218:221], v135 offset:18432
	ds_read_b128 v[222:225], v135 offset:19456
	ds_read_b128 v[226:229], v135 offset:20480
	ds_read_b128 v[230:233], v135 offset:21504
	ds_read_b128 v[234:237], v135 offset:22528
	ds_read_b128 v[238:241], v135 offset:23552
	s_add_u32 s6, s88, 0x20000
	s_addc_u32 s7, s89, 0
	s_mov_b32 m0, s63
	s_nop 0
	global_load_lds_dwordx4 v129, s[6:7]
	s_mov_b32 m0, s64
	s_nop 0
	global_load_lds_dwordx4 v131, s[6:7]
	s_waitcnt vmcnt(8)
	s_waitcnt lgkmcnt(0)
	s_barrier
	s_waitcnt lgkmcnt(14)
	v_mfma_f32_16x16x32_bf16 v[120:123], v[140:143], v[156:159], v[120:123]
	v_mfma_f32_16x16x32_bf16 v[124:127], v[148:151], v[156:159], v[124:127]
	s_waitcnt lgkmcnt(13)
	v_mfma_f32_16x16x32_bf16 v[108:111], v[140:143], v[178:181], v[108:111]
	v_mfma_f32_16x16x32_bf16 v[104:107], v[148:151], v[178:181], v[104:107]
	s_waitcnt lgkmcnt(11)
	v_mfma_f32_16x16x32_bf16 v[92:95], v[140:143], v[186:189], v[92:95]
	v_mfma_f32_16x16x32_bf16 v[88:91], v[148:151], v[186:189], v[88:91]
	s_waitcnt lgkmcnt(9)
	v_mfma_f32_16x16x32_bf16 v[76:79], v[140:143], v[194:197], v[76:79]
	v_mfma_f32_16x16x32_bf16 v[72:75], v[148:151], v[194:197], v[72:75]
	s_waitcnt lgkmcnt(7)
	v_mfma_f32_16x16x32_bf16 v[60:63], v[140:143], v[202:205], v[60:63]
	v_mfma_f32_16x16x32_bf16 v[56:59], v[148:151], v[202:205], v[56:59]
	s_waitcnt lgkmcnt(5)
	v_mfma_f32_16x16x32_bf16 v[44:47], v[140:143], v[218:221], v[44:47]
	v_mfma_f32_16x16x32_bf16 v[40:43], v[148:151], v[218:221], v[40:43]
	s_waitcnt lgkmcnt(3)
	v_mfma_f32_16x16x32_bf16 v[28:31], v[140:143], v[226:229], v[28:31]
	v_mfma_f32_16x16x32_bf16 v[24:27], v[148:151], v[226:229], v[24:27]
	s_waitcnt lgkmcnt(1)
	v_mfma_f32_16x16x32_bf16 v[12:15], v[140:143], v[234:237], v[12:15]
	v_mfma_f32_16x16x32_bf16 v[8:11], v[148:151], v[234:237], v[8:11]
	v_mfma_f32_16x16x32_bf16 v[120:123], v[144:147], v[166:169], v[120:123]
	v_mfma_f32_16x16x32_bf16 v[124:127], v[152:155], v[166:169], v[124:127]
	v_mfma_f32_16x16x32_bf16 v[108:111], v[144:147], v[182:185], v[108:111]
	v_mfma_f32_16x16x32_bf16 v[104:107], v[152:155], v[182:185], v[104:107]
	v_mfma_f32_16x16x32_bf16 v[92:95], v[144:147], v[190:193], v[92:95]
	v_mfma_f32_16x16x32_bf16 v[88:91], v[152:155], v[190:193], v[88:91]
	v_mfma_f32_16x16x32_bf16 v[76:79], v[144:147], v[198:201], v[76:79]
	v_mfma_f32_16x16x32_bf16 v[72:75], v[152:155], v[198:201], v[72:75]
	v_mfma_f32_16x16x32_bf16 v[60:63], v[144:147], v[214:217], v[60:63]
	v_mfma_f32_16x16x32_bf16 v[56:59], v[152:155], v[214:217], v[56:59]
	v_mfma_f32_16x16x32_bf16 v[44:47], v[144:147], v[222:225], v[44:47]
	v_mfma_f32_16x16x32_bf16 v[40:43], v[152:155], v[222:225], v[40:43]
	v_mfma_f32_16x16x32_bf16 v[28:31], v[144:147], v[230:233], v[28:31]
	v_mfma_f32_16x16x32_bf16 v[24:27], v[152:155], v[230:233], v[24:27]
	s_waitcnt lgkmcnt(0)
	v_mfma_f32_16x16x32_bf16 v[12:15], v[144:147], v[238:241], v[12:15]
	v_mfma_f32_16x16x32_bf16 v[8:11], v[152:155], v[238:241], v[8:11]
	s_barrier
	ds_read_b128 v[140:143], v136
	ds_read_b128 v[144:147], v136 offset:1024
	ds_read_b128 v[148:151], v136 offset:2048
	ds_read_b128 v[152:155], v136 offset:3072
	s_mov_b32 m0, s48
	s_nop 0
	global_load_lds_dwordx4 v129, s[90:91]
	s_mov_b32 m0, s49
	s_nop 0
	global_load_lds_dwordx4 v131, s[90:91]
	s_mov_b32 m0, s47
	s_nop 0
	global_load_lds_dwordx4 v128, s[80:81]
	s_mov_b32 m0, s50
	s_nop 0
	global_load_lds_dwordx4 v130, s[80:81]
	s_add_u32 s6, s80, 0x20000
	s_addc_u32 s7, s81, 0
	s_mov_b32 m0, s52
	s_nop 0
	global_load_lds_dwordx4 v128, s[6:7]
	s_mov_b32 m0, s53
	s_nop 0
	global_load_lds_dwordx4 v130, s[6:7]
	s_waitcnt vmcnt(8)
	s_waitcnt lgkmcnt(0)
	s_barrier
; #define PG8_STAGE(bufoff, gbase, voff) do { _Pragma("unroll") for (int _i = 0; _i < 2; ++_i) { \
;         const unsigned _m0 = ldsu + (unsigned)(bufoff) + ldsw + (unsigned)(_i * 8192); \
;         asm volatile("s_mov_b32 m0, %2\n\ts_nop 0\n\tglobal_load_lds_dwordx4 %0, %1" :: "v"((voff)[_i]), "s"((const char*)(gbase)), "s"(_m0) : "memory"); } } while (0)
; #define PG8_LDA(dst, b, h) do { _Pragma("unroll") for (int m = 0; m < 4; ++m) _Pragma("unroll") for (int k = 0; k < 2; ++k) dst[m][k] = *(const LAS bf16x8*)(lds + PG8_SA(b, h) + aoff + m * 2048 + k * 1024); } while (0)
; #define PG8_LDB(dst, b, h) do { _Pragma("unroll") for (int n = 0; n < 2; ++n) _Pragma("unroll") for (int k = 0; k < 2; ++k) dst[n][k] = *(const LAS bf16x8*)(lds + bbase[b][h] + n * 2048 + k * 1024); } while (0)
; #define PG8_WAIT_V(n) asm volatile("s_waitcnt vmcnt(" #n ")" ::: "memory")
; #define PG8_WAIT_L(n) asm volatile("s_waitcnt lgkmcnt(" #n ")" ::: "memory")
; #define PG8_BAR __builtin_amdgcn_s_barrier()
; #define PG8_SCHED __builtin_amdgcn_sched_barrier(0)
; template <class Epi>
; __device__ __forceinline__ void gemm_phase(LAS unsigned char* lds, const Gemm g, const StaticOrder& S, const Epi& E) {
;     ...
;             PG8_WAIT_V(8); PG8_WAIT_L(0); PG8_BAR; PG8_MMA2B(1, At, At2, B0); PG8_BAR; PG8_SCHED;
;             PG8_LDB(B0, 1, 0); PG8_SCHED; PG8_LDA(At, 1, 0); PG8_LDA(At2, 1, 1); PG8_STAGE(PG8_SB(0, 1), b2 + hstepB, voffB);
;             PG8_WAIT_V(8); PG8_WAIT_L(0); PG8_BAR; PG8_MMA2B(0, At, At2, B0); PG8_BAR; PG8_SCHED;
;             PG8_LDB(B0, 1, 1); PG8_STAGE(PG8_SB(1, 0), b3, voffB); PG8_STAGE(PG8_SA(1, 0), a3, voffA); PG8_STAGE(PG8_SA(1, 1), a3 + hstepA, voffA);
	s_waitcnt lgkmcnt(3)
	v_mfma_f32_16x16x32_bf16 v[116:119], v[140:143], v[156:159], v[116:119]
	s_waitcnt lgkmcnt(1)
	v_mfma_f32_16x16x32_bf16 v[112:115], v[148:151], v[156:159], v[112:115]
	v_mfma_f32_16x16x32_bf16 v[100:103], v[140:143], v[178:181], v[100:103]
	v_mfma_f32_16x16x32_bf16 v[96:99], v[148:151], v[178:181], v[96:99]
	v_mfma_f32_16x16x32_bf16 v[84:87], v[140:143], v[186:189], v[84:87]
	v_mfma_f32_16x16x32_bf16 v[80:83], v[148:151], v[186:189], v[80:83]
	v_mfma_f32_16x16x32_bf16 v[68:71], v[140:143], v[194:197], v[68:71]
	v_mfma_f32_16x16x32_bf16 v[64:67], v[148:151], v[194:197], v[64:67]
	v_mfma_f32_16x16x32_bf16 v[52:55], v[140:143], v[202:205], v[52:55]
	v_mfma_f32_16x16x32_bf16 v[48:51], v[148:151], v[202:205], v[48:51]
	v_mfma_f32_16x16x32_bf16 v[36:39], v[140:143], v[218:221], v[36:39]
	v_mfma_f32_16x16x32_bf16 v[32:35], v[148:151], v[218:221], v[32:35]
	v_mfma_f32_16x16x32_bf16 v[20:23], v[140:143], v[226:229], v[20:23]
	v_mfma_f32_16x16x32_bf16 v[16:19], v[148:151], v[226:229], v[16:19]
	v_mfma_f32_16x16x32_bf16 v[4:7], v[140:143], v[234:237], v[4:7]
	v_mfma_f32_16x16x32_bf16 v[0:3], v[148:151], v[234:237], v[0:3]
	v_mfma_f32_16x16x32_bf16 v[116:119], v[144:147], v[166:169], v[116:119]
	s_waitcnt lgkmcnt(0)
	v_mfma_f32_16x16x32_bf16 v[112:115], v[152:155], v[166:169], v[112:115]
	v_mfma_f32_16x16x32_bf16 v[100:103], v[144:147], v[182:185], v[100:103]
	v_mfma_f32_16x16x32_bf16 v[96:99], v[152:155], v[182:185], v[96:99]
	v_mfma_f32_16x16x32_bf16 v[84:87], v[144:147], v[190:193], v[84:87]
	v_mfma_f32_16x16x32_bf16 v[80:83], v[152:155], v[190:193], v[80:83]
	v_mfma_f32_16x16x32_bf16 v[68:71], v[144:147], v[198:201], v[68:71]
	v_mfma_f32_16x16x32_bf16 v[64:67], v[152:155], v[198:201], v[64:67]
	v_mfma_f32_16x16x32_bf16 v[52:55], v[144:147], v[214:217], v[52:55]
	v_mfma_f32_16x16x32_bf16 v[48:51], v[152:155], v[214:217], v[48:51]
	v_mfma_f32_16x16x32_bf16 v[36:39], v[144:147], v[222:225], v[36:39]
	v_mfma_f32_16x16x32_bf16 v[32:35], v[152:155], v[222:225], v[32:35]
	v_mfma_f32_16x16x32_bf16 v[20:23], v[144:147], v[230:233], v[20:23]
	v_mfma_f32_16x16x32_bf16 v[16:19], v[152:155], v[230:233], v[16:19]
	v_mfma_f32_16x16x32_bf16 v[4:7], v[144:147], v[238:241], v[4:7]
	v_mfma_f32_16x16x32_bf16 v[0:3], v[152:155], v[238:241], v[0:3]
	s_barrier
	ds_read_b128 v[140:143], v137
	ds_read_b128 v[144:147], v137 offset:1024
	ds_read_b128 v[148:151], v137 offset:2048
	ds_read_b128 v[152:155], v137 offset:3072
	ds_read_b128 v[156:159], v135 offset:32768
	ds_read_b128 v[166:169], v135 offset:33792
	ds_read_b128 v[178:181], v135 offset:34816
	ds_read_b128 v[182:185], v135 offset:35840
	ds_read_b128 v[186:189], v135 offset:36864
	ds_read_b128 v[190:193], v135 offset:37888
	ds_read_b128 v[194:197], v135 offset:38912
	ds_read_b128 v[198:201], v135 offset:39936
	ds_read_b128 v[202:205], v135 offset:49152
	ds_read_b128 v[214:217], v135 offset:50176
	ds_read_b128 v[218:221], v135 offset:51200
	ds_read_b128 v[222:225], v135 offset:52224
	ds_read_b128 v[226:229], v135 offset:53248
	ds_read_b128 v[230:233], v135 offset:54272
	ds_read_b128 v[234:237], v135 offset:55296
	ds_read_b128 v[238:241], v135 offset:56320
	s_add_u32 s6, s90, 0x20000
	s_addc_u32 s7, s91, 0
	s_mov_b32 m0, s54
	s_nop 0
	global_load_lds_dwordx4 v129, s[6:7]
	s_mov_b32 m0, s55
	s_nop 0
	global_load_lds_dwordx4 v131, s[6:7]
	s_waitcnt vmcnt(8)
	s_waitcnt lgkmcnt(0)
	s_barrier
; #define PG8_STAGE(bufoff, gbase, voff) do { _Pragma("unroll") for (int _i = 0; _i < 2; ++_i) { \
;         const unsigned _m0 = ldsu + (unsigned)(bufoff) + ldsw + (unsigned)(_i * 8192); \
;         asm volatile("s_mov_b32 m0, %2\n\ts_nop 0\n\tglobal_load_lds_dwordx4 %0, %1" :: "v"((voff)[_i]), "s"((const char*)(gbase)), "s"(_m0) : "memory"); } } while (0)
; #define PG8_LDB(dst, b, h) do { _Pragma("unroll") for (int n = 0; n < 2; ++n) _Pragma("unroll") for (int k = 0; k < 2; ++k) dst[n][k] = *(const LAS bf16x8*)(lds + bbase[b][h] + n * 2048 + k * 1024); } while (0)
; #define PG8_WAIT_V(n) asm volatile("s_waitcnt vmcnt(" #n ")" ::: "memory")
; #define PG8_WAIT_L(n) asm volatile("s_waitcnt lgkmcnt(" #n ")" ::: "memory")
; #define PG8_BAR __builtin_amdgcn_s_barrier()
; #define PG8_SCHED __builtin_amdgcn_sched_barrier(0)
; template <class Epi>
; __device__ __forceinline__ void gemm_phase(LAS unsigned char* lds, const Gemm g, const StaticOrder& S, const Epi& E) {
;     ...
;         for (int t = 0; t < nt; t += 2) {
;             const bool last = (t == nt - 2);
;             const char* a2 = last ? nA : cA + (size_t)(t + 2) * kstep; const char* b2 = last ? nB : cB + (size_t)(t + 2) * kstep;
;     ...
;             PG8_WAIT_V(8); PG8_WAIT_L(0); PG8_BAR; PG8_MMA2B(0, At, At2, B0); PG8_BAR; PG8_SCHED;
;             PG8_LDB(B0, 1, 1); PG8_STAGE(PG8_SB(1, 0), b3, voffB); PG8_STAGE(PG8_SA(1, 0), a3, voffA); PG8_STAGE(PG8_SA(1, 1), a3 + hstepA, voffA);
;             PG8_WAIT_V(8); PG8_WAIT_L(0); PG8_BAR; PG8_MMA2B(1, At, At2, B0); PG8_BAR; PG8_SCHED;
	s_waitcnt lgkmcnt(14)
	v_mfma_f32_16x16x32_bf16 v[120:123], v[140:143], v[156:159], v[120:123]
	v_mfma_f32_16x16x32_bf16 v[124:127], v[148:151], v[156:159], v[124:127]
	s_waitcnt lgkmcnt(13)
	v_mfma_f32_16x16x32_bf16 v[108:111], v[140:143], v[178:181], v[108:111]
	v_mfma_f32_16x16x32_bf16 v[104:107], v[148:151], v[178:181], v[104:107]
	s_waitcnt lgkmcnt(11)
	v_mfma_f32_16x16x32_bf16 v[92:95], v[140:143], v[186:189], v[92:95]
	v_mfma_f32_16x16x32_bf16 v[88:91], v[148:151], v[186:189], v[88:91]
	s_waitcnt lgkmcnt(9)
	v_mfma_f32_16x16x32_bf16 v[76:79], v[140:143], v[194:197], v[76:79]
	v_mfma_f32_16x16x32_bf16 v[72:75], v[148:151], v[194:197], v[72:75]
	s_waitcnt lgkmcnt(7)
	v_mfma_f32_16x16x32_bf16 v[60:63], v[140:143], v[202:205], v[60:63]
	v_mfma_f32_16x16x32_bf16 v[56:59], v[148:151], v[202:205], v[56:59]
	s_waitcnt lgkmcnt(5)
	v_mfma_f32_16x16x32_bf16 v[44:47], v[140:143], v[218:221], v[44:47]
	v_mfma_f32_16x16x32_bf16 v[40:43], v[148:151], v[218:221], v[40:43]
	s_waitcnt lgkmcnt(3)
	v_mfma_f32_16x16x32_bf16 v[28:31], v[140:143], v[226:229], v[28:31]
	v_mfma_f32_16x16x32_bf16 v[24:27], v[148:151], v[226:229], v[24:27]
	s_waitcnt lgkmcnt(1)
	v_mfma_f32_16x16x32_bf16 v[12:15], v[140:143], v[234:237], v[12:15]
	v_mfma_f32_16x16x32_bf16 v[8:11], v[148:151], v[234:237], v[8:11]
	v_mfma_f32_16x16x32_bf16 v[120:123], v[144:147], v[166:169], v[120:123]
	v_mfma_f32_16x16x32_bf16 v[124:127], v[152:155], v[166:169], v[124:127]
	v_mfma_f32_16x16x32_bf16 v[108:111], v[144:147], v[182:185], v[108:111]
	v_mfma_f32_16x16x32_bf16 v[104:107], v[152:155], v[182:185], v[104:107]
	v_mfma_f32_16x16x32_bf16 v[92:95], v[144:147], v[190:193], v[92:95]
	v_mfma_f32_16x16x32_bf16 v[88:91], v[152:155], v[190:193], v[88:91]
	v_mfma_f32_16x16x32_bf16 v[76:79], v[144:147], v[198:201], v[76:79]
	v_mfma_f32_16x16x32_bf16 v[72:75], v[152:155], v[198:201], v[72:75]
	v_mfma_f32_16x16x32_bf16 v[60:63], v[144:147], v[214:217], v[60:63]
	v_mfma_f32_16x16x32_bf16 v[56:59], v[152:155], v[214:217], v[56:59]
	v_mfma_f32_16x16x32_bf16 v[44:47], v[144:147], v[222:225], v[44:47]
	v_mfma_f32_16x16x32_bf16 v[40:43], v[152:155], v[222:225], v[40:43]
	v_mfma_f32_16x16x32_bf16 v[28:31], v[144:147], v[230:233], v[28:31]
	v_mfma_f32_16x16x32_bf16 v[24:27], v[152:155], v[230:233], v[24:27]
	s_waitcnt lgkmcnt(0)
	v_mfma_f32_16x16x32_bf16 v[12:15], v[144:147], v[238:241], v[12:15]
	v_mfma_f32_16x16x32_bf16 v[8:11], v[152:155], v[238:241], v[8:11]
	s_barrier
	ds_read_b128 v[140:143], v138
	ds_read_b128 v[144:147], v138 offset:1024
	ds_read_b128 v[148:151], v138 offset:2048
	ds_read_b128 v[152:155], v138 offset:3072
	s_mov_b32 m0, s56
	s_nop 0
	global_load_lds_dwordx4 v129, s[84:85]
	s_mov_b32 m0, s57
	s_nop 0
	global_load_lds_dwordx4 v131, s[84:85]
	s_mov_b32 m0, s58
	s_nop 0
	global_load_lds_dwordx4 v128, s[82:83]
	s_mov_b32 m0, s59
	s_nop 0
	global_load_lds_dwordx4 v130, s[82:83]
	s_add_u32 s6, s80, 0x20080
	s_addc_u32 s7, s81, 0
	s_mov_b32 m0, s60
	s_nop 0
	global_load_lds_dwordx4 v128, s[6:7]
	s_mov_b32 m0, s61
	s_nop 0
	global_load_lds_dwordx4 v130, s[6:7]
	s_waitcnt vmcnt(8)
	s_waitcnt lgkmcnt(0)
	s_barrier
	s_waitcnt lgkmcnt(3)
	v_mfma_f32_16x16x32_bf16 v[116:119], v[140:143], v[156:159], v[116:119]
	s_waitcnt lgkmcnt(1)
	v_mfma_f32_16x16x32_bf16 v[112:115], v[148:151], v[156:159], v[112:115]
	v_mfma_f32_16x16x32_bf16 v[100:103], v[140:143], v[178:181], v[100:103]
	v_mfma_f32_16x16x32_bf16 v[96:99], v[148:151], v[178:181], v[96:99]
	v_mfma_f32_16x16x32_bf16 v[84:87], v[140:143], v[186:189], v[84:87]
	v_mfma_f32_16x16x32_bf16 v[80:83], v[148:151], v[186:189], v[80:83]
	v_mfma_f32_16x16x32_bf16 v[68:71], v[140:143], v[194:197], v[68:71]
	v_mfma_f32_16x16x32_bf16 v[64:67], v[148:151], v[194:197], v[64:67]
	v_mfma_f32_16x16x32_bf16 v[52:55], v[140:143], v[202:205], v[52:55]
	v_mfma_f32_16x16x32_bf16 v[48:51], v[148:151], v[202:205], v[48:51]
	v_mfma_f32_16x16x32_bf16 v[36:39], v[140:143], v[218:221], v[36:39]
	v_mfma_f32_16x16x32_bf16 v[32:35], v[148:151], v[218:221], v[32:35]
	v_mfma_f32_16x16x32_bf16 v[20:23], v[140:143], v[226:229], v[20:23]
	v_mfma_f32_16x16x32_bf16 v[16:19], v[148:151], v[226:229], v[16:19]
	v_mfma_f32_16x16x32_bf16 v[4:7], v[140:143], v[234:237], v[4:7]
	v_mfma_f32_16x16x32_bf16 v[0:3], v[148:151], v[234:237], v[0:3]
	v_mfma_f32_16x16x32_bf16 v[116:119], v[144:147], v[166:169], v[116:119]
	s_waitcnt lgkmcnt(0)
	v_mfma_f32_16x16x32_bf16 v[112:115], v[152:155], v[166:169], v[112:115]
	v_mfma_f32_16x16x32_bf16 v[100:103], v[144:147], v[182:185], v[100:103]
	v_mfma_f32_16x16x32_bf16 v[96:99], v[152:155], v[182:185], v[96:99]
	v_mfma_f32_16x16x32_bf16 v[84:87], v[144:147], v[190:193], v[84:87]
	v_mfma_f32_16x16x32_bf16 v[80:83], v[152:155], v[190:193], v[80:83]
	v_mfma_f32_16x16x32_bf16 v[68:71], v[144:147], v[198:201], v[68:71]
	v_mfma_f32_16x16x32_bf16 v[64:67], v[152:155], v[198:201], v[64:67]
	v_mfma_f32_16x16x32_bf16 v[52:55], v[144:147], v[214:217], v[52:55]
	v_mfma_f32_16x16x32_bf16 v[48:51], v[152:155], v[214:217], v[48:51]
	v_mfma_f32_16x16x32_bf16 v[36:39], v[144:147], v[222:225], v[36:39]
	v_mfma_f32_16x16x32_bf16 v[32:35], v[152:155], v[222:225], v[32:35]
	v_mfma_f32_16x16x32_bf16 v[20:23], v[144:147], v[230:233], v[20:23]
	v_mfma_f32_16x16x32_bf16 v[16:19], v[152:155], v[230:233], v[16:19]
	v_mfma_f32_16x16x32_bf16 v[4:7], v[144:147], v[238:241], v[4:7]
	v_mfma_f32_16x16x32_bf16 v[0:3], v[152:155], v[238:241], v[0:3]
	s_add_u32 s88, s88, 0x100
	s_addc_u32 s89, s89, 0
	s_add_u32 s95, s95, 0x100
	s_addc_u32 s96, s96, 0
	s_cmp_ge_i32 s69, s28
	s_mov_b32 s68, s69
	s_barrier
	s_cbranch_scc0 .LBB0_487
	v_readlane_b32 s96, v252, 29
	v_readlane_b32 s97, v252, 30
	v_readlane_b32 s89, v255, 4
	v_readlane_b32 s95, v255, 2

; #define PG8_STAGE(bufoff, gbase, voff) do { _Pragma("unroll") for (int _i = 0; _i < 2; ++_i) { \
;         const unsigned _m0 = ldsu + (unsigned)(bufoff) + ldsw + (unsigned)(_i * 8192); \
;         asm volatile("s_mov_b32 m0, %2\n\ts_nop 0\n\tglobal_load_lds_dwordx4 %0, %1" :: "v"((voff)[_i]), "s"((const char*)(gbase)), "s"(_m0) : "memory"); } } while (0)
; #define PG8_LDA(dst, b, h) do { _Pragma("unroll") for (int m = 0; m < 4; ++m) _Pragma("unroll") for (int k = 0; k < 2; ++k) dst[m][k] = *(const LAS bf16x8*)(lds + PG8_SA(b, h) + aoff + m * 2048 + k * 1024); } while (0)
; #define PG8_LDB(dst, b, h) do { _Pragma("unroll") for (int n = 0; n < 2; ++n) _Pragma("unroll") for (int k = 0; k < 2; ++k) dst[n][k] = *(const LAS bf16x8*)(lds + bbase[b][h] + n * 2048 + k * 1024); } while (0)
; #define PG8_WAIT_V(n) asm volatile("s_waitcnt vmcnt(" #n ")" ::: "memory")
; #define PG8_WAIT_L(n) asm volatile("s_waitcnt lgkmcnt(" #n ")" ::: "memory")
; #define PG8_BAR __builtin_amdgcn_s_barrier()
; #define PG8_SCHED __builtin_amdgcn_sched_barrier(0)
; template <class Epi>
; __device__ __forceinline__ void gemm_phase(LAS unsigned char* lds, const Gemm g, const StaticOrder& S, const Epi& E) {
;     ...
;             const char* a2 = last ? nA : cA + (size_t)(t + 2) * kstep; const char* b2 = last ? nB : cB + (size_t)(t + 2) * kstep;
;             const char* a3 = a2 + kstep; const char* b3 = b2 + kstep;
;             const char* b1 = cB + (size_t)(t + 1) * kstep;
;             PG8_LDB(B0, 0, 0); PG8_SCHED; PG8_LDA(At, 0, 0); PG8_LDA(At2, 0, 1); PG8_STAGE(PG8_SB(1, 1), b1 + hstepB, voffB);
;             PG8_WAIT_V(8); PG8_WAIT_L(0); PG8_BAR; PG8_MMA2B(0, At, At2, B0); PG8_BAR; PG8_SCHED;
;             PG8_LDB(B0, 0, 1); PG8_STAGE(PG8_SB(0, 0), b2, voffB); PG8_STAGE(PG8_SA(0, 0), a2, voffA); PG8_STAGE(PG8_SA(0, 1), a2 + hstepA, voffA);
;             PG8_WAIT_V(8); PG8_WAIT_L(0); PG8_BAR; PG8_MMA2B(1, At, At2, B0); PG8_BAR; PG8_SCHED;
.LBB0_509:
	s_add_i32 s63, s4, 2
	s_add_u32 s38, s59, 0x80
	ds_read_b128 v[128:131], v144
	ds_read_b128 v[132:135], v144 offset:1024
	ds_read_b128 v[150:153], v144 offset:2048
	ds_read_b128 v[154:157], v144 offset:3072
	s_addc_u32 s39, s60, 0
	s_cmp_eq_u32 s51, s4
	s_cselect_b32 s4, s15, s61
	s_cselect_b32 s5, s13, s62
	s_cselect_b32 s82, s58, s38
	s_cselect_b32 s83, s57, s39
	s_add_u32 s38, s4, 0x80
	s_addc_u32 s39, s5, 0
	s_add_u32 s80, s82, 0x80
	s_addc_u32 s81, s83, 0
	ds_read_b128 v[166:169], v145
	ds_read_b128 v[178:181], v145 offset:1024
	ds_read_b128 v[182:185], v145 offset:2048
	ds_read_b128 v[186:189], v145 offset:3072
	ds_read_b128 v[190:193], v145 offset:4096
	ds_read_b128 v[194:197], v145 offset:5120
	ds_read_b128 v[198:201], v145 offset:6144
	ds_read_b128 v[202:205], v145 offset:7168
	ds_read_b128 v[214:217], v145 offset:16384
	ds_read_b128 v[218:221], v145 offset:17408
	ds_read_b128 v[222:225], v145 offset:18432
	ds_read_b128 v[226:229], v145 offset:19456
	ds_read_b128 v[230:233], v145 offset:20480
	ds_read_b128 v[234:237], v145 offset:21504
	ds_read_b128 v[238:241], v145 offset:22528
	ds_read_b128 v[242:245], v145 offset:23552
	s_add_u32 s64, s59, 0x20000
	s_addc_u32 s65, s60, 0
	s_mov_b32 m0, s52
	s_nop 0
	global_load_lds_dwordx4 v141, s[64:65]
	s_mov_b32 m0, s53
	s_nop 0
	global_load_lds_dwordx4 v143, s[64:65]
	s_waitcnt vmcnt(8)
	s_waitcnt lgkmcnt(0)
	s_barrier
	s_waitcnt lgkmcnt(14)
	v_mfma_f32_16x16x32_bf16 v[120:123], v[128:131], v[166:169], v[120:123]
	v_mfma_f32_16x16x32_bf16 v[124:127], v[150:153], v[166:169], v[124:127]
	s_waitcnt lgkmcnt(13)
	v_mfma_f32_16x16x32_bf16 v[108:111], v[128:131], v[182:185], v[108:111]
	v_mfma_f32_16x16x32_bf16 v[104:107], v[150:153], v[182:185], v[104:107]
	s_waitcnt lgkmcnt(11)
	v_mfma_f32_16x16x32_bf16 v[92:95], v[128:131], v[190:193], v[92:95]
	v_mfma_f32_16x16x32_bf16 v[88:91], v[150:153], v[190:193], v[88:91]
	s_waitcnt lgkmcnt(9)
	v_mfma_f32_16x16x32_bf16 v[76:79], v[128:131], v[198:201], v[76:79]
	v_mfma_f32_16x16x32_bf16 v[72:75], v[150:153], v[198:201], v[72:75]
	s_waitcnt lgkmcnt(7)
	v_mfma_f32_16x16x32_bf16 v[60:63], v[128:131], v[214:217], v[60:63]
	v_mfma_f32_16x16x32_bf16 v[56:59], v[150:153], v[214:217], v[56:59]
	s_waitcnt lgkmcnt(5)
	v_mfma_f32_16x16x32_bf16 v[44:47], v[128:131], v[222:225], v[44:47]
	v_mfma_f32_16x16x32_bf16 v[40:43], v[150:153], v[222:225], v[40:43]
	s_waitcnt lgkmcnt(3)
	v_mfma_f32_16x16x32_bf16 v[28:31], v[128:131], v[230:233], v[28:31]
	v_mfma_f32_16x16x32_bf16 v[24:27], v[150:153], v[230:233], v[24:27]
	s_waitcnt lgkmcnt(1)
	v_mfma_f32_16x16x32_bf16 v[12:15], v[128:131], v[238:241], v[12:15]
	v_mfma_f32_16x16x32_bf16 v[8:11], v[150:153], v[238:241], v[8:11]
	v_mfma_f32_16x16x32_bf16 v[120:123], v[132:135], v[178:181], v[120:123]
	v_mfma_f32_16x16x32_bf16 v[124:127], v[154:157], v[178:181], v[124:127]
	v_mfma_f32_16x16x32_bf16 v[108:111], v[132:135], v[186:189], v[108:111]
	v_mfma_f32_16x16x32_bf16 v[104:107], v[154:157], v[186:189], v[104:107]
	v_mfma_f32_16x16x32_bf16 v[92:95], v[132:135], v[194:197], v[92:95]
	v_mfma_f32_16x16x32_bf16 v[88:91], v[154:157], v[194:197], v[88:91]
	v_mfma_f32_16x16x32_bf16 v[76:79], v[132:135], v[202:205], v[76:79]
	v_mfma_f32_16x16x32_bf16 v[72:75], v[154:157], v[202:205], v[72:75]
	v_mfma_f32_16x16x32_bf16 v[60:63], v[132:135], v[218:221], v[60:63]
	v_mfma_f32_16x16x32_bf16 v[56:59], v[154:157], v[218:221], v[56:59]
	v_mfma_f32_16x16x32_bf16 v[44:47], v[132:135], v[226:229], v[44:47]
	v_mfma_f32_16x16x32_bf16 v[40:43], v[154:157], v[226:229], v[40:43]
	v_mfma_f32_16x16x32_bf16 v[28:31], v[132:135], v[234:237], v[28:31]
	v_mfma_f32_16x16x32_bf16 v[24:27], v[154:157], v[234:237], v[24:27]
	s_waitcnt lgkmcnt(0)
	v_mfma_f32_16x16x32_bf16 v[12:15], v[132:135], v[242:245], v[12:15]
	v_mfma_f32_16x16x32_bf16 v[8:11], v[154:157], v[242:245], v[8:11]
	s_barrier
	ds_read_b128 v[128:131], v146
	ds_read_b128 v[132:135], v146 offset:1024
	ds_read_b128 v[150:153], v146 offset:2048
	ds_read_b128 v[154:157], v146 offset:3072
	s_mov_b32 m0, s85
	s_nop 0
	global_load_lds_dwordx4 v141, s[82:83]
	s_mov_b32 m0, s86
	s_nop 0
	global_load_lds_dwordx4 v143, s[82:83]
	s_mov_b32 m0, s84
	s_nop 0
	global_load_lds_dwordx4 v140, s[4:5]
	s_mov_b32 m0, s87
	s_nop 0
	global_load_lds_dwordx4 v142, s[4:5]
	s_add_u32 s64, s4, 0x20000
	s_addc_u32 s65, s5, 0
	s_mov_b32 m0, s88
	s_nop 0
	global_load_lds_dwordx4 v140, s[64:65]
	s_mov_b32 m0, s89
	s_nop 0
	global_load_lds_dwordx4 v142, s[64:65]
	s_waitcnt vmcnt(8)
	s_waitcnt lgkmcnt(0)
	s_barrier
; #define PG8_STAGE(bufoff, gbase, voff) do { _Pragma("unroll") for (int _i = 0; _i < 2; ++_i) { \
;         const unsigned _m0 = ldsu + (unsigned)(bufoff) + ldsw + (unsigned)(_i * 8192); \
;         asm volatile("s_mov_b32 m0, %2\n\ts_nop 0\n\tglobal_load_lds_dwordx4 %0, %1" :: "v"((voff)[_i]), "s"((const char*)(gbase)), "s"(_m0) : "memory"); } } while (0)
; #define PG8_LDA(dst, b, h) do { _Pragma("unroll") for (int m = 0; m < 4; ++m) _Pragma("unroll") for (int k = 0; k < 2; ++k) dst[m][k] = *(const LAS bf16x8*)(lds + PG8_SA(b, h) + aoff + m * 2048 + k * 1024); } while (0)
; #define PG8_LDB(dst, b, h) do { _Pragma("unroll") for (int n = 0; n < 2; ++n) _Pragma("unroll") for (int k = 0; k < 2; ++k) dst[n][k] = *(const LAS bf16x8*)(lds + bbase[b][h] + n * 2048 + k * 1024); } while (0)
; #define PG8_WAIT_V(n) asm volatile("s_waitcnt vmcnt(" #n ")" ::: "memory")
; #define PG8_WAIT_L(n) asm volatile("s_waitcnt lgkmcnt(" #n ")" ::: "memory")
; #define PG8_BAR __builtin_amdgcn_s_barrier()
; #define PG8_SCHED __builtin_amdgcn_sched_barrier(0)
; template <class Epi>
; __device__ __forceinline__ void gemm_phase(LAS unsigned char* lds, const Gemm g, const StaticOrder& S, const Epi& E) {
;     ...
;             PG8_WAIT_V(8); PG8_WAIT_L(0); PG8_BAR; PG8_MMA2B(1, At, At2, B0); PG8_BAR; PG8_SCHED;
;             PG8_LDB(B0, 1, 0); PG8_SCHED; PG8_LDA(At, 1, 0); PG8_LDA(At2, 1, 1); PG8_STAGE(PG8_SB(0, 1), b2 + hstepB, voffB);
	s_waitcnt lgkmcnt(3)
	v_mfma_f32_16x16x32_bf16 v[116:119], v[128:131], v[166:169], v[116:119]
	s_waitcnt lgkmcnt(1)
	v_mfma_f32_16x16x32_bf16 v[112:115], v[150:153], v[166:169], v[112:115]
	v_mfma_f32_16x16x32_bf16 v[100:103], v[128:131], v[182:185], v[100:103]
	v_mfma_f32_16x16x32_bf16 v[96:99], v[150:153], v[182:185], v[96:99]
	v_mfma_f32_16x16x32_bf16 v[84:87], v[128:131], v[190:193], v[84:87]
	v_mfma_f32_16x16x32_bf16 v[80:83], v[150:153], v[190:193], v[80:83]
	v_mfma_f32_16x16x32_bf16 v[68:71], v[128:131], v[198:201], v[68:71]
	v_mfma_f32_16x16x32_bf16 v[64:67], v[150:153], v[198:201], v[64:67]
	v_mfma_f32_16x16x32_bf16 v[52:55], v[128:131], v[214:217], v[52:55]
	v_mfma_f32_16x16x32_bf16 v[48:51], v[150:153], v[214:217], v[48:51]
	v_mfma_f32_16x16x32_bf16 v[36:39], v[128:131], v[222:225], v[36:39]
	v_mfma_f32_16x16x32_bf16 v[32:35], v[150:153], v[222:225], v[32:35]
	v_mfma_f32_16x16x32_bf16 v[20:23], v[128:131], v[230:233], v[20:23]
	v_mfma_f32_16x16x32_bf16 v[16:19], v[150:153], v[230:233], v[16:19]
	v_mfma_f32_16x16x32_bf16 v[4:7], v[128:131], v[238:241], v[4:7]
	v_mfma_f32_16x16x32_bf16 v[0:3], v[150:153], v[238:241], v[0:3]
	v_mfma_f32_16x16x32_bf16 v[116:119], v[132:135], v[178:181], v[116:119]
	s_waitcnt lgkmcnt(0)
	v_mfma_f32_16x16x32_bf16 v[112:115], v[154:157], v[178:181], v[112:115]
	v_mfma_f32_16x16x32_bf16 v[100:103], v[132:135], v[186:189], v[100:103]
	v_mfma_f32_16x16x32_bf16 v[96:99], v[154:157], v[186:189], v[96:99]
	v_mfma_f32_16x16x32_bf16 v[84:87], v[132:135], v[194:197], v[84:87]
	v_mfma_f32_16x16x32_bf16 v[80:83], v[154:157], v[194:197], v[80:83]
	v_mfma_f32_16x16x32_bf16 v[68:71], v[132:135], v[202:205], v[68:71]
	v_mfma_f32_16x16x32_bf16 v[64:67], v[154:157], v[202:205], v[64:67]
	v_mfma_f32_16x16x32_bf16 v[52:55], v[132:135], v[218:221], v[52:55]
	v_mfma_f32_16x16x32_bf16 v[48:51], v[154:157], v[218:221], v[48:51]
	v_mfma_f32_16x16x32_bf16 v[36:39], v[132:135], v[226:229], v[36:39]
	v_mfma_f32_16x16x32_bf16 v[32:35], v[154:157], v[226:229], v[32:35]
	v_mfma_f32_16x16x32_bf16 v[20:23], v[132:135], v[234:237], v[20:23]
	v_mfma_f32_16x16x32_bf16 v[16:19], v[154:157], v[234:237], v[16:19]
	v_mfma_f32_16x16x32_bf16 v[4:7], v[132:135], v[242:245], v[4:7]
	v_mfma_f32_16x16x32_bf16 v[0:3], v[154:157], v[242:245], v[0:3]
	s_barrier
	ds_read_b128 v[128:131], v147
	ds_read_b128 v[132:135], v147 offset:1024
	ds_read_b128 v[150:153], v147 offset:2048
	ds_read_b128 v[154:157], v147 offset:3072
	ds_read_b128 v[166:169], v145 offset:32768
	ds_read_b128 v[178:181], v145 offset:33792
	ds_read_b128 v[182:185], v145 offset:34816
	ds_read_b128 v[186:189], v145 offset:35840
	ds_read_b128 v[190:193], v145 offset:36864
	ds_read_b128 v[194:197], v145 offset:37888
	ds_read_b128 v[198:201], v145 offset:38912
	ds_read_b128 v[202:205], v145 offset:39936
	ds_read_b128 v[214:217], v145 offset:49152
	ds_read_b128 v[218:221], v145 offset:50176
	ds_read_b128 v[222:225], v145 offset:51200
	ds_read_b128 v[226:229], v145 offset:52224
	ds_read_b128 v[230:233], v145 offset:53248
	ds_read_b128 v[234:237], v145 offset:54272
	ds_read_b128 v[238:241], v145 offset:55296
	ds_read_b128 v[242:245], v145 offset:56320
	s_add_u32 s64, s82, 0x20000
	s_addc_u32 s65, s83, 0
	s_mov_b32 m0, s90
	s_nop 0
	global_load_lds_dwordx4 v141, s[64:65]
	s_mov_b32 m0, s91
	s_nop 0
	global_load_lds_dwordx4 v143, s[64:65]
	s_waitcnt vmcnt(8)
	s_waitcnt lgkmcnt(0)
	s_barrier
; #define PG8_STAGE(bufoff, gbase, voff) do { _Pragma("unroll") for (int _i = 0; _i < 2; ++_i) { \
;         const unsigned _m0 = ldsu + (unsigned)(bufoff) + ldsw + (unsigned)(_i * 8192); \
;         asm volatile("s_mov_b32 m0, %2\n\ts_nop 0\n\tglobal_load_lds_dwordx4 %0, %1" :: "v"((voff)[_i]), "s"((const char*)(gbase)), "s"(_m0) : "memory"); } } while (0)
; #define PG8_LDB(dst, b, h) do { _Pragma("unroll") for (int n = 0; n < 2; ++n) _Pragma("unroll") for (int k = 0; k < 2; ++k) dst[n][k] = *(const LAS bf16x8*)(lds + bbase[b][h] + n * 2048 + k * 1024); } while (0)
; #define PG8_WAIT_V(n) asm volatile("s_waitcnt vmcnt(" #n ")" ::: "memory")
; #define PG8_WAIT_L(n) asm volatile("s_waitcnt lgkmcnt(" #n ")" ::: "memory")
; #define PG8_BAR __builtin_amdgcn_s_barrier()
; #define PG8_SCHED __builtin_amdgcn_sched_barrier(0)
; template <class Epi>
; __device__ __forceinline__ void gemm_phase(LAS unsigned char* lds, const Gemm g, const StaticOrder& S, const Epi& E) {
;     ...
;         for (int t = 0; t < nt; t += 2) {
;             const bool last = (t == nt - 2);
;             const char* a2 = last ? nA : cA + (size_t)(t + 2) * kstep; const char* b2 = last ? nB : cB + (size_t)(t + 2) * kstep;
;     ...
;             PG8_WAIT_V(8); PG8_WAIT_L(0); PG8_BAR; PG8_MMA2B(0, At, At2, B0); PG8_BAR; PG8_SCHED;
;             PG8_LDB(B0, 1, 1); PG8_STAGE(PG8_SB(1, 0), b3, voffB); PG8_STAGE(PG8_SA(1, 0), a3, voffA); PG8_STAGE(PG8_SA(1, 1), a3 + hstepA, voffA);
;             PG8_WAIT_V(8); PG8_WAIT_L(0); PG8_BAR; PG8_MMA2B(1, At, At2, B0); PG8_BAR; PG8_SCHED;
	s_waitcnt lgkmcnt(14)
	v_mfma_f32_16x16x32_bf16 v[120:123], v[128:131], v[166:169], v[120:123]
	v_mfma_f32_16x16x32_bf16 v[124:127], v[150:153], v[166:169], v[124:127]
	s_waitcnt lgkmcnt(13)
	v_mfma_f32_16x16x32_bf16 v[108:111], v[128:131], v[182:185], v[108:111]
	v_mfma_f32_16x16x32_bf16 v[104:107], v[150:153], v[182:185], v[104:107]
	s_waitcnt lgkmcnt(11)
	v_mfma_f32_16x16x32_bf16 v[92:95], v[128:131], v[190:193], v[92:95]
	v_mfma_f32_16x16x32_bf16 v[88:91], v[150:153], v[190:193], v[88:91]
	s_waitcnt lgkmcnt(9)
	v_mfma_f32_16x16x32_bf16 v[76:79], v[128:131], v[198:201], v[76:79]
	v_mfma_f32_16x16x32_bf16 v[72:75], v[150:153], v[198:201], v[72:75]
	s_waitcnt lgkmcnt(7)
	v_mfma_f32_16x16x32_bf16 v[60:63], v[128:131], v[214:217], v[60:63]
	v_mfma_f32_16x16x32_bf16 v[56:59], v[150:153], v[214:217], v[56:59]
	s_waitcnt lgkmcnt(5)
	v_mfma_f32_16x16x32_bf16 v[44:47], v[128:131], v[222:225], v[44:47]
	v_mfma_f32_16x16x32_bf16 v[40:43], v[150:153], v[222:225], v[40:43]
	s_waitcnt lgkmcnt(3)
	v_mfma_f32_16x16x32_bf16 v[28:31], v[128:131], v[230:233], v[28:31]
	v_mfma_f32_16x16x32_bf16 v[24:27], v[150:153], v[230:233], v[24:27]
	s_waitcnt lgkmcnt(1)
	v_mfma_f32_16x16x32_bf16 v[12:15], v[128:131], v[238:241], v[12:15]
	v_mfma_f32_16x16x32_bf16 v[8:11], v[150:153], v[238:241], v[8:11]
	v_mfma_f32_16x16x32_bf16 v[120:123], v[132:135], v[178:181], v[120:123]
	v_mfma_f32_16x16x32_bf16 v[124:127], v[154:157], v[178:181], v[124:127]
	v_mfma_f32_16x16x32_bf16 v[108:111], v[132:135], v[186:189], v[108:111]
	v_mfma_f32_16x16x32_bf16 v[104:107], v[154:157], v[186:189], v[104:107]
	v_mfma_f32_16x16x32_bf16 v[92:95], v[132:135], v[194:197], v[92:95]
	v_mfma_f32_16x16x32_bf16 v[88:91], v[154:157], v[194:197], v[88:91]
	v_mfma_f32_16x16x32_bf16 v[76:79], v[132:135], v[202:205], v[76:79]
	v_mfma_f32_16x16x32_bf16 v[72:75], v[154:157], v[202:205], v[72:75]
	v_mfma_f32_16x16x32_bf16 v[60:63], v[132:135], v[218:221], v[60:63]
	v_mfma_f32_16x16x32_bf16 v[56:59], v[154:157], v[218:221], v[56:59]
	v_mfma_f32_16x16x32_bf16 v[44:47], v[132:135], v[226:229], v[44:47]
	v_mfma_f32_16x16x32_bf16 v[40:43], v[154:157], v[226:229], v[40:43]
	v_mfma_f32_16x16x32_bf16 v[28:31], v[132:135], v[234:237], v[28:31]
	v_mfma_f32_16x16x32_bf16 v[24:27], v[154:157], v[234:237], v[24:27]
	s_waitcnt lgkmcnt(0)
	v_mfma_f32_16x16x32_bf16 v[12:15], v[132:135], v[242:245], v[12:15]
	v_mfma_f32_16x16x32_bf16 v[8:11], v[154:157], v[242:245], v[8:11]
	s_barrier
	ds_read_b128 v[128:131], v148
	ds_read_b128 v[132:135], v148 offset:1024
	ds_read_b128 v[150:153], v148 offset:2048
	ds_read_b128 v[154:157], v148 offset:3072
	s_mov_b32 m0, s97
	s_nop 0
	global_load_lds_dwordx4 v141, s[80:81]
	s_mov_b32 m0, s37
	s_nop 0
	global_load_lds_dwordx4 v143, s[80:81]
	s_mov_b32 m0, s95
	s_nop 0
	global_load_lds_dwordx4 v140, s[38:39]
	s_mov_b32 m0, s48
	s_nop 0
	global_load_lds_dwordx4 v142, s[38:39]
	s_add_u32 s4, s4, 0x20080
	s_addc_u32 s5, s5, 0
	s_mov_b32 m0, s49
	s_nop 0
	global_load_lds_dwordx4 v140, s[4:5]
	s_mov_b32 m0, s50
	s_nop 0
	global_load_lds_dwordx4 v142, s[4:5]
	s_waitcnt vmcnt(8)
	s_waitcnt lgkmcnt(0)
	s_barrier
	s_waitcnt lgkmcnt(3)
	v_mfma_f32_16x16x32_bf16 v[116:119], v[128:131], v[166:169], v[116:119]
	s_waitcnt lgkmcnt(1)
	v_mfma_f32_16x16x32_bf16 v[112:115], v[150:153], v[166:169], v[112:115]
	v_mfma_f32_16x16x32_bf16 v[100:103], v[128:131], v[182:185], v[100:103]
	v_mfma_f32_16x16x32_bf16 v[96:99], v[150:153], v[182:185], v[96:99]
	v_mfma_f32_16x16x32_bf16 v[84:87], v[128:131], v[190:193], v[84:87]
	v_mfma_f32_16x16x32_bf16 v[80:83], v[150:153], v[190:193], v[80:83]
	v_mfma_f32_16x16x32_bf16 v[68:71], v[128:131], v[198:201], v[68:71]
	v_mfma_f32_16x16x32_bf16 v[64:67], v[150:153], v[198:201], v[64:67]
	v_mfma_f32_16x16x32_bf16 v[52:55], v[128:131], v[214:217], v[52:55]
	v_mfma_f32_16x16x32_bf16 v[48:51], v[150:153], v[214:217], v[48:51]
	v_mfma_f32_16x16x32_bf16 v[36:39], v[128:131], v[222:225], v[36:39]
	v_mfma_f32_16x16x32_bf16 v[32:35], v[150:153], v[222:225], v[32:35]
	v_mfma_f32_16x16x32_bf16 v[20:23], v[128:131], v[230:233], v[20:23]
	v_mfma_f32_16x16x32_bf16 v[16:19], v[150:153], v[230:233], v[16:19]
	v_mfma_f32_16x16x32_bf16 v[4:7], v[128:131], v[238:241], v[4:7]
	v_mfma_f32_16x16x32_bf16 v[0:3], v[150:153], v[238:241], v[0:3]
	v_mfma_f32_16x16x32_bf16 v[116:119], v[132:135], v[178:181], v[116:119]
	s_waitcnt lgkmcnt(0)
	v_mfma_f32_16x16x32_bf16 v[112:115], v[154:157], v[178:181], v[112:115]
	v_mfma_f32_16x16x32_bf16 v[100:103], v[132:135], v[186:189], v[100:103]
	v_mfma_f32_16x16x32_bf16 v[96:99], v[154:157], v[186:189], v[96:99]
	v_mfma_f32_16x16x32_bf16 v[84:87], v[132:135], v[194:197], v[84:87]
	v_mfma_f32_16x16x32_bf16 v[80:83], v[154:157], v[194:197], v[80:83]
	v_mfma_f32_16x16x32_bf16 v[68:71], v[132:135], v[202:205], v[68:71]
	v_mfma_f32_16x16x32_bf16 v[64:67], v[154:157], v[202:205], v[64:67]
	v_mfma_f32_16x16x32_bf16 v[52:55], v[132:135], v[218:221], v[52:55]
	v_mfma_f32_16x16x32_bf16 v[48:51], v[154:157], v[218:221], v[48:51]
	v_mfma_f32_16x16x32_bf16 v[36:39], v[132:135], v[226:229], v[36:39]
	v_mfma_f32_16x16x32_bf16 v[32:35], v[154:157], v[226:229], v[32:35]
	v_mfma_f32_16x16x32_bf16 v[20:23], v[132:135], v[234:237], v[20:23]
	v_mfma_f32_16x16x32_bf16 v[16:19], v[154:157], v[234:237], v[16:19]
	v_mfma_f32_16x16x32_bf16 v[4:7], v[132:135], v[242:245], v[4:7]
	v_mfma_f32_16x16x32_bf16 v[0:3], v[154:157], v[242:245], v[0:3]
	s_add_u32 s59, s59, 0x100
	s_addc_u32 s60, s60, 0
	s_add_u32 s61, s61, 0x100
	s_addc_u32 s62, s62, 0
	s_cmp_ge_i32 s63, s28
	s_mov_b32 s4, s63
	s_barrier
	s_cbranch_scc0 .LBB0_509
	v_readlane_b32 s60, v252, 25
	v_readlane_b32 s62, v252, 27
	v_readlane_b32 s64, v252, 9
	v_readlane_b32 s61, v252, 26
	v_readlane_b32 s63, v252, 28
	v_readlane_b32 s65, v252, 10

; #define PG8_STAGE(bufoff, gbase, voff) do { _Pragma("unroll") for (int _i = 0; _i < 2; ++_i) { \
;         const unsigned _m0 = ldsu + (unsigned)(bufoff) + ldsw + (unsigned)(_i * 8192); \
;         asm volatile("s_mov_b32 m0, %2\n\ts_nop 0\n\tglobal_load_lds_dwordx4 %0, %1" :: "v"((voff)[_i]), "s"((const char*)(gbase)), "s"(_m0) : "memory"); } } while (0)
; #define PG8_LDA(dst, b, h) do { _Pragma("unroll") for (int m = 0; m < 4; ++m) _Pragma("unroll") for (int k = 0; k < 2; ++k) dst[m][k] = *(const LAS bf16x8*)(lds + PG8_SA(b, h) + aoff + m * 2048 + k * 1024); } while (0)
; #define PG8_LDB(dst, b, h) do { _Pragma("unroll") for (int n = 0; n < 2; ++n) _Pragma("unroll") for (int k = 0; k < 2; ++k) dst[n][k] = *(const LAS bf16x8*)(lds + bbase[b][h] + n * 2048 + k * 1024); } while (0)
; #define PG8_WAIT_V(n) asm volatile("s_waitcnt vmcnt(" #n ")" ::: "memory")
; #define PG8_WAIT_L(n) asm volatile("s_waitcnt lgkmcnt(" #n ")" ::: "memory")
; #define PG8_BAR __builtin_amdgcn_s_barrier()
; #define PG8_SCHED __builtin_amdgcn_sched_barrier(0)
; template <class Epi>
; __device__ __forceinline__ void gemm_phase(LAS unsigned char* lds, const Gemm g, const StaticOrder& S, const Epi& E) {
;     ...
;             const char* a2 = last ? nA : cA + (size_t)(t + 2) * kstep; const char* b2 = last ? nB : cB + (size_t)(t + 2) * kstep;
;             const char* a3 = a2 + kstep; const char* b3 = b2 + kstep;
;             const char* b1 = cB + (size_t)(t + 1) * kstep;
;             PG8_LDB(B0, 0, 0); PG8_SCHED; PG8_LDA(At, 0, 0); PG8_LDA(At2, 0, 1); PG8_STAGE(PG8_SB(1, 1), b1 + hstepB, voffB);
;             PG8_WAIT_V(8); PG8_WAIT_L(0); PG8_BAR; PG8_MMA2B(0, At, At2, B0); PG8_BAR; PG8_SCHED;
;             PG8_LDB(B0, 0, 1); PG8_STAGE(PG8_SB(0, 0), b2, voffB); PG8_STAGE(PG8_SA(0, 0), a2, voffA); PG8_STAGE(PG8_SA(0, 1), a2 + hstepA, voffA);
;             PG8_WAIT_V(8); PG8_WAIT_L(0); PG8_BAR; PG8_MMA2B(1, At, At2, B0); PG8_BAR; PG8_SCHED;
.LBB0_584:
	ds_read_b128 v[128:131], v155
	ds_read_b128 v[132:135], v155 offset:1024
	ds_read_b128 v[136:139], v155 offset:2048
	ds_read_b128 v[140:143], v155 offset:3072
	s_add_u32 s10, s8, 0x100
	s_addc_u32 s11, s9, 0
	s_cmp_eq_u32 s68, 12
	s_cselect_b32 s84, s67, s87
	s_cselect_b32 s85, s43, s88
	s_cselect_b32 s90, s86, s10
	s_cselect_b32 s91, s39, s11
	s_add_u32 s96, s84, 0x80
	s_addc_u32 s97, s85, 0
	ds_read_b128 v[144:147], v156
	ds_read_b128 v[178:181], v156 offset:1024
	ds_read_b128 v[182:185], v156 offset:2048
	ds_read_b128 v[186:189], v156 offset:3072
	ds_read_b128 v[190:193], v156 offset:4096
	ds_read_b128 v[194:197], v156 offset:5120
	ds_read_b128 v[198:201], v156 offset:6144
	ds_read_b128 v[202:205], v156 offset:7168
	ds_read_b128 v[214:217], v156 offset:16384
	ds_read_b128 v[218:221], v156 offset:17408
	ds_read_b128 v[222:225], v156 offset:18432
	ds_read_b128 v[226:229], v156 offset:19456
	ds_read_b128 v[230:233], v156 offset:20480
	ds_read_b128 v[234:237], v156 offset:21504
	ds_read_b128 v[238:241], v156 offset:22528
	ds_read_b128 v[242:245], v156 offset:23552
	s_add_u32 s8, s8, 0x40080
	s_addc_u32 s9, s9, 0
	s_mov_b32 m0, s61
	s_nop 0
	global_load_lds_dwordx4 v151, s[8:9]
	s_mov_b32 m0, s64
	s_nop 0
	global_load_lds_dwordx4 v153, s[8:9]
	s_waitcnt vmcnt(8)
	s_waitcnt lgkmcnt(0)
	s_barrier
	s_waitcnt lgkmcnt(14)
	v_mfma_f32_16x16x32_bf16 v[76:79], v[128:131], v[144:147], v[76:79]
	v_mfma_f32_16x16x32_bf16 v[72:75], v[136:139], v[144:147], v[72:75]
	s_waitcnt lgkmcnt(13)
	v_mfma_f32_16x16x32_bf16 v[64:67], v[128:131], v[182:185], v[64:67]
	v_mfma_f32_16x16x32_bf16 v[60:63], v[136:139], v[182:185], v[60:63]
	s_waitcnt lgkmcnt(11)
	v_mfma_f32_16x16x32_bf16 v[56:59], v[128:131], v[190:193], v[56:59]
	v_mfma_f32_16x16x32_bf16 v[52:55], v[136:139], v[190:193], v[52:55]
	s_waitcnt lgkmcnt(9)
	v_mfma_f32_16x16x32_bf16 v[112:115], v[128:131], v[198:201], v[112:115]
	v_mfma_f32_16x16x32_bf16 v[104:107], v[136:139], v[198:201], v[104:107]
	s_waitcnt lgkmcnt(7)
	v_mfma_f32_16x16x32_bf16 v[36:39], v[128:131], v[214:217], v[36:39]
	v_mfma_f32_16x16x32_bf16 v[32:35], v[136:139], v[214:217], v[32:35]
	s_waitcnt lgkmcnt(5)
	v_mfma_f32_16x16x32_bf16 v[28:31], v[128:131], v[222:225], v[28:31]
	v_mfma_f32_16x16x32_bf16 v[24:27], v[136:139], v[222:225], v[24:27]
	s_waitcnt lgkmcnt(3)
	v_mfma_f32_16x16x32_bf16 v[16:19], v[128:131], v[230:233], v[16:19]
	v_mfma_f32_16x16x32_bf16 v[12:15], v[136:139], v[230:233], v[12:15]
	s_waitcnt lgkmcnt(1)
	v_mfma_f32_16x16x32_bf16 v[88:91], v[128:131], v[238:241], v[88:91]
	v_mfma_f32_16x16x32_bf16 v[84:87], v[136:139], v[238:241], v[84:87]
	v_mfma_f32_16x16x32_bf16 v[76:79], v[132:135], v[178:181], v[76:79]
	v_mfma_f32_16x16x32_bf16 v[72:75], v[140:143], v[178:181], v[72:75]
	v_mfma_f32_16x16x32_bf16 v[64:67], v[132:135], v[186:189], v[64:67]
	v_mfma_f32_16x16x32_bf16 v[60:63], v[140:143], v[186:189], v[60:63]
	v_mfma_f32_16x16x32_bf16 v[56:59], v[132:135], v[194:197], v[56:59]
	v_mfma_f32_16x16x32_bf16 v[52:55], v[140:143], v[194:197], v[52:55]
	v_mfma_f32_16x16x32_bf16 v[112:115], v[132:135], v[202:205], v[112:115]
	v_mfma_f32_16x16x32_bf16 v[104:107], v[140:143], v[202:205], v[104:107]
	v_mfma_f32_16x16x32_bf16 v[36:39], v[132:135], v[218:221], v[36:39]
	v_mfma_f32_16x16x32_bf16 v[32:35], v[140:143], v[218:221], v[32:35]
	v_mfma_f32_16x16x32_bf16 v[28:31], v[132:135], v[226:229], v[28:31]
	v_mfma_f32_16x16x32_bf16 v[24:27], v[140:143], v[226:229], v[24:27]
	v_mfma_f32_16x16x32_bf16 v[16:19], v[132:135], v[234:237], v[16:19]
	v_mfma_f32_16x16x32_bf16 v[12:15], v[140:143], v[234:237], v[12:15]
	s_waitcnt lgkmcnt(0)
	v_mfma_f32_16x16x32_bf16 v[88:91], v[132:135], v[242:245], v[88:91]
	v_mfma_f32_16x16x32_bf16 v[84:87], v[140:143], v[242:245], v[84:87]
	s_barrier
	ds_read_b128 v[128:131], v157
	ds_read_b128 v[132:135], v157 offset:1024
	ds_read_b128 v[136:139], v157 offset:2048
	ds_read_b128 v[140:143], v157 offset:3072
	s_mov_b32 m0, s47
	s_nop 0
	global_load_lds_dwordx4 v151, s[90:91]
	s_mov_b32 m0, s48
	s_nop 0
	global_load_lds_dwordx4 v153, s[90:91]
	s_mov_b32 m0, s37
	s_nop 0
	global_load_lds_dwordx4 v150, s[84:85]
	s_mov_b32 m0, s49
	s_nop 0
	global_load_lds_dwordx4 v152, s[84:85]
	s_add_u32 s8, s84, 0x40000
	s_addc_u32 s9, s85, 0
	s_mov_b32 m0, s50
	s_nop 0
	global_load_lds_dwordx4 v150, s[8:9]
	s_mov_b32 m0, s51
	s_nop 0
	global_load_lds_dwordx4 v152, s[8:9]
	s_waitcnt vmcnt(8)
	s_waitcnt lgkmcnt(0)
	s_barrier
	s_waitcnt lgkmcnt(3)
	v_mfma_f32_16x16x32_bf16 v[68:71], v[128:131], v[144:147], v[68:71]
	s_waitcnt lgkmcnt(1)
	v_mfma_f32_16x16x32_bf16 v[124:127], v[136:139], v[144:147], v[124:127]
	v_mfma_f32_16x16x32_bf16 v[48:51], v[128:131], v[182:185], v[48:51]
	v_mfma_f32_16x16x32_bf16 v[120:123], v[136:139], v[182:185], v[120:123]
	v_mfma_f32_16x16x32_bf16 v[44:47], v[128:131], v[190:193], v[44:47]
	v_mfma_f32_16x16x32_bf16 v[116:119], v[136:139], v[190:193], v[116:119]
	v_mfma_f32_16x16x32_bf16 v[40:43], v[128:131], v[198:201], v[40:43]
	v_mfma_f32_16x16x32_bf16 v[108:111], v[136:139], v[198:201], v[108:111]
	v_mfma_f32_16x16x32_bf16 v[20:23], v[128:131], v[214:217], v[20:23]
	v_mfma_f32_16x16x32_bf16 v[100:103], v[136:139], v[214:217], v[100:103]
	v_mfma_f32_16x16x32_bf16 v[8:11], v[128:131], v[222:225], v[8:11]
	v_mfma_f32_16x16x32_bf16 v[96:99], v[136:139], v[222:225], v[96:99]
	v_mfma_f32_16x16x32_bf16 v[4:7], v[128:131], v[230:233], v[4:7]
	v_mfma_f32_16x16x32_bf16 v[92:95], v[136:139], v[230:233], v[92:95]
	v_mfma_f32_16x16x32_bf16 v[0:3], v[128:131], v[238:241], v[0:3]
	v_mfma_f32_16x16x32_bf16 v[80:83], v[136:139], v[238:241], v[80:83]
	v_mfma_f32_16x16x32_bf16 v[68:71], v[132:135], v[178:181], v[68:71]
	s_waitcnt lgkmcnt(0)
	v_mfma_f32_16x16x32_bf16 v[124:127], v[140:143], v[178:181], v[124:127]
	v_mfma_f32_16x16x32_bf16 v[48:51], v[132:135], v[186:189], v[48:51]
	v_mfma_f32_16x16x32_bf16 v[120:123], v[140:143], v[186:189], v[120:123]
	v_mfma_f32_16x16x32_bf16 v[44:47], v[132:135], v[194:197], v[44:47]
	v_mfma_f32_16x16x32_bf16 v[116:119], v[140:143], v[194:197], v[116:119]
	v_mfma_f32_16x16x32_bf16 v[40:43], v[132:135], v[202:205], v[40:43]
	v_mfma_f32_16x16x32_bf16 v[108:111], v[140:143], v[202:205], v[108:111]
	v_mfma_f32_16x16x32_bf16 v[20:23], v[132:135], v[218:221], v[20:23]
	v_mfma_f32_16x16x32_bf16 v[100:103], v[140:143], v[218:221], v[100:103]
	v_mfma_f32_16x16x32_bf16 v[8:11], v[132:135], v[226:229], v[8:11]
	v_mfma_f32_16x16x32_bf16 v[96:99], v[140:143], v[226:229], v[96:99]
	v_mfma_f32_16x16x32_bf16 v[4:7], v[132:135], v[234:237], v[4:7]
	v_mfma_f32_16x16x32_bf16 v[92:95], v[140:143], v[234:237], v[92:95]
	v_mfma_f32_16x16x32_bf16 v[0:3], v[132:135], v[242:245], v[0:3]
	v_mfma_f32_16x16x32_bf16 v[80:83], v[140:143], v[242:245], v[80:83]
	s_barrier
; #define PG8_STAGE(bufoff, gbase, voff) do { _Pragma("unroll") for (int _i = 0; _i < 2; ++_i) { \
;         const unsigned _m0 = ldsu + (unsigned)(bufoff) + ldsw + (unsigned)(_i * 8192); \
;         asm volatile("s_mov_b32 m0, %2\n\ts_nop 0\n\tglobal_load_lds_dwordx4 %0, %1" :: "v"((voff)[_i]), "s"((const char*)(gbase)), "s"(_m0) : "memory"); } } while (0)
; #define PG8_LDA(dst, b, h) do { _Pragma("unroll") for (int m = 0; m < 4; ++m) _Pragma("unroll") for (int k = 0; k < 2; ++k) dst[m][k] = *(const LAS bf16x8*)(lds + PG8_SA(b, h) + aoff + m * 2048 + k * 1024); } while (0)
; #define PG8_LDB(dst, b, h) do { _Pragma("unroll") for (int n = 0; n < 2; ++n) _Pragma("unroll") for (int k = 0; k < 2; ++k) dst[n][k] = *(const LAS bf16x8*)(lds + bbase[b][h] + n * 2048 + k * 1024); } while (0)
; #define PG8_WAIT_V(n) asm volatile("s_waitcnt vmcnt(" #n ")" ::: "memory")
; #define PG8_WAIT_L(n) asm volatile("s_waitcnt lgkmcnt(" #n ")" ::: "memory")
; #define PG8_BAR __builtin_amdgcn_s_barrier()
; #define PG8_SCHED __builtin_amdgcn_sched_barrier(0)
; template <class Epi>
; __device__ __forceinline__ void gemm_phase(LAS unsigned char* lds, const Gemm g, const StaticOrder& S, const Epi& E) {
;     ...
;         for (int t = 0; t < nt; t += 2) {
;     ...
;             PG8_LDB(B0, 1, 0); PG8_SCHED; PG8_LDA(At, 1, 0); PG8_LDA(At2, 1, 1); PG8_STAGE(PG8_SB(0, 1), b2 + hstepB, voffB);
;             PG8_WAIT_V(8); PG8_WAIT_L(0); PG8_BAR; PG8_MMA2B(0, At, At2, B0); PG8_BAR; PG8_SCHED;
;             PG8_LDB(B0, 1, 1); PG8_STAGE(PG8_SB(1, 0), b3, voffB); PG8_STAGE(PG8_SA(1, 0), a3, voffA); PG8_STAGE(PG8_SA(1, 1), a3 + hstepA, voffA);
;             PG8_WAIT_V(8); PG8_WAIT_L(0); PG8_BAR; PG8_MMA2B(1, At, At2, B0); PG8_BAR; PG8_SCHED;
;     ...
;         if (wr == 0) PG8_BAR;
	ds_read_b128 v[128:131], v158
	ds_read_b128 v[132:135], v158 offset:1024
	ds_read_b128 v[136:139], v158 offset:2048
	ds_read_b128 v[140:143], v158 offset:3072
	ds_read_b128 v[144:147], v156 offset:32768
	ds_read_b128 v[178:181], v156 offset:33792
	ds_read_b128 v[182:185], v156 offset:34816
	ds_read_b128 v[186:189], v156 offset:35840
	ds_read_b128 v[190:193], v156 offset:36864
	ds_read_b128 v[194:197], v156 offset:37888
	ds_read_b128 v[198:201], v156 offset:38912
	ds_read_b128 v[202:205], v156 offset:39936
	ds_read_b128 v[214:217], v156 offset:49152
	ds_read_b128 v[218:221], v156 offset:50176
	ds_read_b128 v[222:225], v156 offset:51200
	ds_read_b128 v[226:229], v156 offset:52224
	ds_read_b128 v[230:233], v156 offset:53248
	ds_read_b128 v[234:237], v156 offset:54272
	ds_read_b128 v[238:241], v156 offset:55296
	ds_read_b128 v[242:245], v156 offset:56320
	s_add_u32 s8, s90, 0x40000
	s_addc_u32 s9, s91, 0
	s_mov_b32 m0, s52
	s_nop 0
	global_load_lds_dwordx4 v151, s[8:9]
	s_mov_b32 m0, s53
	s_nop 0
	global_load_lds_dwordx4 v153, s[8:9]
	s_waitcnt vmcnt(8)
	s_waitcnt lgkmcnt(0)
	s_barrier
	s_waitcnt lgkmcnt(14)
	v_mfma_f32_16x16x32_bf16 v[76:79], v[128:131], v[144:147], v[76:79]
	v_mfma_f32_16x16x32_bf16 v[72:75], v[136:139], v[144:147], v[72:75]
	s_waitcnt lgkmcnt(13)
	v_mfma_f32_16x16x32_bf16 v[64:67], v[128:131], v[182:185], v[64:67]
	v_mfma_f32_16x16x32_bf16 v[60:63], v[136:139], v[182:185], v[60:63]
	s_waitcnt lgkmcnt(11)
	v_mfma_f32_16x16x32_bf16 v[56:59], v[128:131], v[190:193], v[56:59]
	v_mfma_f32_16x16x32_bf16 v[52:55], v[136:139], v[190:193], v[52:55]
	s_waitcnt lgkmcnt(9)
	v_mfma_f32_16x16x32_bf16 v[112:115], v[128:131], v[198:201], v[112:115]
	v_mfma_f32_16x16x32_bf16 v[104:107], v[136:139], v[198:201], v[104:107]
	s_waitcnt lgkmcnt(7)
	v_mfma_f32_16x16x32_bf16 v[36:39], v[128:131], v[214:217], v[36:39]
	v_mfma_f32_16x16x32_bf16 v[32:35], v[136:139], v[214:217], v[32:35]
	s_waitcnt lgkmcnt(5)
	v_mfma_f32_16x16x32_bf16 v[28:31], v[128:131], v[222:225], v[28:31]
	v_mfma_f32_16x16x32_bf16 v[24:27], v[136:139], v[222:225], v[24:27]
	s_waitcnt lgkmcnt(3)
	v_mfma_f32_16x16x32_bf16 v[16:19], v[128:131], v[230:233], v[16:19]
	v_mfma_f32_16x16x32_bf16 v[12:15], v[136:139], v[230:233], v[12:15]
	s_waitcnt lgkmcnt(1)
	v_mfma_f32_16x16x32_bf16 v[88:91], v[128:131], v[238:241], v[88:91]
	v_mfma_f32_16x16x32_bf16 v[84:87], v[136:139], v[238:241], v[84:87]
	v_mfma_f32_16x16x32_bf16 v[76:79], v[132:135], v[178:181], v[76:79]
	v_mfma_f32_16x16x32_bf16 v[72:75], v[140:143], v[178:181], v[72:75]
	v_mfma_f32_16x16x32_bf16 v[64:67], v[132:135], v[186:189], v[64:67]
	v_mfma_f32_16x16x32_bf16 v[60:63], v[140:143], v[186:189], v[60:63]
	v_mfma_f32_16x16x32_bf16 v[56:59], v[132:135], v[194:197], v[56:59]
	v_mfma_f32_16x16x32_bf16 v[52:55], v[140:143], v[194:197], v[52:55]
	v_mfma_f32_16x16x32_bf16 v[112:115], v[132:135], v[202:205], v[112:115]
	v_mfma_f32_16x16x32_bf16 v[104:107], v[140:143], v[202:205], v[104:107]
	v_mfma_f32_16x16x32_bf16 v[36:39], v[132:135], v[218:221], v[36:39]
	v_mfma_f32_16x16x32_bf16 v[32:35], v[140:143], v[218:221], v[32:35]
	v_mfma_f32_16x16x32_bf16 v[28:31], v[132:135], v[226:229], v[28:31]
	v_mfma_f32_16x16x32_bf16 v[24:27], v[140:143], v[226:229], v[24:27]
	v_mfma_f32_16x16x32_bf16 v[16:19], v[132:135], v[234:237], v[16:19]
	v_mfma_f32_16x16x32_bf16 v[12:15], v[140:143], v[234:237], v[12:15]
	s_waitcnt lgkmcnt(0)
	v_mfma_f32_16x16x32_bf16 v[88:91], v[132:135], v[242:245], v[88:91]
	v_mfma_f32_16x16x32_bf16 v[84:87], v[140:143], v[242:245], v[84:87]
	s_barrier
	s_add_u32 s8, s90, 0x80
	ds_read_b128 v[128:131], v159
	ds_read_b128 v[132:135], v159 offset:1024
	ds_read_b128 v[136:139], v159 offset:2048
	ds_read_b128 v[140:143], v159 offset:3072
	s_addc_u32 s9, s91, 0
	s_mov_b32 m0, s55
	s_nop 0
	global_load_lds_dwordx4 v151, s[8:9]
	s_mov_b32 m0, s56
	s_nop 0
	global_load_lds_dwordx4 v153, s[8:9]
	s_mov_b32 m0, s57
	s_nop 0
	global_load_lds_dwordx4 v150, s[96:97]
	s_mov_b32 m0, s58
	s_nop 0
	global_load_lds_dwordx4 v152, s[96:97]
	s_add_u32 s8, s84, 0x40080
	s_addc_u32 s9, s85, 0
	s_mov_b32 m0, s59
	s_nop 0
	global_load_lds_dwordx4 v150, s[8:9]
	s_mov_b32 m0, s60
	s_nop 0
	global_load_lds_dwordx4 v152, s[8:9]
	s_waitcnt vmcnt(8)
	s_waitcnt lgkmcnt(0)
	s_barrier
	s_waitcnt lgkmcnt(3)
	v_mfma_f32_16x16x32_bf16 v[68:71], v[128:131], v[144:147], v[68:71]
	s_waitcnt lgkmcnt(1)
	v_mfma_f32_16x16x32_bf16 v[124:127], v[136:139], v[144:147], v[124:127]
	v_mfma_f32_16x16x32_bf16 v[48:51], v[128:131], v[182:185], v[48:51]
	v_mfma_f32_16x16x32_bf16 v[120:123], v[136:139], v[182:185], v[120:123]
	v_mfma_f32_16x16x32_bf16 v[44:47], v[128:131], v[190:193], v[44:47]
	v_mfma_f32_16x16x32_bf16 v[116:119], v[136:139], v[190:193], v[116:119]
	v_mfma_f32_16x16x32_bf16 v[40:43], v[128:131], v[198:201], v[40:43]
	v_mfma_f32_16x16x32_bf16 v[108:111], v[136:139], v[198:201], v[108:111]
	v_mfma_f32_16x16x32_bf16 v[20:23], v[128:131], v[214:217], v[20:23]
	v_mfma_f32_16x16x32_bf16 v[100:103], v[136:139], v[214:217], v[100:103]
	v_mfma_f32_16x16x32_bf16 v[8:11], v[128:131], v[222:225], v[8:11]
	v_mfma_f32_16x16x32_bf16 v[96:99], v[136:139], v[222:225], v[96:99]
	v_mfma_f32_16x16x32_bf16 v[4:7], v[128:131], v[230:233], v[4:7]
	v_mfma_f32_16x16x32_bf16 v[92:95], v[136:139], v[230:233], v[92:95]
	v_mfma_f32_16x16x32_bf16 v[0:3], v[128:131], v[238:241], v[0:3]
	v_mfma_f32_16x16x32_bf16 v[80:83], v[136:139], v[238:241], v[80:83]
	v_mfma_f32_16x16x32_bf16 v[68:71], v[132:135], v[178:181], v[68:71]
	s_waitcnt lgkmcnt(0)
	v_mfma_f32_16x16x32_bf16 v[124:127], v[140:143], v[178:181], v[124:127]
	v_mfma_f32_16x16x32_bf16 v[48:51], v[132:135], v[186:189], v[48:51]
	v_mfma_f32_16x16x32_bf16 v[120:123], v[140:143], v[186:189], v[120:123]
	v_mfma_f32_16x16x32_bf16 v[44:47], v[132:135], v[194:197], v[44:47]
	v_mfma_f32_16x16x32_bf16 v[116:119], v[140:143], v[194:197], v[116:119]
	v_mfma_f32_16x16x32_bf16 v[40:43], v[132:135], v[202:205], v[40:43]
	v_mfma_f32_16x16x32_bf16 v[108:111], v[140:143], v[202:205], v[108:111]
	v_mfma_f32_16x16x32_bf16 v[20:23], v[132:135], v[218:221], v[20:23]
	v_mfma_f32_16x16x32_bf16 v[100:103], v[140:143], v[218:221], v[100:103]
	v_mfma_f32_16x16x32_bf16 v[8:11], v[132:135], v[226:229], v[8:11]
	v_mfma_f32_16x16x32_bf16 v[96:99], v[140:143], v[226:229], v[96:99]
	v_mfma_f32_16x16x32_bf16 v[4:7], v[132:135], v[234:237], v[4:7]
	v_mfma_f32_16x16x32_bf16 v[92:95], v[140:143], v[234:237], v[92:95]
	v_mfma_f32_16x16x32_bf16 v[0:3], v[132:135], v[242:245], v[0:3]
	v_mfma_f32_16x16x32_bf16 v[80:83], v[140:143], v[242:245], v[80:83]
	s_add_i32 s68, s68, 2
	s_add_u32 s87, s87, 0x100
	s_addc_u32 s88, s88, 0
	s_cmp_gt_u32 s68, 13
	s_mov_b64 s[8:9], s[10:11]
	s_barrier
	s_cbranch_scc0 .LBB0_584
	s_and_b64 vcc, exec, s[4:5]
	s_cbranch_vccz .LBB0_587
	s_barrier

; #define PG8_STAGE(bufoff, gbase, voff) do { _Pragma("unroll") for (int _i = 0; _i < 2; ++_i) { \
;         const unsigned _m0 = ldsu + (unsigned)(bufoff) + ldsw + (unsigned)(_i * 8192); \
;         asm volatile("s_mov_b32 m0, %2\n\ts_nop 0\n\tglobal_load_lds_dwordx4 %0, %1" :: "v"((voff)[_i]), "s"((const char*)(gbase)), "s"(_m0) : "memory"); } } while (0)
; #define PG8_LDA(dst, b, h) do { _Pragma("unroll") for (int m = 0; m < 4; ++m) _Pragma("unroll") for (int k = 0; k < 2; ++k) dst[m][k] = *(const LAS bf16x8*)(lds + PG8_SA(b, h) + aoff + m * 2048 + k * 1024); } while (0)
; #define PG8_LDB(dst, b, h) do { _Pragma("unroll") for (int n = 0; n < 2; ++n) _Pragma("unroll") for (int k = 0; k < 2; ++k) dst[n][k] = *(const LAS bf16x8*)(lds + bbase[b][h] + n * 2048 + k * 1024); } while (0)
; #define PG8_WAIT_V(n) asm volatile("s_waitcnt vmcnt(" #n ")" ::: "memory")
; #define PG8_WAIT_L(n) asm volatile("s_waitcnt lgkmcnt(" #n ")" ::: "memory")
; #define PG8_BAR __builtin_amdgcn_s_barrier()
; #define PG8_SCHED __builtin_amdgcn_sched_barrier(0)
; template <class Epi>
; __device__ __forceinline__ void gemm_phase(LAS unsigned char* lds, const Gemm g, const StaticOrder& S, const Epi& E) {
;     ...
;             const char* a2 = last ? nA : cA + (size_t)(t + 2) * kstep; const char* b2 = last ? nB : cB + (size_t)(t + 2) * kstep;
;             const char* a3 = a2 + kstep; const char* b3 = b2 + kstep;
;             const char* b1 = cB + (size_t)(t + 1) * kstep;
;             PG8_LDB(B0, 0, 0); PG8_SCHED; PG8_LDA(At, 0, 0); PG8_LDA(At2, 0, 1); PG8_STAGE(PG8_SB(1, 1), b1 + hstepB, voffB);
;             PG8_WAIT_V(8); PG8_WAIT_L(0); PG8_BAR; PG8_MMA2B(0, At, At2, B0); PG8_BAR; PG8_SCHED;
;             PG8_LDB(B0, 0, 1); PG8_STAGE(PG8_SB(0, 0), b2, voffB); PG8_STAGE(PG8_SA(0, 0), a2, voffA); PG8_STAGE(PG8_SA(0, 1), a2 + hstepA, voffA);
;             PG8_WAIT_V(8); PG8_WAIT_L(0); PG8_BAR; PG8_MMA2B(1, At, At2, B0); PG8_BAR; PG8_SCHED;
.LBB0_662:
	s_add_i32 s85, s38, 2
	s_add_u32 s42, s67, 0x80
	ds_read_b128 v[74:77], v71
	ds_read_b128 v[78:81], v71 offset:1024
	ds_read_b128 v[82:85], v71 offset:2048
	ds_read_b128 v[86:89], v71 offset:3072
	s_addc_u32 s43, s68, 0
	s_cmp_eq_u32 s62, s38
	s_cselect_b32 s38, s10, s69
	s_cselect_b32 s39, s11, s84
	s_cselect_b32 s82, s37, s42
	s_cselect_b32 s83, s13, s43
	s_add_u32 s42, s38, 0x80
	s_addc_u32 s43, s39, 0
	s_add_u32 s80, s82, 0x80
	s_addc_u32 s81, s83, 0
	ds_read_b128 v[90:93], v72
	ds_read_b128 v[94:97], v72 offset:1024
	ds_read_b128 v[98:101], v72 offset:2048
	ds_read_b128 v[102:105], v72 offset:3072
	ds_read_b128 v[106:109], v72 offset:4096
	ds_read_b128 v[110:113], v72 offset:5120
	ds_read_b128 v[114:117], v72 offset:6144
	ds_read_b128 v[118:121], v72 offset:7168
	ds_read_b128 v[122:125], v72 offset:16384
	ds_read_b128 v[126:129], v72 offset:17408
	ds_read_b128 v[130:133], v72 offset:18432
	ds_read_b128 v[134:137], v72 offset:19456
	ds_read_b128 v[138:141], v72 offset:20480
	ds_read_b128 v[142:145], v72 offset:21504
	ds_read_b128 v[146:149], v72 offset:22528
	ds_read_b128 v[150:153], v72 offset:23552
	s_add_u32 s86, s67, 0x10000
	s_addc_u32 s87, s68, 0
	s_mov_b32 m0, s63
	s_nop 0
	global_load_lds_dwordx4 v67, s[86:87]
	s_mov_b32 m0, s64
	s_nop 0
	global_load_lds_dwordx4 v69, s[86:87]
	s_waitcnt vmcnt(8)
	s_waitcnt lgkmcnt(0)
	s_barrier
	s_waitcnt lgkmcnt(14)
	v_mfma_f32_16x16x32_bf16 v[60:63], v[74:77], v[90:93], v[60:63]
	v_mfma_f32_16x16x32_bf16 v[56:59], v[82:85], v[90:93], v[56:59]
	s_waitcnt lgkmcnt(13)
	v_mfma_f32_16x16x32_bf16 v[52:55], v[74:77], v[98:101], v[52:55]
	v_mfma_f32_16x16x32_bf16 v[48:51], v[82:85], v[98:101], v[48:51]
	s_waitcnt lgkmcnt(11)
	v_mfma_f32_16x16x32_bf16 v[44:47], v[74:77], v[106:109], v[44:47]
	v_mfma_f32_16x16x32_bf16 v[40:43], v[82:85], v[106:109], v[40:43]
	s_waitcnt lgkmcnt(9)
	v_mfma_f32_16x16x32_bf16 v[36:39], v[74:77], v[114:117], v[36:39]
	v_mfma_f32_16x16x32_bf16 v[32:35], v[82:85], v[114:117], v[32:35]
	s_waitcnt lgkmcnt(7)
	v_mfma_f32_16x16x32_bf16 v[28:31], v[74:77], v[122:125], v[28:31]
	v_mfma_f32_16x16x32_bf16 v[24:27], v[82:85], v[122:125], v[24:27]
	s_waitcnt lgkmcnt(5)
	v_mfma_f32_16x16x32_bf16 v[20:23], v[74:77], v[130:133], v[20:23]
	v_mfma_f32_16x16x32_bf16 v[16:19], v[82:85], v[130:133], v[16:19]
	s_waitcnt lgkmcnt(3)
	v_mfma_f32_16x16x32_bf16 v[12:15], v[74:77], v[138:141], v[12:15]
	v_mfma_f32_16x16x32_bf16 v[8:11], v[82:85], v[138:141], v[8:11]
	s_waitcnt lgkmcnt(1)
	v_mfma_f32_16x16x32_bf16 v[4:7], v[74:77], v[146:149], v[4:7]
	v_mfma_f32_16x16x32_bf16 v[0:3], v[82:85], v[146:149], v[0:3]
	v_mfma_f32_16x16x32_bf16 v[60:63], v[78:81], v[94:97], v[60:63]
	v_mfma_f32_16x16x32_bf16 v[56:59], v[86:89], v[94:97], v[56:59]
	v_mfma_f32_16x16x32_bf16 v[52:55], v[78:81], v[102:105], v[52:55]
	v_mfma_f32_16x16x32_bf16 v[48:51], v[86:89], v[102:105], v[48:51]
	v_mfma_f32_16x16x32_bf16 v[44:47], v[78:81], v[110:113], v[44:47]
	v_mfma_f32_16x16x32_bf16 v[40:43], v[86:89], v[110:113], v[40:43]
	v_mfma_f32_16x16x32_bf16 v[36:39], v[78:81], v[118:121], v[36:39]
	v_mfma_f32_16x16x32_bf16 v[32:35], v[86:89], v[118:121], v[32:35]
	v_mfma_f32_16x16x32_bf16 v[28:31], v[78:81], v[126:129], v[28:31]
	v_mfma_f32_16x16x32_bf16 v[24:27], v[86:89], v[126:129], v[24:27]
	v_mfma_f32_16x16x32_bf16 v[20:23], v[78:81], v[134:137], v[20:23]
	v_mfma_f32_16x16x32_bf16 v[16:19], v[86:89], v[134:137], v[16:19]
	v_mfma_f32_16x16x32_bf16 v[12:15], v[78:81], v[142:145], v[12:15]
	v_mfma_f32_16x16x32_bf16 v[8:11], v[86:89], v[142:145], v[8:11]
	s_waitcnt lgkmcnt(0)
	v_mfma_f32_16x16x32_bf16 v[4:7], v[78:81], v[150:153], v[4:7]
	v_mfma_f32_16x16x32_bf16 v[0:3], v[86:89], v[150:153], v[0:3]
	s_barrier
	s_mov_b32 m0, s48
	s_nop 0
	global_load_lds_dwordx4 v67, s[82:83]
	s_mov_b32 m0, s49
	s_nop 0
	global_load_lds_dwordx4 v69, s[82:83]
	s_mov_b32 m0, s47
	s_nop 0
	global_load_lds_dwordx4 v66, s[38:39]
	s_mov_b32 m0, s50
	s_nop 0
	global_load_lds_dwordx4 v68, s[38:39]
	s_add_u32 s86, s38, 0x18000
	s_addc_u32 s87, s39, 0
	s_mov_b32 m0, s51
	s_nop 0
	global_load_lds_dwordx4 v66, s[86:87]
	s_mov_b32 m0, s52
	s_nop 0
	global_load_lds_dwordx4 v68, s[86:87]
	s_waitcnt vmcnt(8)
	s_waitcnt lgkmcnt(0)
	s_barrier
; #define PG8_STAGE(bufoff, gbase, voff) do { _Pragma("unroll") for (int _i = 0; _i < 2; ++_i) { \
;         const unsigned _m0 = ldsu + (unsigned)(bufoff) + ldsw + (unsigned)(_i * 8192); \
;         asm volatile("s_mov_b32 m0, %2\n\ts_nop 0\n\tglobal_load_lds_dwordx4 %0, %1" :: "v"((voff)[_i]), "s"((const char*)(gbase)), "s"(_m0) : "memory"); } } while (0)
; #define PG8_LDA(dst, b, h) do { _Pragma("unroll") for (int m = 0; m < 4; ++m) _Pragma("unroll") for (int k = 0; k < 2; ++k) dst[m][k] = *(const LAS bf16x8*)(lds + PG8_SA(b, h) + aoff + m * 2048 + k * 1024); } while (0)
; #define PG8_LDB(dst, b, h) do { _Pragma("unroll") for (int n = 0; n < 2; ++n) _Pragma("unroll") for (int k = 0; k < 2; ++k) dst[n][k] = *(const LAS bf16x8*)(lds + bbase[b][h] + n * 2048 + k * 1024); } while (0)
; #define PG8_WAIT_V(n) asm volatile("s_waitcnt vmcnt(" #n ")" ::: "memory")
; #define PG8_WAIT_L(n) asm volatile("s_waitcnt lgkmcnt(" #n ")" ::: "memory")
; #define PG8_BAR __builtin_amdgcn_s_barrier()
; #define PG8_SCHED __builtin_amdgcn_sched_barrier(0)
; template <class Epi>
; __device__ __forceinline__ void gemm_phase(LAS unsigned char* lds, const Gemm g, const StaticOrder& S, const Epi& E) {
;     ...
;         for (int t = 0; t < nt; t += 2) {
;     ...
;             PG8_LDB(B0, 1, 0); PG8_SCHED; PG8_LDA(At, 1, 0); PG8_LDA(At2, 1, 1); PG8_STAGE(PG8_SB(0, 1), b2 + hstepB, voffB);
;             PG8_WAIT_V(8); PG8_WAIT_L(0); PG8_BAR; PG8_MMA2B(0, At, At2, B0); PG8_BAR; PG8_SCHED;
;             PG8_LDB(B0, 1, 1); PG8_STAGE(PG8_SB(1, 0), b3, voffB); PG8_STAGE(PG8_SA(1, 0), a3, voffA); PG8_STAGE(PG8_SA(1, 1), a3 + hstepA, voffA);
;             PG8_WAIT_V(8); PG8_WAIT_L(0); PG8_BAR; PG8_MMA2B(1, At, At2, B0); PG8_BAR; PG8_SCHED;
	s_barrier
	ds_read_b128 v[74:77], v73
	ds_read_b128 v[78:81], v73 offset:1024
	ds_read_b128 v[82:85], v73 offset:2048
	ds_read_b128 v[86:89], v73 offset:3072
	ds_read_b128 v[90:93], v72 offset:32768
	ds_read_b128 v[94:97], v72 offset:33792
	ds_read_b128 v[98:101], v72 offset:34816
	ds_read_b128 v[102:105], v72 offset:35840
	ds_read_b128 v[106:109], v72 offset:36864
	ds_read_b128 v[110:113], v72 offset:37888
	ds_read_b128 v[114:117], v72 offset:38912
	ds_read_b128 v[118:121], v72 offset:39936
	ds_read_b128 v[122:125], v72 offset:49152
	ds_read_b128 v[126:129], v72 offset:50176
	ds_read_b128 v[130:133], v72 offset:51200
	ds_read_b128 v[134:137], v72 offset:52224
	ds_read_b128 v[138:141], v72 offset:53248
	ds_read_b128 v[142:145], v72 offset:54272
	ds_read_b128 v[146:149], v72 offset:55296
	ds_read_b128 v[150:153], v72 offset:56320
	s_add_u32 s82, s82, 0x10000
	s_addc_u32 s83, s83, 0
	s_mov_b32 m0, s53
	s_nop 0
	global_load_lds_dwordx4 v67, s[82:83]
	s_mov_b32 m0, s54
	s_nop 0
	global_load_lds_dwordx4 v69, s[82:83]
	s_waitcnt vmcnt(8)
	s_waitcnt lgkmcnt(0)
	s_barrier
	s_waitcnt lgkmcnt(14)
	v_mfma_f32_16x16x32_bf16 v[60:63], v[74:77], v[90:93], v[60:63]
	v_mfma_f32_16x16x32_bf16 v[56:59], v[82:85], v[90:93], v[56:59]
	s_waitcnt lgkmcnt(13)
	v_mfma_f32_16x16x32_bf16 v[52:55], v[74:77], v[98:101], v[52:55]
	v_mfma_f32_16x16x32_bf16 v[48:51], v[82:85], v[98:101], v[48:51]
	s_waitcnt lgkmcnt(11)
	v_mfma_f32_16x16x32_bf16 v[44:47], v[74:77], v[106:109], v[44:47]
	v_mfma_f32_16x16x32_bf16 v[40:43], v[82:85], v[106:109], v[40:43]
	s_waitcnt lgkmcnt(9)
	v_mfma_f32_16x16x32_bf16 v[36:39], v[74:77], v[114:117], v[36:39]
	v_mfma_f32_16x16x32_bf16 v[32:35], v[82:85], v[114:117], v[32:35]
	s_waitcnt lgkmcnt(7)
	v_mfma_f32_16x16x32_bf16 v[28:31], v[74:77], v[122:125], v[28:31]
	v_mfma_f32_16x16x32_bf16 v[24:27], v[82:85], v[122:125], v[24:27]
	s_waitcnt lgkmcnt(5)
	v_mfma_f32_16x16x32_bf16 v[20:23], v[74:77], v[130:133], v[20:23]
	v_mfma_f32_16x16x32_bf16 v[16:19], v[82:85], v[130:133], v[16:19]
	s_waitcnt lgkmcnt(3)
	v_mfma_f32_16x16x32_bf16 v[12:15], v[74:77], v[138:141], v[12:15]
	v_mfma_f32_16x16x32_bf16 v[8:11], v[82:85], v[138:141], v[8:11]
	s_waitcnt lgkmcnt(1)
	v_mfma_f32_16x16x32_bf16 v[4:7], v[74:77], v[146:149], v[4:7]
	v_mfma_f32_16x16x32_bf16 v[0:3], v[82:85], v[146:149], v[0:3]
	v_mfma_f32_16x16x32_bf16 v[60:63], v[78:81], v[94:97], v[60:63]
	v_mfma_f32_16x16x32_bf16 v[56:59], v[86:89], v[94:97], v[56:59]
	v_mfma_f32_16x16x32_bf16 v[52:55], v[78:81], v[102:105], v[52:55]
	v_mfma_f32_16x16x32_bf16 v[48:51], v[86:89], v[102:105], v[48:51]
	v_mfma_f32_16x16x32_bf16 v[44:47], v[78:81], v[110:113], v[44:47]
	v_mfma_f32_16x16x32_bf16 v[40:43], v[86:89], v[110:113], v[40:43]
	v_mfma_f32_16x16x32_bf16 v[36:39], v[78:81], v[118:121], v[36:39]
	v_mfma_f32_16x16x32_bf16 v[32:35], v[86:89], v[118:121], v[32:35]
	v_mfma_f32_16x16x32_bf16 v[28:31], v[78:81], v[126:129], v[28:31]
	v_mfma_f32_16x16x32_bf16 v[24:27], v[86:89], v[126:129], v[24:27]
	v_mfma_f32_16x16x32_bf16 v[20:23], v[78:81], v[134:137], v[20:23]
	v_mfma_f32_16x16x32_bf16 v[16:19], v[86:89], v[134:137], v[16:19]
	v_mfma_f32_16x16x32_bf16 v[12:15], v[78:81], v[142:145], v[12:15]
	v_mfma_f32_16x16x32_bf16 v[8:11], v[86:89], v[142:145], v[8:11]
	s_waitcnt lgkmcnt(0)
	v_mfma_f32_16x16x32_bf16 v[4:7], v[78:81], v[150:153], v[4:7]
	v_mfma_f32_16x16x32_bf16 v[0:3], v[86:89], v[150:153], v[0:3]
	s_barrier
	s_mov_b32 m0, s56
	s_nop 0
	global_load_lds_dwordx4 v67, s[80:81]
	s_mov_b32 m0, s57
	s_nop 0
	global_load_lds_dwordx4 v69, s[80:81]
	s_mov_b32 m0, s58
	s_nop 0
	global_load_lds_dwordx4 v66, s[42:43]
	s_mov_b32 m0, s59
	s_nop 0
	global_load_lds_dwordx4 v68, s[42:43]
	s_add_u32 s38, s38, 0x18080
	s_addc_u32 s39, s39, 0
	s_mov_b32 m0, s60
	s_nop 0
	global_load_lds_dwordx4 v66, s[38:39]
	s_mov_b32 m0, s61
	s_nop 0
	global_load_lds_dwordx4 v68, s[38:39]
	s_waitcnt vmcnt(8)
	s_waitcnt lgkmcnt(0)
	s_barrier
	s_add_u32 s67, s67, 0x100
	s_addc_u32 s68, s68, 0
	s_add_u32 s69, s69, 0x100
	s_addc_u32 s84, s84, 0
	s_cmp_ge_i32 s85, s55
	s_mov_b32 s38, s85
	s_barrier
	s_cbranch_scc0 .LBB0_662

; #define PG8_STAGE(bufoff, gbase, voff) do { _Pragma("unroll") for (int _i = 0; _i < 2; ++_i) { \
;         const unsigned _m0 = ldsu + (unsigned)(bufoff) + ldsw + (unsigned)(_i * 8192); \
;         asm volatile("s_mov_b32 m0, %2\n\ts_nop 0\n\tglobal_load_lds_dwordx4 %0, %1" :: "v"((voff)[_i]), "s"((const char*)(gbase)), "s"(_m0) : "memory"); } } while (0)
; #define PG8_LDA(dst, b, h) do { _Pragma("unroll") for (int m = 0; m < 4; ++m) _Pragma("unroll") for (int k = 0; k < 2; ++k) dst[m][k] = *(const LAS bf16x8*)(lds + PG8_SA(b, h) + aoff + m * 2048 + k * 1024); } while (0)
; #define PG8_LDB(dst, b, h) do { _Pragma("unroll") for (int n = 0; n < 2; ++n) _Pragma("unroll") for (int k = 0; k < 2; ++k) dst[n][k] = *(const LAS bf16x8*)(lds + bbase[b][h] + n * 2048 + k * 1024); } while (0)
; #define PG8_WAIT_V(n) asm volatile("s_waitcnt vmcnt(" #n ")" ::: "memory")
; #define PG8_WAIT_L(n) asm volatile("s_waitcnt lgkmcnt(" #n ")" ::: "memory")
; #define PG8_BAR __builtin_amdgcn_s_barrier()
; #define PG8_SCHED __builtin_amdgcn_sched_barrier(0)
; template <class Epi>
; __device__ __forceinline__ void gemm_phase(LAS unsigned char* lds, const Gemm g, const StaticOrder& S, const Epi& E) {
;     ...
;             const char* a2 = last ? nA : cA + (size_t)(t + 2) * kstep; const char* b2 = last ? nB : cB + (size_t)(t + 2) * kstep;
;             const char* a3 = a2 + kstep; const char* b3 = b2 + kstep;
;             const char* b1 = cB + (size_t)(t + 1) * kstep;
;             PG8_LDB(B0, 0, 0); PG8_SCHED; PG8_LDA(At, 0, 0); PG8_LDA(At2, 0, 1); PG8_STAGE(PG8_SB(1, 1), b1 + hstepB, voffB);
;             PG8_WAIT_V(8); PG8_WAIT_L(0); PG8_BAR; PG8_MMA2B(0, At, At2, B0); PG8_BAR; PG8_SCHED;
;             PG8_LDB(B0, 0, 1); PG8_STAGE(PG8_SB(0, 0), b2, voffB); PG8_STAGE(PG8_SA(0, 0), a2, voffA); PG8_STAGE(PG8_SA(0, 1), a2 + hstepA, voffA);
;             PG8_WAIT_V(8); PG8_WAIT_L(0); PG8_BAR; PG8_MMA2B(1, At, At2, B0); PG8_BAR; PG8_SCHED;
.LBB0_797:
	s_add_i32 s52, s4, 2
	s_add_u32 s38, s1, 0x80
	ds_read_b128 v[128:131], v153
	ds_read_b128 v[132:135], v153 offset:1024
	ds_read_b128 v[142:145], v153 offset:2048
	ds_read_b128 v[178:181], v153 offset:3072
	s_addc_u32 s39, s43, 0
	s_cmp_eq_u32 s47, s4
	s_cselect_b32 s4, s16, s50
	s_cselect_b32 s5, s17, s51
	s_cselect_b32 s82, s10, s38
	s_cselect_b32 s83, s11, s39
	s_add_u32 s38, s4, 0x80
	s_addc_u32 s39, s5, 0
	s_add_u32 s80, s82, 0x80
	s_addc_u32 s81, s83, 0
	ds_read_b128 v[182:185], v154
	ds_read_b128 v[186:189], v154 offset:1024
	ds_read_b128 v[190:193], v154 offset:2048
	ds_read_b128 v[194:197], v154 offset:3072
	ds_read_b128 v[198:201], v154 offset:4096
	ds_read_b128 v[202:205], v154 offset:5120
	ds_read_b128 v[214:217], v154 offset:6144
	ds_read_b128 v[218:221], v154 offset:7168
	ds_read_b128 v[222:225], v154 offset:16384
	ds_read_b128 v[226:229], v154 offset:17408
	ds_read_b128 v[230:233], v154 offset:18432
	ds_read_b128 v[234:237], v154 offset:19456
	ds_read_b128 v[238:241], v154 offset:20480
	ds_read_b128 v[242:245], v154 offset:21504
	ds_read_b128 v[246:249], v154 offset:22528
	ds_read_b128 v[166:169], v154 offset:23552
	s_add_u32 s54, s1, 0x18000
	s_addc_u32 s55, s43, 0
	s_mov_b32 m0, s87
	s_nop 0
	global_load_lds_dwordx4 v147, s[54:55]
	s_mov_b32 m0, s28
	s_nop 0
	global_load_lds_dwordx4 v149, s[54:55]
	s_waitcnt vmcnt(8)
	s_waitcnt lgkmcnt(0)
	s_barrier
	s_waitcnt lgkmcnt(14)
	v_mfma_f32_16x16x32_bf16 v[124:127], v[128:131], v[182:185], v[124:127]
	v_mfma_f32_16x16x32_bf16 v[120:123], v[142:145], v[182:185], v[120:123]
	s_waitcnt lgkmcnt(13)
	v_mfma_f32_16x16x32_bf16 v[108:111], v[128:131], v[190:193], v[108:111]
	v_mfma_f32_16x16x32_bf16 v[104:107], v[142:145], v[190:193], v[104:107]
	s_waitcnt lgkmcnt(11)
	v_mfma_f32_16x16x32_bf16 v[92:95], v[128:131], v[198:201], v[92:95]
	v_mfma_f32_16x16x32_bf16 v[88:91], v[142:145], v[198:201], v[88:91]
	s_waitcnt lgkmcnt(9)
	v_mfma_f32_16x16x32_bf16 v[76:79], v[128:131], v[214:217], v[76:79]
	v_mfma_f32_16x16x32_bf16 v[72:75], v[142:145], v[214:217], v[72:75]
	s_waitcnt lgkmcnt(7)
	v_mfma_f32_16x16x32_bf16 v[60:63], v[128:131], v[222:225], v[60:63]
	v_mfma_f32_16x16x32_bf16 v[56:59], v[142:145], v[222:225], v[56:59]
	s_waitcnt lgkmcnt(5)
	v_mfma_f32_16x16x32_bf16 v[44:47], v[128:131], v[230:233], v[44:47]
	v_mfma_f32_16x16x32_bf16 v[40:43], v[142:145], v[230:233], v[40:43]
	s_waitcnt lgkmcnt(3)
	v_mfma_f32_16x16x32_bf16 v[28:31], v[128:131], v[238:241], v[28:31]
	v_mfma_f32_16x16x32_bf16 v[24:27], v[142:145], v[238:241], v[24:27]
	s_waitcnt lgkmcnt(1)
	v_mfma_f32_16x16x32_bf16 v[12:15], v[128:131], v[246:249], v[12:15]
	v_mfma_f32_16x16x32_bf16 v[8:11], v[142:145], v[246:249], v[8:11]
	v_mfma_f32_16x16x32_bf16 v[124:127], v[132:135], v[186:189], v[124:127]
	v_mfma_f32_16x16x32_bf16 v[120:123], v[178:181], v[186:189], v[120:123]
	v_mfma_f32_16x16x32_bf16 v[108:111], v[132:135], v[194:197], v[108:111]
	v_mfma_f32_16x16x32_bf16 v[104:107], v[178:181], v[194:197], v[104:107]
	v_mfma_f32_16x16x32_bf16 v[92:95], v[132:135], v[202:205], v[92:95]
	v_mfma_f32_16x16x32_bf16 v[88:91], v[178:181], v[202:205], v[88:91]
	v_mfma_f32_16x16x32_bf16 v[76:79], v[132:135], v[218:221], v[76:79]
	v_mfma_f32_16x16x32_bf16 v[72:75], v[178:181], v[218:221], v[72:75]
	v_mfma_f32_16x16x32_bf16 v[60:63], v[132:135], v[226:229], v[60:63]
	v_mfma_f32_16x16x32_bf16 v[56:59], v[178:181], v[226:229], v[56:59]
	v_mfma_f32_16x16x32_bf16 v[44:47], v[132:135], v[234:237], v[44:47]
	v_mfma_f32_16x16x32_bf16 v[40:43], v[178:181], v[234:237], v[40:43]
	v_mfma_f32_16x16x32_bf16 v[28:31], v[132:135], v[242:245], v[28:31]
	v_mfma_f32_16x16x32_bf16 v[24:27], v[178:181], v[242:245], v[24:27]
	s_waitcnt lgkmcnt(0)
	v_mfma_f32_16x16x32_bf16 v[12:15], v[132:135], v[166:169], v[12:15]
	v_mfma_f32_16x16x32_bf16 v[8:11], v[178:181], v[166:169], v[8:11]
	s_barrier
	ds_read_b128 v[128:131], v155
	ds_read_b128 v[132:135], v155 offset:1024
	ds_read_b128 v[142:145], v155 offset:2048
	ds_read_b128 v[178:181], v155 offset:3072
	s_mov_b32 m0, s90
	s_nop 0
	global_load_lds_dwordx4 v147, s[82:83]
	s_mov_b32 m0, s91
	s_nop 0
	global_load_lds_dwordx4 v149, s[82:83]
	s_mov_b32 m0, s85
	s_nop 0
	global_load_lds_dwordx4 v146, s[4:5]
	s_mov_b32 m0, s95
	s_nop 0
	global_load_lds_dwordx4 v148, s[4:5]
	s_add_u32 s54, s4, 0x18000
	s_addc_u32 s55, s5, 0
	s_mov_b32 m0, s96
	s_nop 0
	global_load_lds_dwordx4 v146, s[54:55]
	s_mov_b32 m0, s97
	s_nop 0
	global_load_lds_dwordx4 v148, s[54:55]
	s_waitcnt vmcnt(8)
	s_waitcnt lgkmcnt(0)
	s_barrier
; #define PG8_STAGE(bufoff, gbase, voff) do { _Pragma("unroll") for (int _i = 0; _i < 2; ++_i) { \
;         const unsigned _m0 = ldsu + (unsigned)(bufoff) + ldsw + (unsigned)(_i * 8192); \
;         asm volatile("s_mov_b32 m0, %2\n\ts_nop 0\n\tglobal_load_lds_dwordx4 %0, %1" :: "v"((voff)[_i]), "s"((const char*)(gbase)), "s"(_m0) : "memory"); } } while (0)
; #define PG8_LDA(dst, b, h) do { _Pragma("unroll") for (int m = 0; m < 4; ++m) _Pragma("unroll") for (int k = 0; k < 2; ++k) dst[m][k] = *(const LAS bf16x8*)(lds + PG8_SA(b, h) + aoff + m * 2048 + k * 1024); } while (0)
; #define PG8_LDB(dst, b, h) do { _Pragma("unroll") for (int n = 0; n < 2; ++n) _Pragma("unroll") for (int k = 0; k < 2; ++k) dst[n][k] = *(const LAS bf16x8*)(lds + bbase[b][h] + n * 2048 + k * 1024); } while (0)
; #define PG8_WAIT_V(n) asm volatile("s_waitcnt vmcnt(" #n ")" ::: "memory")
; #define PG8_WAIT_L(n) asm volatile("s_waitcnt lgkmcnt(" #n ")" ::: "memory")
; #define PG8_BAR __builtin_amdgcn_s_barrier()
; #define PG8_SCHED __builtin_amdgcn_sched_barrier(0)
; template <class Epi>
; __device__ __forceinline__ void gemm_phase(LAS unsigned char* lds, const Gemm g, const StaticOrder& S, const Epi& E) {
;     ...
;             PG8_WAIT_V(8); PG8_WAIT_L(0); PG8_BAR; PG8_MMA2B(1, At, At2, B0); PG8_BAR; PG8_SCHED;
;             PG8_LDB(B0, 1, 0); PG8_SCHED; PG8_LDA(At, 1, 0); PG8_LDA(At2, 1, 1); PG8_STAGE(PG8_SB(0, 1), b2 + hstepB, voffB);
	s_waitcnt lgkmcnt(3)
	v_mfma_f32_16x16x32_bf16 v[116:119], v[128:131], v[182:185], v[116:119]
	s_waitcnt lgkmcnt(1)
	v_mfma_f32_16x16x32_bf16 v[112:115], v[142:145], v[182:185], v[112:115]
	v_mfma_f32_16x16x32_bf16 v[100:103], v[128:131], v[190:193], v[100:103]
	v_mfma_f32_16x16x32_bf16 v[96:99], v[142:145], v[190:193], v[96:99]
	v_mfma_f32_16x16x32_bf16 v[84:87], v[128:131], v[198:201], v[84:87]
	v_mfma_f32_16x16x32_bf16 v[80:83], v[142:145], v[198:201], v[80:83]
	v_mfma_f32_16x16x32_bf16 v[68:71], v[128:131], v[214:217], v[68:71]
	v_mfma_f32_16x16x32_bf16 v[64:67], v[142:145], v[214:217], v[64:67]
	v_mfma_f32_16x16x32_bf16 v[52:55], v[128:131], v[222:225], v[52:55]
	v_mfma_f32_16x16x32_bf16 v[48:51], v[142:145], v[222:225], v[48:51]
	v_mfma_f32_16x16x32_bf16 v[36:39], v[128:131], v[230:233], v[36:39]
	v_mfma_f32_16x16x32_bf16 v[32:35], v[142:145], v[230:233], v[32:35]
	v_mfma_f32_16x16x32_bf16 v[20:23], v[128:131], v[238:241], v[20:23]
	v_mfma_f32_16x16x32_bf16 v[16:19], v[142:145], v[238:241], v[16:19]
	v_mfma_f32_16x16x32_bf16 v[4:7], v[128:131], v[246:249], v[4:7]
	v_mfma_f32_16x16x32_bf16 v[0:3], v[142:145], v[246:249], v[0:3]
	v_mfma_f32_16x16x32_bf16 v[116:119], v[132:135], v[186:189], v[116:119]
	s_waitcnt lgkmcnt(0)
	v_mfma_f32_16x16x32_bf16 v[112:115], v[178:181], v[186:189], v[112:115]
	v_mfma_f32_16x16x32_bf16 v[100:103], v[132:135], v[194:197], v[100:103]
	v_mfma_f32_16x16x32_bf16 v[96:99], v[178:181], v[194:197], v[96:99]
	v_mfma_f32_16x16x32_bf16 v[84:87], v[132:135], v[202:205], v[84:87]
	v_mfma_f32_16x16x32_bf16 v[80:83], v[178:181], v[202:205], v[80:83]
	v_mfma_f32_16x16x32_bf16 v[68:71], v[132:135], v[218:221], v[68:71]
	v_mfma_f32_16x16x32_bf16 v[64:67], v[178:181], v[218:221], v[64:67]
	v_mfma_f32_16x16x32_bf16 v[52:55], v[132:135], v[226:229], v[52:55]
	v_mfma_f32_16x16x32_bf16 v[48:51], v[178:181], v[226:229], v[48:51]
	v_mfma_f32_16x16x32_bf16 v[36:39], v[132:135], v[234:237], v[36:39]
	v_mfma_f32_16x16x32_bf16 v[32:35], v[178:181], v[234:237], v[32:35]
	v_mfma_f32_16x16x32_bf16 v[20:23], v[132:135], v[242:245], v[20:23]
	v_mfma_f32_16x16x32_bf16 v[16:19], v[178:181], v[242:245], v[16:19]
	v_mfma_f32_16x16x32_bf16 v[4:7], v[132:135], v[166:169], v[4:7]
	v_mfma_f32_16x16x32_bf16 v[0:3], v[178:181], v[166:169], v[0:3]
	s_barrier
	ds_read_b128 v[128:131], v156
	ds_read_b128 v[132:135], v156 offset:1024
	ds_read_b128 v[142:145], v156 offset:2048
	ds_read_b128 v[166:169], v156 offset:3072
	ds_read_b128 v[178:181], v154 offset:32768
	ds_read_b128 v[182:185], v154 offset:33792
	ds_read_b128 v[186:189], v154 offset:34816
	ds_read_b128 v[190:193], v154 offset:35840
	ds_read_b128 v[194:197], v154 offset:36864
	ds_read_b128 v[198:201], v154 offset:37888
	ds_read_b128 v[202:205], v154 offset:38912
	ds_read_b128 v[214:217], v154 offset:39936
	ds_read_b128 v[218:221], v154 offset:49152
	ds_read_b128 v[222:225], v154 offset:50176
	ds_read_b128 v[226:229], v154 offset:51200
	ds_read_b128 v[230:233], v154 offset:52224
	ds_read_b128 v[234:237], v154 offset:53248
	ds_read_b128 v[238:241], v154 offset:54272
	ds_read_b128 v[242:245], v154 offset:55296
	ds_read_b128 v[246:249], v154 offset:56320
	s_add_u32 s54, s82, 0x18000
	s_addc_u32 s55, s83, 0
	s_mov_b32 m0, s6
	s_nop 0
	global_load_lds_dwordx4 v147, s[54:55]
	s_mov_b32 m0, s7
	s_nop 0
	global_load_lds_dwordx4 v149, s[54:55]
	s_waitcnt vmcnt(8)
	s_waitcnt lgkmcnt(0)
	s_barrier
; #define PG8_STAGE(bufoff, gbase, voff) do { _Pragma("unroll") for (int _i = 0; _i < 2; ++_i) { \
;         const unsigned _m0 = ldsu + (unsigned)(bufoff) + ldsw + (unsigned)(_i * 8192); \
;         asm volatile("s_mov_b32 m0, %2\n\ts_nop 0\n\tglobal_load_lds_dwordx4 %0, %1" :: "v"((voff)[_i]), "s"((const char*)(gbase)), "s"(_m0) : "memory"); } } while (0)
; #define PG8_LDB(dst, b, h) do { _Pragma("unroll") for (int n = 0; n < 2; ++n) _Pragma("unroll") for (int k = 0; k < 2; ++k) dst[n][k] = *(const LAS bf16x8*)(lds + bbase[b][h] + n * 2048 + k * 1024); } while (0)
; #define PG8_WAIT_V(n) asm volatile("s_waitcnt vmcnt(" #n ")" ::: "memory")
; #define PG8_WAIT_L(n) asm volatile("s_waitcnt lgkmcnt(" #n ")" ::: "memory")
; #define PG8_BAR __builtin_amdgcn_s_barrier()
; #define PG8_SCHED __builtin_amdgcn_sched_barrier(0)
; template <class Epi>
; __device__ __forceinline__ void gemm_phase(LAS unsigned char* lds, const Gemm g, const StaticOrder& S, const Epi& E) {
;     ...
;         for (int t = 0; t < nt; t += 2) {
;             const bool last = (t == nt - 2);
;             const char* a2 = last ? nA : cA + (size_t)(t + 2) * kstep; const char* b2 = last ? nB : cB + (size_t)(t + 2) * kstep;
;     ...
;             PG8_WAIT_V(8); PG8_WAIT_L(0); PG8_BAR; PG8_MMA2B(0, At, At2, B0); PG8_BAR; PG8_SCHED;
;             PG8_LDB(B0, 1, 1); PG8_STAGE(PG8_SB(1, 0), b3, voffB); PG8_STAGE(PG8_SA(1, 0), a3, voffA); PG8_STAGE(PG8_SA(1, 1), a3 + hstepA, voffA);
;             PG8_WAIT_V(8); PG8_WAIT_L(0); PG8_BAR; PG8_MMA2B(1, At, At2, B0); PG8_BAR; PG8_SCHED;
	s_waitcnt lgkmcnt(14)
	v_mfma_f32_16x16x32_bf16 v[124:127], v[128:131], v[178:181], v[124:127]
	v_mfma_f32_16x16x32_bf16 v[120:123], v[142:145], v[178:181], v[120:123]
	s_waitcnt lgkmcnt(13)
	v_mfma_f32_16x16x32_bf16 v[108:111], v[128:131], v[186:189], v[108:111]
	v_mfma_f32_16x16x32_bf16 v[104:107], v[142:145], v[186:189], v[104:107]
	s_waitcnt lgkmcnt(11)
	v_mfma_f32_16x16x32_bf16 v[92:95], v[128:131], v[194:197], v[92:95]
	v_mfma_f32_16x16x32_bf16 v[88:91], v[142:145], v[194:197], v[88:91]
	s_waitcnt lgkmcnt(9)
	v_mfma_f32_16x16x32_bf16 v[76:79], v[128:131], v[202:205], v[76:79]
	v_mfma_f32_16x16x32_bf16 v[72:75], v[142:145], v[202:205], v[72:75]
	s_waitcnt lgkmcnt(7)
	v_mfma_f32_16x16x32_bf16 v[60:63], v[128:131], v[218:221], v[60:63]
	v_mfma_f32_16x16x32_bf16 v[56:59], v[142:145], v[218:221], v[56:59]
	s_waitcnt lgkmcnt(5)
	v_mfma_f32_16x16x32_bf16 v[44:47], v[128:131], v[226:229], v[44:47]
	v_mfma_f32_16x16x32_bf16 v[40:43], v[142:145], v[226:229], v[40:43]
	s_waitcnt lgkmcnt(3)
	v_mfma_f32_16x16x32_bf16 v[28:31], v[128:131], v[234:237], v[28:31]
	v_mfma_f32_16x16x32_bf16 v[24:27], v[142:145], v[234:237], v[24:27]
	s_waitcnt lgkmcnt(1)
	v_mfma_f32_16x16x32_bf16 v[12:15], v[128:131], v[242:245], v[12:15]
	v_mfma_f32_16x16x32_bf16 v[8:11], v[142:145], v[242:245], v[8:11]
	v_mfma_f32_16x16x32_bf16 v[124:127], v[132:135], v[182:185], v[124:127]
	v_mfma_f32_16x16x32_bf16 v[120:123], v[166:169], v[182:185], v[120:123]
	v_mfma_f32_16x16x32_bf16 v[108:111], v[132:135], v[190:193], v[108:111]
	v_mfma_f32_16x16x32_bf16 v[104:107], v[166:169], v[190:193], v[104:107]
	v_mfma_f32_16x16x32_bf16 v[92:95], v[132:135], v[198:201], v[92:95]
	v_mfma_f32_16x16x32_bf16 v[88:91], v[166:169], v[198:201], v[88:91]
	v_mfma_f32_16x16x32_bf16 v[76:79], v[132:135], v[214:217], v[76:79]
	v_mfma_f32_16x16x32_bf16 v[72:75], v[166:169], v[214:217], v[72:75]
	v_mfma_f32_16x16x32_bf16 v[60:63], v[132:135], v[222:225], v[60:63]
	v_mfma_f32_16x16x32_bf16 v[56:59], v[166:169], v[222:225], v[56:59]
	v_mfma_f32_16x16x32_bf16 v[44:47], v[132:135], v[230:233], v[44:47]
	v_mfma_f32_16x16x32_bf16 v[40:43], v[166:169], v[230:233], v[40:43]
	v_mfma_f32_16x16x32_bf16 v[28:31], v[132:135], v[238:241], v[28:31]
	v_mfma_f32_16x16x32_bf16 v[24:27], v[166:169], v[238:241], v[24:27]
	s_waitcnt lgkmcnt(0)
	v_mfma_f32_16x16x32_bf16 v[12:15], v[132:135], v[246:249], v[12:15]
	v_mfma_f32_16x16x32_bf16 v[8:11], v[166:169], v[246:249], v[8:11]
	s_barrier
	ds_read_b128 v[128:131], v157
	ds_read_b128 v[132:135], v157 offset:1024
	ds_read_b128 v[142:145], v157 offset:2048
	ds_read_b128 v[166:169], v157 offset:3072
	s_mov_b32 m0, s2
	s_nop 0
	global_load_lds_dwordx4 v147, s[80:81]
	s_mov_b32 m0, s3
	s_nop 0
	global_load_lds_dwordx4 v149, s[80:81]
	s_mov_b32 m0, s88
	s_nop 0
	global_load_lds_dwordx4 v146, s[38:39]
	s_mov_b32 m0, s89
	s_nop 0
	global_load_lds_dwordx4 v148, s[38:39]
	s_add_u32 s4, s4, 0x18080
	s_addc_u32 s5, s5, 0
	s_mov_b32 m0, s37
	s_nop 0
	global_load_lds_dwordx4 v146, s[4:5]
	s_mov_b32 m0, s84
	s_nop 0
	global_load_lds_dwordx4 v148, s[4:5]
	s_waitcnt vmcnt(8)
	s_waitcnt lgkmcnt(0)
	s_barrier
	s_waitcnt lgkmcnt(3)
	v_mfma_f32_16x16x32_bf16 v[116:119], v[128:131], v[178:181], v[116:119]
	s_waitcnt lgkmcnt(1)
	v_mfma_f32_16x16x32_bf16 v[112:115], v[142:145], v[178:181], v[112:115]
	v_mfma_f32_16x16x32_bf16 v[100:103], v[128:131], v[186:189], v[100:103]
	v_mfma_f32_16x16x32_bf16 v[96:99], v[142:145], v[186:189], v[96:99]
	v_mfma_f32_16x16x32_bf16 v[84:87], v[128:131], v[194:197], v[84:87]
	v_mfma_f32_16x16x32_bf16 v[80:83], v[142:145], v[194:197], v[80:83]
	v_mfma_f32_16x16x32_bf16 v[68:71], v[128:131], v[202:205], v[68:71]
	v_mfma_f32_16x16x32_bf16 v[64:67], v[142:145], v[202:205], v[64:67]
	v_mfma_f32_16x16x32_bf16 v[52:55], v[128:131], v[218:221], v[52:55]
	v_mfma_f32_16x16x32_bf16 v[48:51], v[142:145], v[218:221], v[48:51]
	v_mfma_f32_16x16x32_bf16 v[36:39], v[128:131], v[226:229], v[36:39]
	v_mfma_f32_16x16x32_bf16 v[32:35], v[142:145], v[226:229], v[32:35]
	v_mfma_f32_16x16x32_bf16 v[20:23], v[128:131], v[234:237], v[20:23]
	v_mfma_f32_16x16x32_bf16 v[16:19], v[142:145], v[234:237], v[16:19]
	v_mfma_f32_16x16x32_bf16 v[4:7], v[128:131], v[242:245], v[4:7]
	v_mfma_f32_16x16x32_bf16 v[0:3], v[142:145], v[242:245], v[0:3]
	v_mfma_f32_16x16x32_bf16 v[116:119], v[132:135], v[182:185], v[116:119]
	s_waitcnt lgkmcnt(0)
	v_mfma_f32_16x16x32_bf16 v[112:115], v[166:169], v[182:185], v[112:115]
	v_mfma_f32_16x16x32_bf16 v[100:103], v[132:135], v[190:193], v[100:103]
	v_mfma_f32_16x16x32_bf16 v[96:99], v[166:169], v[190:193], v[96:99]
	v_mfma_f32_16x16x32_bf16 v[84:87], v[132:135], v[198:201], v[84:87]
	v_mfma_f32_16x16x32_bf16 v[80:83], v[166:169], v[198:201], v[80:83]
	v_mfma_f32_16x16x32_bf16 v[68:71], v[132:135], v[214:217], v[68:71]
	v_mfma_f32_16x16x32_bf16 v[64:67], v[166:169], v[214:217], v[64:67]
	v_mfma_f32_16x16x32_bf16 v[52:55], v[132:135], v[222:225], v[52:55]
	v_mfma_f32_16x16x32_bf16 v[48:51], v[166:169], v[222:225], v[48:51]
	v_mfma_f32_16x16x32_bf16 v[36:39], v[132:135], v[230:233], v[36:39]
	v_mfma_f32_16x16x32_bf16 v[32:35], v[166:169], v[230:233], v[32:35]
	v_mfma_f32_16x16x32_bf16 v[20:23], v[132:135], v[238:241], v[20:23]
	v_mfma_f32_16x16x32_bf16 v[16:19], v[166:169], v[238:241], v[16:19]
	v_mfma_f32_16x16x32_bf16 v[4:7], v[132:135], v[246:249], v[4:7]
	v_mfma_f32_16x16x32_bf16 v[0:3], v[166:169], v[246:249], v[0:3]
	s_add_u32 s1, s1, 0x100
	s_addc_u32 s43, s43, 0
	s_add_u32 s50, s50, 0x100
	s_addc_u32 s51, s51, 0
	s_cmp_ge_i32 s52, s86
	s_mov_b32 s4, s52
	s_barrier
	s_cbranch_scc0 .LBB0_797
	v_readlane_b32 s52, v252, 7
	v_readlane_b32 s54, v254, 61
	v_readlane_b32 s53, v252, 8
	v_readlane_b32 s55, v254, 62
	v_mov_b32_e32 v246, v141

; #define PG8_STAGE(bufoff, gbase, voff) do { _Pragma("unroll") for (int _i = 0; _i < 2; ++_i) { \
;         const unsigned _m0 = ldsu + (unsigned)(bufoff) + ldsw + (unsigned)(_i * 8192); \
;         asm volatile("s_mov_b32 m0, %2\n\ts_nop 0\n\tglobal_load_lds_dwordx4 %0, %1" :: "v"((voff)[_i]), "s"((const char*)(gbase)), "s"(_m0) : "memory"); } } while (0)
; #define PG8_LDA(dst, b, h) do { _Pragma("unroll") for (int m = 0; m < 4; ++m) _Pragma("unroll") for (int k = 0; k < 2; ++k) dst[m][k] = *(const LAS bf16x8*)(lds + PG8_SA(b, h) + aoff + m * 2048 + k * 1024); } while (0)
; #define PG8_LDB(dst, b, h) do { _Pragma("unroll") for (int n = 0; n < 2; ++n) _Pragma("unroll") for (int k = 0; k < 2; ++k) dst[n][k] = *(const LAS bf16x8*)(lds + bbase[b][h] + n * 2048 + k * 1024); } while (0)
; #define PG8_WAIT_V(n) asm volatile("s_waitcnt vmcnt(" #n ")" ::: "memory")
; #define PG8_WAIT_L(n) asm volatile("s_waitcnt lgkmcnt(" #n ")" ::: "memory")
; #define PG8_BAR __builtin_amdgcn_s_barrier()
; #define PG8_SCHED __builtin_amdgcn_sched_barrier(0)
; template <class Epi>
; __device__ __forceinline__ void gemm_phase(LAS unsigned char* lds, const Gemm g, const StaticOrder& S, const Epi& E) {
;     ...
;             const char* a2 = last ? nA : cA + (size_t)(t + 2) * kstep; const char* b2 = last ? nB : cB + (size_t)(t + 2) * kstep;
;             const char* a3 = a2 + kstep; const char* b3 = b2 + kstep;
;             const char* b1 = cB + (size_t)(t + 1) * kstep;
;             PG8_LDB(B0, 0, 0); PG8_SCHED; PG8_LDA(At, 0, 0); PG8_LDA(At2, 0, 1); PG8_STAGE(PG8_SB(1, 1), b1 + hstepB, voffB);
;             PG8_WAIT_V(8); PG8_WAIT_L(0); PG8_BAR; PG8_MMA2B(0, At, At2, B0); PG8_BAR; PG8_SCHED;
;             PG8_LDB(B0, 0, 1); PG8_STAGE(PG8_SB(0, 0), b2, voffB); PG8_STAGE(PG8_SA(0, 0), a2, voffA); PG8_STAGE(PG8_SA(0, 1), a2 + hstepA, voffA);
;             PG8_WAIT_V(8); PG8_WAIT_L(0); PG8_BAR; PG8_MMA2B(1, At, At2, B0); PG8_BAR; PG8_SCHED;
.LBB0_870:
	ds_read_b128 v[128:131], v140
	ds_read_b128 v[146:149], v140 offset:1024
	ds_read_b128 v[150:153], v140 offset:2048
	ds_read_b128 v[154:157], v140 offset:3072
	s_add_u32 s38, s16, 0x100
	s_addc_u32 s39, s17, 0
	s_cmp_eq_u32 s68, 4
	s_cselect_b32 s42, s65, s67
	s_cselect_b32 s43, s11, s84
	s_cselect_b32 s82, s66, s38
	s_cselect_b32 s83, s9, s39
	s_add_u32 s80, s42, 0x80
	s_addc_u32 s81, s43, 0
	ds_read_b128 v[166:169], v141
	ds_read_b128 v[178:181], v141 offset:1024
	ds_read_b128 v[182:185], v141 offset:2048
	ds_read_b128 v[186:189], v141 offset:3072
	ds_read_b128 v[190:193], v141 offset:4096
	ds_read_b128 v[194:197], v141 offset:5120
	ds_read_b128 v[198:201], v141 offset:6144
	ds_read_b128 v[202:205], v141 offset:7168
	ds_read_b128 v[214:217], v141 offset:16384
	ds_read_b128 v[218:221], v141 offset:17408
	ds_read_b128 v[222:225], v141 offset:18432
	ds_read_b128 v[226:229], v141 offset:19456
	ds_read_b128 v[230:233], v141 offset:20480
	ds_read_b128 v[234:237], v141 offset:21504
	ds_read_b128 v[238:241], v141 offset:22528
	ds_read_b128 v[242:245], v141 offset:23552
	s_add_u32 s16, s16, 0x20080
	s_addc_u32 s17, s17, 0
	s_mov_b32 m0, s60
	s_nop 0
	global_load_lds_dwordx4 v135, s[16:17]
	s_mov_b32 m0, s61
	s_nop 0
	global_load_lds_dwordx4 v137, s[16:17]
	s_waitcnt vmcnt(8)
	s_waitcnt lgkmcnt(0)
	s_barrier
	s_waitcnt lgkmcnt(14)
	v_mfma_f32_16x16x32_bf16 v[124:127], v[128:131], v[166:169], v[124:127]
	v_mfma_f32_16x16x32_bf16 v[120:123], v[150:153], v[166:169], v[120:123]
	s_waitcnt lgkmcnt(13)
	v_mfma_f32_16x16x32_bf16 v[108:111], v[128:131], v[182:185], v[108:111]
	v_mfma_f32_16x16x32_bf16 v[104:107], v[150:153], v[182:185], v[104:107]
	s_waitcnt lgkmcnt(11)
	v_mfma_f32_16x16x32_bf16 v[92:95], v[128:131], v[190:193], v[92:95]
	v_mfma_f32_16x16x32_bf16 v[88:91], v[150:153], v[190:193], v[88:91]
	s_waitcnt lgkmcnt(9)
	v_mfma_f32_16x16x32_bf16 v[76:79], v[128:131], v[198:201], v[76:79]
	v_mfma_f32_16x16x32_bf16 v[72:75], v[150:153], v[198:201], v[72:75]
	s_waitcnt lgkmcnt(7)
	v_mfma_f32_16x16x32_bf16 v[60:63], v[128:131], v[214:217], v[60:63]
	v_mfma_f32_16x16x32_bf16 v[56:59], v[150:153], v[214:217], v[56:59]
	s_waitcnt lgkmcnt(5)
	v_mfma_f32_16x16x32_bf16 v[44:47], v[128:131], v[222:225], v[44:47]
	v_mfma_f32_16x16x32_bf16 v[40:43], v[150:153], v[222:225], v[40:43]
	s_waitcnt lgkmcnt(3)
	v_mfma_f32_16x16x32_bf16 v[28:31], v[128:131], v[230:233], v[28:31]
	v_mfma_f32_16x16x32_bf16 v[24:27], v[150:153], v[230:233], v[24:27]
	s_waitcnt lgkmcnt(1)
	v_mfma_f32_16x16x32_bf16 v[12:15], v[128:131], v[238:241], v[12:15]
	v_mfma_f32_16x16x32_bf16 v[8:11], v[150:153], v[238:241], v[8:11]
	v_mfma_f32_16x16x32_bf16 v[124:127], v[146:149], v[178:181], v[124:127]
	v_mfma_f32_16x16x32_bf16 v[120:123], v[154:157], v[178:181], v[120:123]
	v_mfma_f32_16x16x32_bf16 v[108:111], v[146:149], v[186:189], v[108:111]
	v_mfma_f32_16x16x32_bf16 v[104:107], v[154:157], v[186:189], v[104:107]
	v_mfma_f32_16x16x32_bf16 v[92:95], v[146:149], v[194:197], v[92:95]
	v_mfma_f32_16x16x32_bf16 v[88:91], v[154:157], v[194:197], v[88:91]
	v_mfma_f32_16x16x32_bf16 v[76:79], v[146:149], v[202:205], v[76:79]
	v_mfma_f32_16x16x32_bf16 v[72:75], v[154:157], v[202:205], v[72:75]
	v_mfma_f32_16x16x32_bf16 v[60:63], v[146:149], v[218:221], v[60:63]
	v_mfma_f32_16x16x32_bf16 v[56:59], v[154:157], v[218:221], v[56:59]
	v_mfma_f32_16x16x32_bf16 v[44:47], v[146:149], v[226:229], v[44:47]
	v_mfma_f32_16x16x32_bf16 v[40:43], v[154:157], v[226:229], v[40:43]
	v_mfma_f32_16x16x32_bf16 v[28:31], v[146:149], v[234:237], v[28:31]
	v_mfma_f32_16x16x32_bf16 v[24:27], v[154:157], v[234:237], v[24:27]
	s_waitcnt lgkmcnt(0)
	v_mfma_f32_16x16x32_bf16 v[12:15], v[146:149], v[242:245], v[12:15]
	v_mfma_f32_16x16x32_bf16 v[8:11], v[154:157], v[242:245], v[8:11]
	s_barrier
	ds_read_b128 v[128:131], v142
	ds_read_b128 v[146:149], v142 offset:1024
	ds_read_b128 v[150:153], v142 offset:2048
	ds_read_b128 v[154:157], v142 offset:3072
	s_mov_b32 m0, s47
	s_nop 0
	global_load_lds_dwordx4 v135, s[82:83]
	s_mov_b32 m0, s48
	s_nop 0
	global_load_lds_dwordx4 v137, s[82:83]
	s_mov_b32 m0, s37
	s_nop 0
	global_load_lds_dwordx4 v134, s[42:43]
	s_mov_b32 m0, s49
	s_nop 0
	global_load_lds_dwordx4 v136, s[42:43]
	s_add_u32 s16, s42, 0x20000
	s_addc_u32 s17, s43, 0
	s_mov_b32 m0, s50
	s_nop 0
	global_load_lds_dwordx4 v134, s[16:17]
	s_mov_b32 m0, s51
	s_nop 0
	global_load_lds_dwordx4 v136, s[16:17]
	s_waitcnt vmcnt(8)
	s_waitcnt lgkmcnt(0)
	s_barrier
	s_waitcnt lgkmcnt(3)
	v_mfma_f32_16x16x32_bf16 v[116:119], v[128:131], v[166:169], v[116:119]
	s_waitcnt lgkmcnt(1)
	v_mfma_f32_16x16x32_bf16 v[112:115], v[150:153], v[166:169], v[112:115]
	v_mfma_f32_16x16x32_bf16 v[100:103], v[128:131], v[182:185], v[100:103]
	v_mfma_f32_16x16x32_bf16 v[96:99], v[150:153], v[182:185], v[96:99]
	v_mfma_f32_16x16x32_bf16 v[84:87], v[128:131], v[190:193], v[84:87]
	v_mfma_f32_16x16x32_bf16 v[80:83], v[150:153], v[190:193], v[80:83]
	v_mfma_f32_16x16x32_bf16 v[68:71], v[128:131], v[198:201], v[68:71]
	v_mfma_f32_16x16x32_bf16 v[64:67], v[150:153], v[198:201], v[64:67]
	v_mfma_f32_16x16x32_bf16 v[52:55], v[128:131], v[214:217], v[52:55]
	v_mfma_f32_16x16x32_bf16 v[48:51], v[150:153], v[214:217], v[48:51]
	v_mfma_f32_16x16x32_bf16 v[36:39], v[128:131], v[222:225], v[36:39]
	v_mfma_f32_16x16x32_bf16 v[32:35], v[150:153], v[222:225], v[32:35]
	v_mfma_f32_16x16x32_bf16 v[20:23], v[128:131], v[230:233], v[20:23]
	v_mfma_f32_16x16x32_bf16 v[16:19], v[150:153], v[230:233], v[16:19]
	v_mfma_f32_16x16x32_bf16 v[4:7], v[128:131], v[238:241], v[4:7]
	v_mfma_f32_16x16x32_bf16 v[0:3], v[150:153], v[238:241], v[0:3]
	v_mfma_f32_16x16x32_bf16 v[116:119], v[146:149], v[178:181], v[116:119]
	s_waitcnt lgkmcnt(0)
	v_mfma_f32_16x16x32_bf16 v[112:115], v[154:157], v[178:181], v[112:115]
	v_mfma_f32_16x16x32_bf16 v[100:103], v[146:149], v[186:189], v[100:103]
	v_mfma_f32_16x16x32_bf16 v[96:99], v[154:157], v[186:189], v[96:99]
	v_mfma_f32_16x16x32_bf16 v[84:87], v[146:149], v[194:197], v[84:87]
	v_mfma_f32_16x16x32_bf16 v[80:83], v[154:157], v[194:197], v[80:83]
	v_mfma_f32_16x16x32_bf16 v[68:71], v[146:149], v[202:205], v[68:71]
	v_mfma_f32_16x16x32_bf16 v[64:67], v[154:157], v[202:205], v[64:67]
	v_mfma_f32_16x16x32_bf16 v[52:55], v[146:149], v[218:221], v[52:55]
	v_mfma_f32_16x16x32_bf16 v[48:51], v[154:157], v[218:221], v[48:51]
	v_mfma_f32_16x16x32_bf16 v[36:39], v[146:149], v[226:229], v[36:39]
	v_mfma_f32_16x16x32_bf16 v[32:35], v[154:157], v[226:229], v[32:35]
	v_mfma_f32_16x16x32_bf16 v[20:23], v[146:149], v[234:237], v[20:23]
	v_mfma_f32_16x16x32_bf16 v[16:19], v[154:157], v[234:237], v[16:19]
	v_mfma_f32_16x16x32_bf16 v[4:7], v[146:149], v[242:245], v[4:7]
	v_mfma_f32_16x16x32_bf16 v[0:3], v[154:157], v[242:245], v[0:3]
	s_barrier
; #define PG8_STAGE(bufoff, gbase, voff) do { _Pragma("unroll") for (int _i = 0; _i < 2; ++_i) { \
;         const unsigned _m0 = ldsu + (unsigned)(bufoff) + ldsw + (unsigned)(_i * 8192); \
;         asm volatile("s_mov_b32 m0, %2\n\ts_nop 0\n\tglobal_load_lds_dwordx4 %0, %1" :: "v"((voff)[_i]), "s"((const char*)(gbase)), "s"(_m0) : "memory"); } } while (0)
; #define PG8_LDA(dst, b, h) do { _Pragma("unroll") for (int m = 0; m < 4; ++m) _Pragma("unroll") for (int k = 0; k < 2; ++k) dst[m][k] = *(const LAS bf16x8*)(lds + PG8_SA(b, h) + aoff + m * 2048 + k * 1024); } while (0)
; #define PG8_LDB(dst, b, h) do { _Pragma("unroll") for (int n = 0; n < 2; ++n) _Pragma("unroll") for (int k = 0; k < 2; ++k) dst[n][k] = *(const LAS bf16x8*)(lds + bbase[b][h] + n * 2048 + k * 1024); } while (0)
; #define PG8_WAIT_V(n) asm volatile("s_waitcnt vmcnt(" #n ")" ::: "memory")
; #define PG8_WAIT_L(n) asm volatile("s_waitcnt lgkmcnt(" #n ")" ::: "memory")
; #define PG8_BAR __builtin_amdgcn_s_barrier()
; #define PG8_SCHED __builtin_amdgcn_sched_barrier(0)
; template <class Epi>
; __device__ __forceinline__ void gemm_phase(LAS unsigned char* lds, const Gemm g, const StaticOrder& S, const Epi& E) {
;     ...
;         for (int t = 0; t < nt; t += 2) {
;     ...
;             PG8_LDB(B0, 1, 0); PG8_SCHED; PG8_LDA(At, 1, 0); PG8_LDA(At2, 1, 1); PG8_STAGE(PG8_SB(0, 1), b2 + hstepB, voffB);
;             PG8_WAIT_V(8); PG8_WAIT_L(0); PG8_BAR; PG8_MMA2B(0, At, At2, B0); PG8_BAR; PG8_SCHED;
;             PG8_LDB(B0, 1, 1); PG8_STAGE(PG8_SB(1, 0), b3, voffB); PG8_STAGE(PG8_SA(1, 0), a3, voffA); PG8_STAGE(PG8_SA(1, 1), a3 + hstepA, voffA);
;             PG8_WAIT_V(8); PG8_WAIT_L(0); PG8_BAR; PG8_MMA2B(1, At, At2, B0); PG8_BAR; PG8_SCHED;
;     ...
;         if (wr == 0) PG8_BAR;
	ds_read_b128 v[128:131], v143
	ds_read_b128 v[146:149], v143 offset:1024
	ds_read_b128 v[150:153], v143 offset:2048
	ds_read_b128 v[154:157], v143 offset:3072
	ds_read_b128 v[166:169], v141 offset:32768
	ds_read_b128 v[178:181], v141 offset:33792
	ds_read_b128 v[182:185], v141 offset:34816
	ds_read_b128 v[186:189], v141 offset:35840
	ds_read_b128 v[190:193], v141 offset:36864
	ds_read_b128 v[194:197], v141 offset:37888
	ds_read_b128 v[198:201], v141 offset:38912
	ds_read_b128 v[202:205], v141 offset:39936
	ds_read_b128 v[214:217], v141 offset:49152
	ds_read_b128 v[218:221], v141 offset:50176
	ds_read_b128 v[222:225], v141 offset:51200
	ds_read_b128 v[226:229], v141 offset:52224
	ds_read_b128 v[230:233], v141 offset:53248
	ds_read_b128 v[234:237], v141 offset:54272
	ds_read_b128 v[238:241], v141 offset:55296
	ds_read_b128 v[242:245], v141 offset:56320
	s_add_u32 s16, s82, 0x20000
	s_addc_u32 s17, s83, 0
	s_mov_b32 m0, s52
	s_nop 0
	global_load_lds_dwordx4 v135, s[16:17]
	s_mov_b32 m0, s53
	s_nop 0
	global_load_lds_dwordx4 v137, s[16:17]
	s_waitcnt vmcnt(8)
	s_waitcnt lgkmcnt(0)
	s_barrier
	s_waitcnt lgkmcnt(14)
	v_mfma_f32_16x16x32_bf16 v[124:127], v[128:131], v[166:169], v[124:127]
	v_mfma_f32_16x16x32_bf16 v[120:123], v[150:153], v[166:169], v[120:123]
	s_waitcnt lgkmcnt(13)
	v_mfma_f32_16x16x32_bf16 v[108:111], v[128:131], v[182:185], v[108:111]
	v_mfma_f32_16x16x32_bf16 v[104:107], v[150:153], v[182:185], v[104:107]
	s_waitcnt lgkmcnt(11)
	v_mfma_f32_16x16x32_bf16 v[92:95], v[128:131], v[190:193], v[92:95]
	v_mfma_f32_16x16x32_bf16 v[88:91], v[150:153], v[190:193], v[88:91]
	s_waitcnt lgkmcnt(9)
	v_mfma_f32_16x16x32_bf16 v[76:79], v[128:131], v[198:201], v[76:79]
	v_mfma_f32_16x16x32_bf16 v[72:75], v[150:153], v[198:201], v[72:75]
	s_waitcnt lgkmcnt(7)
	v_mfma_f32_16x16x32_bf16 v[60:63], v[128:131], v[214:217], v[60:63]
	v_mfma_f32_16x16x32_bf16 v[56:59], v[150:153], v[214:217], v[56:59]
	s_waitcnt lgkmcnt(5)
	v_mfma_f32_16x16x32_bf16 v[44:47], v[128:131], v[222:225], v[44:47]
	v_mfma_f32_16x16x32_bf16 v[40:43], v[150:153], v[222:225], v[40:43]
	s_waitcnt lgkmcnt(3)
	v_mfma_f32_16x16x32_bf16 v[28:31], v[128:131], v[230:233], v[28:31]
	v_mfma_f32_16x16x32_bf16 v[24:27], v[150:153], v[230:233], v[24:27]
	s_waitcnt lgkmcnt(1)
	v_mfma_f32_16x16x32_bf16 v[12:15], v[128:131], v[238:241], v[12:15]
	v_mfma_f32_16x16x32_bf16 v[8:11], v[150:153], v[238:241], v[8:11]
	v_mfma_f32_16x16x32_bf16 v[124:127], v[146:149], v[178:181], v[124:127]
	v_mfma_f32_16x16x32_bf16 v[120:123], v[154:157], v[178:181], v[120:123]
	v_mfma_f32_16x16x32_bf16 v[108:111], v[146:149], v[186:189], v[108:111]
	v_mfma_f32_16x16x32_bf16 v[104:107], v[154:157], v[186:189], v[104:107]
	v_mfma_f32_16x16x32_bf16 v[92:95], v[146:149], v[194:197], v[92:95]
	v_mfma_f32_16x16x32_bf16 v[88:91], v[154:157], v[194:197], v[88:91]
	v_mfma_f32_16x16x32_bf16 v[76:79], v[146:149], v[202:205], v[76:79]
	v_mfma_f32_16x16x32_bf16 v[72:75], v[154:157], v[202:205], v[72:75]
	v_mfma_f32_16x16x32_bf16 v[60:63], v[146:149], v[218:221], v[60:63]
	v_mfma_f32_16x16x32_bf16 v[56:59], v[154:157], v[218:221], v[56:59]
	v_mfma_f32_16x16x32_bf16 v[44:47], v[146:149], v[226:229], v[44:47]
	v_mfma_f32_16x16x32_bf16 v[40:43], v[154:157], v[226:229], v[40:43]
	v_mfma_f32_16x16x32_bf16 v[28:31], v[146:149], v[234:237], v[28:31]
	v_mfma_f32_16x16x32_bf16 v[24:27], v[154:157], v[234:237], v[24:27]
	s_waitcnt lgkmcnt(0)
	v_mfma_f32_16x16x32_bf16 v[12:15], v[146:149], v[242:245], v[12:15]
	v_mfma_f32_16x16x32_bf16 v[8:11], v[154:157], v[242:245], v[8:11]
	s_barrier
	s_add_u32 s16, s82, 0x80
	ds_read_b128 v[128:131], v144
	ds_read_b128 v[146:149], v144 offset:1024
	ds_read_b128 v[150:153], v144 offset:2048
	ds_read_b128 v[154:157], v144 offset:3072
	s_addc_u32 s17, s83, 0
	s_mov_b32 m0, s54
	s_nop 0
	global_load_lds_dwordx4 v135, s[16:17]
	s_mov_b32 m0, s55
	s_nop 0
	global_load_lds_dwordx4 v137, s[16:17]
	s_mov_b32 m0, s56
	s_nop 0
	global_load_lds_dwordx4 v134, s[80:81]
	s_mov_b32 m0, s57
	s_nop 0
	global_load_lds_dwordx4 v136, s[80:81]
	s_add_u32 s16, s42, 0x20080
	s_addc_u32 s17, s43, 0
	s_mov_b32 m0, s58
	s_nop 0
	global_load_lds_dwordx4 v134, s[16:17]
	s_mov_b32 m0, s59
	s_nop 0
	global_load_lds_dwordx4 v136, s[16:17]
	s_waitcnt vmcnt(8)
	s_waitcnt lgkmcnt(0)
	s_barrier
	s_waitcnt lgkmcnt(3)
	v_mfma_f32_16x16x32_bf16 v[116:119], v[128:131], v[166:169], v[116:119]
	s_waitcnt lgkmcnt(1)
	v_mfma_f32_16x16x32_bf16 v[112:115], v[150:153], v[166:169], v[112:115]
	v_mfma_f32_16x16x32_bf16 v[100:103], v[128:131], v[182:185], v[100:103]
	v_mfma_f32_16x16x32_bf16 v[96:99], v[150:153], v[182:185], v[96:99]
	v_mfma_f32_16x16x32_bf16 v[84:87], v[128:131], v[190:193], v[84:87]
	v_mfma_f32_16x16x32_bf16 v[80:83], v[150:153], v[190:193], v[80:83]
	v_mfma_f32_16x16x32_bf16 v[68:71], v[128:131], v[198:201], v[68:71]
	v_mfma_f32_16x16x32_bf16 v[64:67], v[150:153], v[198:201], v[64:67]
	v_mfma_f32_16x16x32_bf16 v[52:55], v[128:131], v[214:217], v[52:55]
	v_mfma_f32_16x16x32_bf16 v[48:51], v[150:153], v[214:217], v[48:51]
	v_mfma_f32_16x16x32_bf16 v[36:39], v[128:131], v[222:225], v[36:39]
	v_mfma_f32_16x16x32_bf16 v[32:35], v[150:153], v[222:225], v[32:35]
	v_mfma_f32_16x16x32_bf16 v[20:23], v[128:131], v[230:233], v[20:23]
	v_mfma_f32_16x16x32_bf16 v[16:19], v[150:153], v[230:233], v[16:19]
	v_mfma_f32_16x16x32_bf16 v[4:7], v[128:131], v[238:241], v[4:7]
	v_mfma_f32_16x16x32_bf16 v[0:3], v[150:153], v[238:241], v[0:3]
	v_mfma_f32_16x16x32_bf16 v[116:119], v[146:149], v[178:181], v[116:119]
	s_waitcnt lgkmcnt(0)
	v_mfma_f32_16x16x32_bf16 v[112:115], v[154:157], v[178:181], v[112:115]
	v_mfma_f32_16x16x32_bf16 v[100:103], v[146:149], v[186:189], v[100:103]
	v_mfma_f32_16x16x32_bf16 v[96:99], v[154:157], v[186:189], v[96:99]
	v_mfma_f32_16x16x32_bf16 v[84:87], v[146:149], v[194:197], v[84:87]
	v_mfma_f32_16x16x32_bf16 v[80:83], v[154:157], v[194:197], v[80:83]
	v_mfma_f32_16x16x32_bf16 v[68:71], v[146:149], v[202:205], v[68:71]
	v_mfma_f32_16x16x32_bf16 v[64:67], v[154:157], v[202:205], v[64:67]
	v_mfma_f32_16x16x32_bf16 v[52:55], v[146:149], v[218:221], v[52:55]
	v_mfma_f32_16x16x32_bf16 v[48:51], v[154:157], v[218:221], v[48:51]
	v_mfma_f32_16x16x32_bf16 v[36:39], v[146:149], v[226:229], v[36:39]
	v_mfma_f32_16x16x32_bf16 v[32:35], v[154:157], v[226:229], v[32:35]
	v_mfma_f32_16x16x32_bf16 v[20:23], v[146:149], v[234:237], v[20:23]
	v_mfma_f32_16x16x32_bf16 v[16:19], v[154:157], v[234:237], v[16:19]
	v_mfma_f32_16x16x32_bf16 v[4:7], v[146:149], v[242:245], v[4:7]
	v_mfma_f32_16x16x32_bf16 v[0:3], v[154:157], v[242:245], v[0:3]
	s_add_i32 s68, s68, 2
	s_add_u32 s67, s67, 0x100
	s_addc_u32 s84, s84, 0
	s_cmp_gt_u32 s68, 5
	s_mov_b64 s[16:17], s[38:39]
	s_barrier
	s_cbranch_scc0 .LBB0_870
	s_and_b64 vcc, exec, s[4:5]
	s_cbranch_vccz .LBB0_873
	s_barrier

; #define PG8_STAGE(bufoff, gbase, voff) do { _Pragma("unroll") for (int _i = 0; _i < 2; ++_i) { \
;         const unsigned _m0 = ldsu + (unsigned)(bufoff) + ldsw + (unsigned)(_i * 8192); \
;         asm volatile("s_mov_b32 m0, %2\n\ts_nop 0\n\tglobal_load_lds_dwordx4 %0, %1" :: "v"((voff)[_i]), "s"((const char*)(gbase)), "s"(_m0) : "memory"); } } while (0)
; #define PG8_LDA(dst, b, h) do { _Pragma("unroll") for (int m = 0; m < 4; ++m) _Pragma("unroll") for (int k = 0; k < 2; ++k) dst[m][k] = *(const LAS bf16x8*)(lds + PG8_SA(b, h) + aoff + m * 2048 + k * 1024); } while (0)
; #define PG8_LDB(dst, b, h) do { _Pragma("unroll") for (int n = 0; n < 2; ++n) _Pragma("unroll") for (int k = 0; k < 2; ++k) dst[n][k] = *(const LAS bf16x8*)(lds + bbase[b][h] + n * 2048 + k * 1024); } while (0)
; #define PG8_WAIT_V(n) asm volatile("s_waitcnt vmcnt(" #n ")" ::: "memory")
; #define PG8_WAIT_L(n) asm volatile("s_waitcnt lgkmcnt(" #n ")" ::: "memory")
; #define PG8_BAR __builtin_amdgcn_s_barrier()
; #define PG8_SCHED __builtin_amdgcn_sched_barrier(0)
; template <class Epi>
; __device__ __forceinline__ void gemm_phase(LAS unsigned char* lds, const Gemm g, const StaticOrder& S, const Epi& E) {
;     ...
;             const char* a2 = last ? nA : cA + (size_t)(t + 2) * kstep; const char* b2 = last ? nB : cB + (size_t)(t + 2) * kstep;
;             const char* a3 = a2 + kstep; const char* b3 = b2 + kstep;
;             const char* b1 = cB + (size_t)(t + 1) * kstep;
;             PG8_LDB(B0, 0, 0); PG8_SCHED; PG8_LDA(At, 0, 0); PG8_LDA(At2, 0, 1); PG8_STAGE(PG8_SB(1, 1), b1 + hstepB, voffB);
;             PG8_WAIT_V(8); PG8_WAIT_L(0); PG8_BAR; PG8_MMA2B(0, At, At2, B0); PG8_BAR; PG8_SCHED;
;             PG8_LDB(B0, 0, 1); PG8_STAGE(PG8_SB(0, 0), b2, voffB); PG8_STAGE(PG8_SA(0, 0), a2, voffA); PG8_STAGE(PG8_SA(0, 1), a2 + hstepA, voffA);
;             PG8_WAIT_V(8); PG8_WAIT_L(0); PG8_BAR; PG8_MMA2B(1, At, At2, B0); PG8_BAR; PG8_SCHED;
.LBB0_943:
	ds_read_b128 v[128:131], v138
	ds_read_b128 v[144:147], v138 offset:1024
	ds_read_b128 v[148:151], v138 offset:2048
	ds_read_b128 v[152:155], v138 offset:3072
	s_cmp_eq_u32 s68, 12
	s_cselect_b32 s38, s66, s84
	s_cselect_b32 s39, s13, s85
	s_cselect_b32 s82, s67, s86
	s_cselect_b32 s83, s5, s87
	s_add_u32 s42, s38, 0x80
	s_addc_u32 s43, s39, 0
	s_add_u32 s80, s82, 0x80
	s_addc_u32 s81, s83, 0
	ds_read_b128 v[156:159], v139
	ds_read_b128 v[166:169], v139 offset:1024
	ds_read_b128 v[178:181], v139 offset:2048
	ds_read_b128 v[182:185], v139 offset:3072
	ds_read_b128 v[186:189], v139 offset:4096
	ds_read_b128 v[190:193], v139 offset:5120
	ds_read_b128 v[194:197], v139 offset:6144
	ds_read_b128 v[198:201], v139 offset:7168
	ds_read_b128 v[202:205], v139 offset:16384
	ds_read_b128 v[214:217], v139 offset:17408
	ds_read_b128 v[218:221], v139 offset:18432
	ds_read_b128 v[222:225], v139 offset:19456
	ds_read_b128 v[226:229], v139 offset:20480
	ds_read_b128 v[230:233], v139 offset:21504
	ds_read_b128 v[234:237], v139 offset:22528
	ds_read_b128 v[238:241], v139 offset:23552
	s_mov_b32 m0, s61
	s_nop 0
	global_load_lds_dwordx4 v133, s[6:7]
	s_mov_b32 m0, s63
	s_nop 0
	global_load_lds_dwordx4 v135, s[6:7]
	s_waitcnt vmcnt(8)
	s_waitcnt lgkmcnt(0)
	s_barrier
	s_waitcnt lgkmcnt(14)
	v_mfma_f32_16x16x32_bf16 v[124:127], v[128:131], v[156:159], v[124:127]
	v_mfma_f32_16x16x32_bf16 v[120:123], v[148:151], v[156:159], v[120:123]
	s_waitcnt lgkmcnt(13)
	v_mfma_f32_16x16x32_bf16 v[108:111], v[128:131], v[178:181], v[108:111]
	v_mfma_f32_16x16x32_bf16 v[104:107], v[148:151], v[178:181], v[104:107]
	s_waitcnt lgkmcnt(11)
	v_mfma_f32_16x16x32_bf16 v[92:95], v[128:131], v[186:189], v[92:95]
	v_mfma_f32_16x16x32_bf16 v[88:91], v[148:151], v[186:189], v[88:91]
	s_waitcnt lgkmcnt(9)
	v_mfma_f32_16x16x32_bf16 v[76:79], v[128:131], v[194:197], v[76:79]
	v_mfma_f32_16x16x32_bf16 v[72:75], v[148:151], v[194:197], v[72:75]
	s_waitcnt lgkmcnt(7)
	v_mfma_f32_16x16x32_bf16 v[60:63], v[128:131], v[202:205], v[60:63]
	v_mfma_f32_16x16x32_bf16 v[56:59], v[148:151], v[202:205], v[56:59]
	s_waitcnt lgkmcnt(5)
	v_mfma_f32_16x16x32_bf16 v[44:47], v[128:131], v[218:221], v[44:47]
	v_mfma_f32_16x16x32_bf16 v[40:43], v[148:151], v[218:221], v[40:43]
	s_waitcnt lgkmcnt(3)
	v_mfma_f32_16x16x32_bf16 v[28:31], v[128:131], v[226:229], v[28:31]
	v_mfma_f32_16x16x32_bf16 v[24:27], v[148:151], v[226:229], v[24:27]
	s_waitcnt lgkmcnt(1)
	v_mfma_f32_16x16x32_bf16 v[12:15], v[128:131], v[234:237], v[12:15]
	v_mfma_f32_16x16x32_bf16 v[8:11], v[148:151], v[234:237], v[8:11]
	v_mfma_f32_16x16x32_bf16 v[124:127], v[144:147], v[166:169], v[124:127]
	v_mfma_f32_16x16x32_bf16 v[120:123], v[152:155], v[166:169], v[120:123]
	v_mfma_f32_16x16x32_bf16 v[108:111], v[144:147], v[182:185], v[108:111]
	v_mfma_f32_16x16x32_bf16 v[104:107], v[152:155], v[182:185], v[104:107]
	v_mfma_f32_16x16x32_bf16 v[92:95], v[144:147], v[190:193], v[92:95]
	v_mfma_f32_16x16x32_bf16 v[88:91], v[152:155], v[190:193], v[88:91]
	v_mfma_f32_16x16x32_bf16 v[76:79], v[144:147], v[198:201], v[76:79]
	v_mfma_f32_16x16x32_bf16 v[72:75], v[152:155], v[198:201], v[72:75]
	v_mfma_f32_16x16x32_bf16 v[60:63], v[144:147], v[214:217], v[60:63]
	v_mfma_f32_16x16x32_bf16 v[56:59], v[152:155], v[214:217], v[56:59]
	v_mfma_f32_16x16x32_bf16 v[44:47], v[144:147], v[222:225], v[44:47]
	v_mfma_f32_16x16x32_bf16 v[40:43], v[152:155], v[222:225], v[40:43]
	v_mfma_f32_16x16x32_bf16 v[28:31], v[144:147], v[230:233], v[28:31]
	v_mfma_f32_16x16x32_bf16 v[24:27], v[152:155], v[230:233], v[24:27]
	s_waitcnt lgkmcnt(0)
	v_mfma_f32_16x16x32_bf16 v[12:15], v[144:147], v[238:241], v[12:15]
	v_mfma_f32_16x16x32_bf16 v[8:11], v[152:155], v[238:241], v[8:11]
	s_barrier
	ds_read_b128 v[128:131], v140
	ds_read_b128 v[144:147], v140 offset:1024
	ds_read_b128 v[148:151], v140 offset:2048
	ds_read_b128 v[152:155], v140 offset:3072
	s_mov_b32 m0, s48
	s_nop 0
	global_load_lds_dwordx4 v133, s[82:83]
	s_mov_b32 m0, s49
	s_nop 0
	global_load_lds_dwordx4 v135, s[82:83]
	s_mov_b32 m0, s47
	s_nop 0
	global_load_lds_dwordx4 v132, s[38:39]
	s_mov_b32 m0, s50
	s_nop 0
	global_load_lds_dwordx4 v134, s[38:39]
	s_add_u32 s88, s38, 0x40000
	s_addc_u32 s89, s39, 0
	s_mov_b32 m0, s51
	s_nop 0
	global_load_lds_dwordx4 v132, s[88:89]
	s_mov_b32 m0, s52
	s_nop 0
	global_load_lds_dwordx4 v134, s[88:89]
	s_waitcnt vmcnt(8)
	s_waitcnt lgkmcnt(0)
	s_barrier
	s_waitcnt lgkmcnt(3)
	v_mfma_f32_16x16x32_bf16 v[116:119], v[128:131], v[156:159], v[116:119]
	s_waitcnt lgkmcnt(1)
	v_mfma_f32_16x16x32_bf16 v[112:115], v[148:151], v[156:159], v[112:115]
	v_mfma_f32_16x16x32_bf16 v[100:103], v[128:131], v[178:181], v[100:103]
	v_mfma_f32_16x16x32_bf16 v[96:99], v[148:151], v[178:181], v[96:99]
	v_mfma_f32_16x16x32_bf16 v[84:87], v[128:131], v[186:189], v[84:87]
	v_mfma_f32_16x16x32_bf16 v[80:83], v[148:151], v[186:189], v[80:83]
	v_mfma_f32_16x16x32_bf16 v[68:71], v[128:131], v[194:197], v[68:71]
	v_mfma_f32_16x16x32_bf16 v[64:67], v[148:151], v[194:197], v[64:67]
	v_mfma_f32_16x16x32_bf16 v[52:55], v[128:131], v[202:205], v[52:55]
	v_mfma_f32_16x16x32_bf16 v[48:51], v[148:151], v[202:205], v[48:51]
	v_mfma_f32_16x16x32_bf16 v[36:39], v[128:131], v[218:221], v[36:39]
	v_mfma_f32_16x16x32_bf16 v[32:35], v[148:151], v[218:221], v[32:35]
	v_mfma_f32_16x16x32_bf16 v[20:23], v[128:131], v[226:229], v[20:23]
	v_mfma_f32_16x16x32_bf16 v[16:19], v[148:151], v[226:229], v[16:19]
	v_mfma_f32_16x16x32_bf16 v[4:7], v[128:131], v[234:237], v[4:7]
	v_mfma_f32_16x16x32_bf16 v[0:3], v[148:151], v[234:237], v[0:3]
	v_mfma_f32_16x16x32_bf16 v[116:119], v[144:147], v[166:169], v[116:119]
	s_waitcnt lgkmcnt(0)
	v_mfma_f32_16x16x32_bf16 v[112:115], v[152:155], v[166:169], v[112:115]
	v_mfma_f32_16x16x32_bf16 v[100:103], v[144:147], v[182:185], v[100:103]
	v_mfma_f32_16x16x32_bf16 v[96:99], v[152:155], v[182:185], v[96:99]
	v_mfma_f32_16x16x32_bf16 v[84:87], v[144:147], v[190:193], v[84:87]
	v_mfma_f32_16x16x32_bf16 v[80:83], v[152:155], v[190:193], v[80:83]
	v_mfma_f32_16x16x32_bf16 v[68:71], v[144:147], v[198:201], v[68:71]
	v_mfma_f32_16x16x32_bf16 v[64:67], v[152:155], v[198:201], v[64:67]
	v_mfma_f32_16x16x32_bf16 v[52:55], v[144:147], v[214:217], v[52:55]
	v_mfma_f32_16x16x32_bf16 v[48:51], v[152:155], v[214:217], v[48:51]
	v_mfma_f32_16x16x32_bf16 v[36:39], v[144:147], v[222:225], v[36:39]
	v_mfma_f32_16x16x32_bf16 v[32:35], v[152:155], v[222:225], v[32:35]
	v_mfma_f32_16x16x32_bf16 v[20:23], v[144:147], v[230:233], v[20:23]
	v_mfma_f32_16x16x32_bf16 v[16:19], v[152:155], v[230:233], v[16:19]
	v_mfma_f32_16x16x32_bf16 v[4:7], v[144:147], v[238:241], v[4:7]
	v_mfma_f32_16x16x32_bf16 v[0:3], v[152:155], v[238:241], v[0:3]
	s_barrier
; #define PG8_STAGE(bufoff, gbase, voff) do { _Pragma("unroll") for (int _i = 0; _i < 2; ++_i) { \
;         const unsigned _m0 = ldsu + (unsigned)(bufoff) + ldsw + (unsigned)(_i * 8192); \
;         asm volatile("s_mov_b32 m0, %2\n\ts_nop 0\n\tglobal_load_lds_dwordx4 %0, %1" :: "v"((voff)[_i]), "s"((const char*)(gbase)), "s"(_m0) : "memory"); } } while (0)
; #define PG8_LDA(dst, b, h) do { _Pragma("unroll") for (int m = 0; m < 4; ++m) _Pragma("unroll") for (int k = 0; k < 2; ++k) dst[m][k] = *(const LAS bf16x8*)(lds + PG8_SA(b, h) + aoff + m * 2048 + k * 1024); } while (0)
; #define PG8_LDB(dst, b, h) do { _Pragma("unroll") for (int n = 0; n < 2; ++n) _Pragma("unroll") for (int k = 0; k < 2; ++k) dst[n][k] = *(const LAS bf16x8*)(lds + bbase[b][h] + n * 2048 + k * 1024); } while (0)
; #define PG8_WAIT_V(n) asm volatile("s_waitcnt vmcnt(" #n ")" ::: "memory")
; #define PG8_WAIT_L(n) asm volatile("s_waitcnt lgkmcnt(" #n ")" ::: "memory")
; #define PG8_BAR __builtin_amdgcn_s_barrier()
; #define PG8_SCHED __builtin_amdgcn_sched_barrier(0)
; template <class Epi>
; __device__ __forceinline__ void gemm_phase(LAS unsigned char* lds, const Gemm g, const StaticOrder& S, const Epi& E) {
;     ...
;         for (int t = 0; t < nt; t += 2) {
;     ...
;             PG8_LDB(B0, 1, 0); PG8_SCHED; PG8_LDA(At, 1, 0); PG8_LDA(At2, 1, 1); PG8_STAGE(PG8_SB(0, 1), b2 + hstepB, voffB);
;             PG8_WAIT_V(8); PG8_WAIT_L(0); PG8_BAR; PG8_MMA2B(0, At, At2, B0); PG8_BAR; PG8_SCHED;
;             PG8_LDB(B0, 1, 1); PG8_STAGE(PG8_SB(1, 0), b3, voffB); PG8_STAGE(PG8_SA(1, 0), a3, voffA); PG8_STAGE(PG8_SA(1, 1), a3 + hstepA, voffA);
;             PG8_WAIT_V(8); PG8_WAIT_L(0); PG8_BAR; PG8_MMA2B(1, At, At2, B0); PG8_BAR; PG8_SCHED;
;     ...
;         if (wr == 0) PG8_BAR;
	ds_read_b128 v[128:131], v141
	ds_read_b128 v[144:147], v141 offset:1024
	ds_read_b128 v[148:151], v141 offset:2048
	ds_read_b128 v[152:155], v141 offset:3072
	ds_read_b128 v[156:159], v139 offset:32768
	ds_read_b128 v[166:169], v139 offset:33792
	ds_read_b128 v[178:181], v139 offset:34816
	ds_read_b128 v[182:185], v139 offset:35840
	ds_read_b128 v[186:189], v139 offset:36864
	ds_read_b128 v[190:193], v139 offset:37888
	ds_read_b128 v[194:197], v139 offset:38912
	ds_read_b128 v[198:201], v139 offset:39936
	ds_read_b128 v[202:205], v139 offset:49152
	ds_read_b128 v[214:217], v139 offset:50176
	ds_read_b128 v[218:221], v139 offset:51200
	ds_read_b128 v[222:225], v139 offset:52224
	ds_read_b128 v[226:229], v139 offset:53248
	ds_read_b128 v[230:233], v139 offset:54272
	ds_read_b128 v[234:237], v139 offset:55296
	ds_read_b128 v[238:241], v139 offset:56320
	s_add_u32 s82, s82, 0x40000
	s_addc_u32 s83, s83, 0
	s_mov_b32 m0, s53
	s_nop 0
	global_load_lds_dwordx4 v133, s[82:83]
	s_mov_b32 m0, s54
	s_nop 0
	global_load_lds_dwordx4 v135, s[82:83]
	s_waitcnt vmcnt(8)
	s_waitcnt lgkmcnt(0)
	s_barrier
	s_waitcnt lgkmcnt(14)
	v_mfma_f32_16x16x32_bf16 v[124:127], v[128:131], v[156:159], v[124:127]
	v_mfma_f32_16x16x32_bf16 v[120:123], v[148:151], v[156:159], v[120:123]
	s_waitcnt lgkmcnt(13)
	v_mfma_f32_16x16x32_bf16 v[108:111], v[128:131], v[178:181], v[108:111]
	v_mfma_f32_16x16x32_bf16 v[104:107], v[148:151], v[178:181], v[104:107]
	s_waitcnt lgkmcnt(11)
	v_mfma_f32_16x16x32_bf16 v[92:95], v[128:131], v[186:189], v[92:95]
	v_mfma_f32_16x16x32_bf16 v[88:91], v[148:151], v[186:189], v[88:91]
	s_waitcnt lgkmcnt(9)
	v_mfma_f32_16x16x32_bf16 v[76:79], v[128:131], v[194:197], v[76:79]
	v_mfma_f32_16x16x32_bf16 v[72:75], v[148:151], v[194:197], v[72:75]
	s_waitcnt lgkmcnt(7)
	v_mfma_f32_16x16x32_bf16 v[60:63], v[128:131], v[202:205], v[60:63]
	v_mfma_f32_16x16x32_bf16 v[56:59], v[148:151], v[202:205], v[56:59]
	s_waitcnt lgkmcnt(5)
	v_mfma_f32_16x16x32_bf16 v[44:47], v[128:131], v[218:221], v[44:47]
	v_mfma_f32_16x16x32_bf16 v[40:43], v[148:151], v[218:221], v[40:43]
	s_waitcnt lgkmcnt(3)
	v_mfma_f32_16x16x32_bf16 v[28:31], v[128:131], v[226:229], v[28:31]
	v_mfma_f32_16x16x32_bf16 v[24:27], v[148:151], v[226:229], v[24:27]
	s_waitcnt lgkmcnt(1)
	v_mfma_f32_16x16x32_bf16 v[12:15], v[128:131], v[234:237], v[12:15]
	v_mfma_f32_16x16x32_bf16 v[8:11], v[148:151], v[234:237], v[8:11]
	v_mfma_f32_16x16x32_bf16 v[124:127], v[144:147], v[166:169], v[124:127]
	v_mfma_f32_16x16x32_bf16 v[120:123], v[152:155], v[166:169], v[120:123]
	v_mfma_f32_16x16x32_bf16 v[108:111], v[144:147], v[182:185], v[108:111]
	v_mfma_f32_16x16x32_bf16 v[104:107], v[152:155], v[182:185], v[104:107]
	v_mfma_f32_16x16x32_bf16 v[92:95], v[144:147], v[190:193], v[92:95]
	v_mfma_f32_16x16x32_bf16 v[88:91], v[152:155], v[190:193], v[88:91]
	v_mfma_f32_16x16x32_bf16 v[76:79], v[144:147], v[198:201], v[76:79]
	v_mfma_f32_16x16x32_bf16 v[72:75], v[152:155], v[198:201], v[72:75]
	v_mfma_f32_16x16x32_bf16 v[60:63], v[144:147], v[214:217], v[60:63]
	v_mfma_f32_16x16x32_bf16 v[56:59], v[152:155], v[214:217], v[56:59]
	v_mfma_f32_16x16x32_bf16 v[44:47], v[144:147], v[222:225], v[44:47]
	v_mfma_f32_16x16x32_bf16 v[40:43], v[152:155], v[222:225], v[40:43]
	v_mfma_f32_16x16x32_bf16 v[28:31], v[144:147], v[230:233], v[28:31]
	v_mfma_f32_16x16x32_bf16 v[24:27], v[152:155], v[230:233], v[24:27]
	s_waitcnt lgkmcnt(0)
	v_mfma_f32_16x16x32_bf16 v[12:15], v[144:147], v[238:241], v[12:15]
	v_mfma_f32_16x16x32_bf16 v[8:11], v[152:155], v[238:241], v[8:11]
	s_barrier
	ds_read_b128 v[128:131], v142
	ds_read_b128 v[144:147], v142 offset:1024
	ds_read_b128 v[148:151], v142 offset:2048
	ds_read_b128 v[152:155], v142 offset:3072
	s_mov_b32 m0, s55
	s_nop 0
	global_load_lds_dwordx4 v133, s[80:81]
	s_mov_b32 m0, s56
	s_nop 0
	global_load_lds_dwordx4 v135, s[80:81]
	s_mov_b32 m0, s57
	s_nop 0
	global_load_lds_dwordx4 v132, s[42:43]
	s_mov_b32 m0, s58
	s_nop 0
	global_load_lds_dwordx4 v134, s[42:43]
	s_add_u32 s38, s38, 0x40080
	s_addc_u32 s39, s39, 0
	s_mov_b32 m0, s59
	s_nop 0
	global_load_lds_dwordx4 v132, s[38:39]
	s_mov_b32 m0, s60
	s_nop 0
	global_load_lds_dwordx4 v134, s[38:39]
	s_waitcnt vmcnt(8)
	s_waitcnt lgkmcnt(0)
	s_barrier
	s_waitcnt lgkmcnt(3)
	v_mfma_f32_16x16x32_bf16 v[116:119], v[128:131], v[156:159], v[116:119]
	s_waitcnt lgkmcnt(1)
	v_mfma_f32_16x16x32_bf16 v[112:115], v[148:151], v[156:159], v[112:115]
	v_mfma_f32_16x16x32_bf16 v[100:103], v[128:131], v[178:181], v[100:103]
	v_mfma_f32_16x16x32_bf16 v[96:99], v[148:151], v[178:181], v[96:99]
	v_mfma_f32_16x16x32_bf16 v[84:87], v[128:131], v[186:189], v[84:87]
	v_mfma_f32_16x16x32_bf16 v[80:83], v[148:151], v[186:189], v[80:83]
	v_mfma_f32_16x16x32_bf16 v[68:71], v[128:131], v[194:197], v[68:71]
	v_mfma_f32_16x16x32_bf16 v[64:67], v[148:151], v[194:197], v[64:67]
	v_mfma_f32_16x16x32_bf16 v[52:55], v[128:131], v[202:205], v[52:55]
	v_mfma_f32_16x16x32_bf16 v[48:51], v[148:151], v[202:205], v[48:51]
	v_mfma_f32_16x16x32_bf16 v[36:39], v[128:131], v[218:221], v[36:39]
	v_mfma_f32_16x16x32_bf16 v[32:35], v[148:151], v[218:221], v[32:35]
	v_mfma_f32_16x16x32_bf16 v[20:23], v[128:131], v[226:229], v[20:23]
	v_mfma_f32_16x16x32_bf16 v[16:19], v[148:151], v[226:229], v[16:19]
	v_mfma_f32_16x16x32_bf16 v[4:7], v[128:131], v[234:237], v[4:7]
	v_mfma_f32_16x16x32_bf16 v[0:3], v[148:151], v[234:237], v[0:3]
	v_mfma_f32_16x16x32_bf16 v[116:119], v[144:147], v[166:169], v[116:119]
	s_waitcnt lgkmcnt(0)
	v_mfma_f32_16x16x32_bf16 v[112:115], v[152:155], v[166:169], v[112:115]
	v_mfma_f32_16x16x32_bf16 v[100:103], v[144:147], v[182:185], v[100:103]
	v_mfma_f32_16x16x32_bf16 v[96:99], v[152:155], v[182:185], v[96:99]
	v_mfma_f32_16x16x32_bf16 v[84:87], v[144:147], v[190:193], v[84:87]
	v_mfma_f32_16x16x32_bf16 v[80:83], v[152:155], v[190:193], v[80:83]
	v_mfma_f32_16x16x32_bf16 v[68:71], v[144:147], v[198:201], v[68:71]
	v_mfma_f32_16x16x32_bf16 v[64:67], v[152:155], v[198:201], v[64:67]
	v_mfma_f32_16x16x32_bf16 v[52:55], v[144:147], v[214:217], v[52:55]
	v_mfma_f32_16x16x32_bf16 v[48:51], v[152:155], v[214:217], v[48:51]
	v_mfma_f32_16x16x32_bf16 v[36:39], v[144:147], v[222:225], v[36:39]
	v_mfma_f32_16x16x32_bf16 v[32:35], v[152:155], v[222:225], v[32:35]
	v_mfma_f32_16x16x32_bf16 v[20:23], v[144:147], v[230:233], v[20:23]
	v_mfma_f32_16x16x32_bf16 v[16:19], v[152:155], v[230:233], v[16:19]
	v_mfma_f32_16x16x32_bf16 v[4:7], v[144:147], v[238:241], v[4:7]
	v_mfma_f32_16x16x32_bf16 v[0:3], v[152:155], v[238:241], v[0:3]
	s_add_i32 s68, s68, 2
	s_add_u32 s6, s6, 0x100
	s_addc_u32 s7, s7, 0
	s_add_u32 s84, s84, 0x100
	s_addc_u32 s85, s85, 0
	s_add_u32 s86, s86, 0x100
	s_addc_u32 s87, s87, 0
	s_cmp_gt_u32 s68, 13
	s_barrier
	s_cbranch_scc0 .LBB0_943
	s_and_b64 vcc, exec, s[2:3]
	s_cbranch_vccz .LBB0_946
	s_barrier

; #define PG8_STAGE(bufoff, gbase, voff) do { _Pragma("unroll") for (int _i = 0; _i < 2; ++_i) { \
;         const unsigned _m0 = ldsu + (unsigned)(bufoff) + ldsw + (unsigned)(_i * 8192); \
;         asm volatile("s_mov_b32 m0, %2\n\ts_nop 0\n\tglobal_load_lds_dwordx4 %0, %1" :: "v"((voff)[_i]), "s"((const char*)(gbase)), "s"(_m0) : "memory"); } } while (0)
; #define PG8_LDA(dst, b, h) do { _Pragma("unroll") for (int m = 0; m < 4; ++m) _Pragma("unroll") for (int k = 0; k < 2; ++k) dst[m][k] = *(const LAS bf16x8*)(lds + PG8_SA(b, h) + aoff + m * 2048 + k * 1024); } while (0)
; #define PG8_LDB(dst, b, h) do { _Pragma("unroll") for (int n = 0; n < 2; ++n) _Pragma("unroll") for (int k = 0; k < 2; ++k) dst[n][k] = *(const LAS bf16x8*)(lds + bbase[b][h] + n * 2048 + k * 1024); } while (0)
; #define PG8_WAIT_V(n) asm volatile("s_waitcnt vmcnt(" #n ")" ::: "memory")
; #define PG8_WAIT_L(n) asm volatile("s_waitcnt lgkmcnt(" #n ")" ::: "memory")
; #define PG8_BAR __builtin_amdgcn_s_barrier()
; #define PG8_SCHED __builtin_amdgcn_sched_barrier(0)
; template <class Epi>
; __device__ __forceinline__ void gemm_phase(LAS unsigned char* lds, const Gemm g, const StaticOrder& S, const Epi& E) {
;     ...
;             const char* a2 = last ? nA : cA + (size_t)(t + 2) * kstep; const char* b2 = last ? nB : cB + (size_t)(t + 2) * kstep;
;             const char* a3 = a2 + kstep; const char* b3 = b2 + kstep;
;             const char* b1 = cB + (size_t)(t + 1) * kstep;
;             PG8_LDB(B0, 0, 0); PG8_SCHED; PG8_LDA(At, 0, 0); PG8_LDA(At2, 0, 1); PG8_STAGE(PG8_SB(1, 1), b1 + hstepB, voffB);
;             PG8_WAIT_V(8); PG8_WAIT_L(0); PG8_BAR; PG8_MMA2B(0, At, At2, B0); PG8_BAR; PG8_SCHED;
;             PG8_LDB(B0, 0, 1); PG8_STAGE(PG8_SB(0, 0), b2, voffB); PG8_STAGE(PG8_SA(0, 0), a2, voffA); PG8_STAGE(PG8_SA(0, 1), a2 + hstepA, voffA);
;             PG8_WAIT_V(8); PG8_WAIT_L(0); PG8_BAR; PG8_MMA2B(1, At, At2, B0); PG8_BAR; PG8_SCHED;
.LBB0_1027:
	ds_read_b128 v[68:71], v220
	ds_read_b128 v[84:87], v220 offset:1024
	ds_read_b128 v[88:91], v220 offset:2048
	ds_read_b128 v[92:95], v220 offset:3072
	s_add_u32 s12, s10, 0x100
	s_addc_u32 s13, s11, 0
	s_cmp_eq_u32 s69, 12
	s_cselect_b32 s14, s97, vcc_hi
	s_cselect_b32 s15, s7, s68
	s_cselect_b32 s84, vcc_lo, s12
	s_cselect_b32 s85, s39, s13
	s_add_u32 s16, s14, 0x80
	s_addc_u32 s17, s15, 0
	ds_read_b128 v[96:99], v221
	ds_read_b128 v[100:103], v221 offset:1024
	ds_read_b128 v[152:155], v221 offset:2048
	ds_read_b128 v[156:159], v221 offset:3072
	ds_read_b128 v[166:169], v221 offset:4096
	ds_read_b128 v[178:181], v221 offset:5120
	ds_read_b128 v[182:185], v221 offset:6144
	ds_read_b128 v[186:189], v221 offset:7168
	ds_read_b128 v[190:193], v221 offset:16384
	ds_read_b128 v[194:197], v221 offset:17408
	ds_read_b128 v[198:201], v221 offset:18432
	ds_read_b128 v[202:205], v221 offset:19456
	ds_read_b128 v[226:229], v221 offset:20480
	ds_read_b128 v[230:233], v221 offset:21504
	ds_read_b128 v[234:237], v221 offset:22528
	ds_read_b128 v[238:241], v221 offset:23552
	s_add_u32 s10, s10, 0x40080
	s_addc_u32 s11, s11, 0
	s_mov_b32 m0, s58
	s_nop 0
	global_load_lds_dwordx4 v217, s[10:11]
	s_mov_b32 m0, s60
	s_nop 0
	global_load_lds_dwordx4 v219, s[10:11]
	s_waitcnt vmcnt(8)
	s_waitcnt lgkmcnt(0)
	s_barrier
	s_waitcnt lgkmcnt(14)
	v_mfma_f32_16x16x32_bf16 v[80:83], v[68:71], v[96:99], v[80:83]
	v_mfma_f32_16x16x32_bf16 v[76:79], v[88:91], v[96:99], v[76:79]
	s_waitcnt lgkmcnt(13)
	v_mfma_f32_16x16x32_bf16 v[148:151], v[68:71], v[152:155], v[148:151]
	v_mfma_f32_16x16x32_bf16 v[52:55], v[88:91], v[152:155], v[52:55]
	s_waitcnt lgkmcnt(11)
	v_mfma_f32_16x16x32_bf16 v[144:147], v[68:71], v[166:169], v[144:147]
	v_mfma_f32_16x16x32_bf16 v[48:51], v[88:91], v[166:169], v[48:51]
	s_waitcnt lgkmcnt(9)
	v_mfma_f32_16x16x32_bf16 v[136:139], v[68:71], v[182:185], v[136:139]
	v_mfma_f32_16x16x32_bf16 v[40:43], v[88:91], v[182:185], v[40:43]
	s_waitcnt lgkmcnt(7)
	v_mfma_f32_16x16x32_bf16 v[124:127], v[68:71], v[190:193], v[124:127]
	v_mfma_f32_16x16x32_bf16 v[28:31], v[88:91], v[190:193], v[28:31]
	s_waitcnt lgkmcnt(5)
	v_mfma_f32_16x16x32_bf16 v[120:123], v[68:71], v[198:201], v[120:123]
	v_mfma_f32_16x16x32_bf16 v[24:27], v[88:91], v[198:201], v[24:27]
	s_waitcnt lgkmcnt(3)
	v_mfma_f32_16x16x32_bf16 v[112:115], v[68:71], v[226:229], v[112:115]
	v_mfma_f32_16x16x32_bf16 v[16:19], v[88:91], v[226:229], v[16:19]
	s_waitcnt lgkmcnt(1)
	v_mfma_f32_16x16x32_bf16 v[64:67], v[68:71], v[234:237], v[64:67]
	v_mfma_f32_16x16x32_bf16 v[4:7], v[88:91], v[234:237], v[4:7]
	v_mfma_f32_16x16x32_bf16 v[80:83], v[84:87], v[100:103], v[80:83]
	v_mfma_f32_16x16x32_bf16 v[76:79], v[92:95], v[100:103], v[76:79]
	v_mfma_f32_16x16x32_bf16 v[148:151], v[84:87], v[156:159], v[148:151]
	v_mfma_f32_16x16x32_bf16 v[52:55], v[92:95], v[156:159], v[52:55]
	v_mfma_f32_16x16x32_bf16 v[144:147], v[84:87], v[178:181], v[144:147]
	v_mfma_f32_16x16x32_bf16 v[48:51], v[92:95], v[178:181], v[48:51]
	v_mfma_f32_16x16x32_bf16 v[136:139], v[84:87], v[186:189], v[136:139]
	v_mfma_f32_16x16x32_bf16 v[40:43], v[92:95], v[186:189], v[40:43]
	v_mfma_f32_16x16x32_bf16 v[124:127], v[84:87], v[194:197], v[124:127]
	v_mfma_f32_16x16x32_bf16 v[28:31], v[92:95], v[194:197], v[28:31]
	v_mfma_f32_16x16x32_bf16 v[120:123], v[84:87], v[202:205], v[120:123]
	v_mfma_f32_16x16x32_bf16 v[24:27], v[92:95], v[202:205], v[24:27]
	v_mfma_f32_16x16x32_bf16 v[112:115], v[84:87], v[230:233], v[112:115]
	v_mfma_f32_16x16x32_bf16 v[16:19], v[92:95], v[230:233], v[16:19]
	s_waitcnt lgkmcnt(0)
	v_mfma_f32_16x16x32_bf16 v[64:67], v[84:87], v[238:241], v[64:67]
	v_mfma_f32_16x16x32_bf16 v[4:7], v[92:95], v[238:241], v[4:7]
	s_barrier
	ds_read_b128 v[68:71], v222
	ds_read_b128 v[84:87], v222 offset:1024
	ds_read_b128 v[88:91], v222 offset:2048
	ds_read_b128 v[92:95], v222 offset:3072
	s_mov_b32 m0, s48
	s_nop 0
	global_load_lds_dwordx4 v217, s[84:85]
	s_mov_b32 m0, s49
	s_nop 0
	global_load_lds_dwordx4 v219, s[84:85]
	s_mov_b32 m0, s47
	s_nop 0
	global_load_lds_dwordx4 v216, s[14:15]
	s_mov_b32 m0, s50
	s_nop 0
	global_load_lds_dwordx4 v218, s[14:15]
	s_add_u32 s10, s14, 0x40000
	s_addc_u32 s11, s15, 0
	s_mov_b32 m0, s51
	s_nop 0
	global_load_lds_dwordx4 v216, s[10:11]
	s_mov_b32 m0, s52
	s_nop 0
	global_load_lds_dwordx4 v218, s[10:11]
	s_waitcnt vmcnt(8)
	s_waitcnt lgkmcnt(0)
	s_barrier
	s_waitcnt lgkmcnt(3)
	v_mfma_f32_16x16x32_bf16 v[72:75], v[68:71], v[96:99], v[72:75]
	s_waitcnt lgkmcnt(1)
	v_mfma_f32_16x16x32_bf16 v[56:59], v[88:91], v[96:99], v[56:59]
	v_mfma_f32_16x16x32_bf16 v[44:47], v[88:91], v[152:155], v[44:47]
	v_mfma_f32_16x16x32_bf16 v[36:39], v[88:91], v[166:169], v[36:39]
	v_mfma_f32_16x16x32_bf16 v[128:131], v[68:71], v[182:185], v[128:131]
	v_mfma_f32_16x16x32_bf16 v[32:35], v[88:91], v[182:185], v[32:35]
	v_mfma_f32_16x16x32_bf16 v[116:119], v[68:71], v[190:193], v[116:119]
	v_mfma_f32_16x16x32_bf16 v[20:23], v[88:91], v[190:193], v[20:23]
	v_mfma_f32_16x16x32_bf16 v[108:111], v[68:71], v[198:201], v[108:111]
	v_mfma_f32_16x16x32_bf16 v[12:15], v[88:91], v[198:201], v[12:15]
	v_mfma_f32_16x16x32_bf16 v[104:107], v[68:71], v[226:229], v[104:107]
	v_mfma_f32_16x16x32_bf16 v[8:11], v[88:91], v[226:229], v[8:11]
	v_mfma_f32_16x16x32_bf16 v[60:63], v[68:71], v[234:237], v[60:63]
	v_mfma_f32_16x16x32_bf16 v[0:3], v[88:91], v[234:237], v[0:3]
	v_mfma_f32_16x16x32_bf16 v[72:75], v[84:87], v[100:103], v[72:75]
	s_waitcnt lgkmcnt(0)
	v_mfma_f32_16x16x32_bf16 v[56:59], v[92:95], v[100:103], v[56:59]
	v_mfma_f32_16x16x32_bf16 v[96:99], v[68:71], v[152:155], v[140:143]
	v_mfma_f32_16x16x32_bf16 v[44:47], v[92:95], v[156:159], v[44:47]
	v_mfma_f32_16x16x32_bf16 v[100:103], v[68:71], v[166:169], v[132:135]
	v_mfma_f32_16x16x32_bf16 v[36:39], v[92:95], v[178:181], v[36:39]
	v_mfma_f32_16x16x32_bf16 v[128:131], v[84:87], v[186:189], v[128:131]
	v_mfma_f32_16x16x32_bf16 v[32:35], v[92:95], v[186:189], v[32:35]
	v_mfma_f32_16x16x32_bf16 v[116:119], v[84:87], v[194:197], v[116:119]
	v_mfma_f32_16x16x32_bf16 v[20:23], v[92:95], v[194:197], v[20:23]
	v_mfma_f32_16x16x32_bf16 v[108:111], v[84:87], v[202:205], v[108:111]
	v_mfma_f32_16x16x32_bf16 v[12:15], v[92:95], v[202:205], v[12:15]
	v_mfma_f32_16x16x32_bf16 v[104:107], v[84:87], v[230:233], v[104:107]
	v_mfma_f32_16x16x32_bf16 v[8:11], v[92:95], v[230:233], v[8:11]
	v_mfma_f32_16x16x32_bf16 v[60:63], v[84:87], v[238:241], v[60:63]
	v_mfma_f32_16x16x32_bf16 v[0:3], v[92:95], v[238:241], v[0:3]
	v_mfma_f32_16x16x32_bf16 v[96:99], v[84:87], v[156:159], v[96:99]
	v_mfma_f32_16x16x32_bf16 v[100:103], v[84:87], v[178:181], v[100:103]
	s_barrier
; #define PG8_STAGE(bufoff, gbase, voff) do { _Pragma("unroll") for (int _i = 0; _i < 2; ++_i) { \
;         const unsigned _m0 = ldsu + (unsigned)(bufoff) + ldsw + (unsigned)(_i * 8192); \
;         asm volatile("s_mov_b32 m0, %2\n\ts_nop 0\n\tglobal_load_lds_dwordx4 %0, %1" :: "v"((voff)[_i]), "s"((const char*)(gbase)), "s"(_m0) : "memory"); } } while (0)
; #define PG8_LDA(dst, b, h) do { _Pragma("unroll") for (int m = 0; m < 4; ++m) _Pragma("unroll") for (int k = 0; k < 2; ++k) dst[m][k] = *(const LAS bf16x8*)(lds + PG8_SA(b, h) + aoff + m * 2048 + k * 1024); } while (0)
; #define PG8_LDB(dst, b, h) do { _Pragma("unroll") for (int n = 0; n < 2; ++n) _Pragma("unroll") for (int k = 0; k < 2; ++k) dst[n][k] = *(const LAS bf16x8*)(lds + bbase[b][h] + n * 2048 + k * 1024); } while (0)
; #define PG8_WAIT_V(n) asm volatile("s_waitcnt vmcnt(" #n ")" ::: "memory")
; #define PG8_WAIT_L(n) asm volatile("s_waitcnt lgkmcnt(" #n ")" ::: "memory")
; #define PG8_BAR __builtin_amdgcn_s_barrier()
; #define PG8_SCHED __builtin_amdgcn_sched_barrier(0)
; template <class Epi>
; __device__ __forceinline__ void gemm_phase(LAS unsigned char* lds, const Gemm g, const StaticOrder& S, const Epi& E) {
;     ...
;             PG8_LDB(B0, 1, 0); PG8_SCHED; PG8_LDA(At, 1, 0); PG8_LDA(At2, 1, 1); PG8_STAGE(PG8_SB(0, 1), b2 + hstepB, voffB);
;             PG8_WAIT_V(8); PG8_WAIT_L(0); PG8_BAR; PG8_MMA2B(0, At, At2, B0); PG8_BAR; PG8_SCHED;
	ds_read_b128 v[68:71], v223
	ds_read_b128 v[84:87], v223 offset:1024
	ds_read_b128 v[88:91], v223 offset:2048
	ds_read_b128 v[92:95], v223 offset:3072
	ds_read_b128 v[132:135], v221 offset:32768
	ds_read_b128 v[140:143], v221 offset:33792
	ds_read_b128 v[152:155], v221 offset:34816
	ds_read_b128 v[156:159], v221 offset:35840
	ds_read_b128 v[166:169], v221 offset:36864
	ds_read_b128 v[178:181], v221 offset:37888
	ds_read_b128 v[182:185], v221 offset:38912
	ds_read_b128 v[186:189], v221 offset:39936
	ds_read_b128 v[190:193], v221 offset:49152
	ds_read_b128 v[194:197], v221 offset:50176
	ds_read_b128 v[198:201], v221 offset:51200
	ds_read_b128 v[202:205], v221 offset:52224
	ds_read_b128 v[226:229], v221 offset:53248
	ds_read_b128 v[230:233], v221 offset:54272
	ds_read_b128 v[234:237], v221 offset:55296
	ds_read_b128 v[238:241], v221 offset:56320
	s_add_u32 s10, s84, 0x40000
	s_addc_u32 s11, s85, 0
	s_mov_b32 m0, s53
	s_nop 0
	global_load_lds_dwordx4 v217, s[10:11]
	s_mov_b32 m0, s54
	s_nop 0
	global_load_lds_dwordx4 v219, s[10:11]
	s_waitcnt vmcnt(8)
	s_waitcnt lgkmcnt(0)
	s_barrier
	s_waitcnt lgkmcnt(14)
	v_mfma_f32_16x16x32_bf16 v[80:83], v[68:71], v[132:135], v[80:83]
	v_mfma_f32_16x16x32_bf16 v[76:79], v[88:91], v[132:135], v[76:79]
	s_waitcnt lgkmcnt(13)
	v_mfma_f32_16x16x32_bf16 v[148:151], v[68:71], v[152:155], v[148:151]
	v_mfma_f32_16x16x32_bf16 v[52:55], v[88:91], v[152:155], v[52:55]
	s_waitcnt lgkmcnt(11)
	v_mfma_f32_16x16x32_bf16 v[144:147], v[68:71], v[166:169], v[144:147]
	v_mfma_f32_16x16x32_bf16 v[48:51], v[88:91], v[166:169], v[48:51]
	s_waitcnt lgkmcnt(9)
	v_mfma_f32_16x16x32_bf16 v[136:139], v[68:71], v[182:185], v[136:139]
	v_mfma_f32_16x16x32_bf16 v[40:43], v[88:91], v[182:185], v[40:43]
	s_waitcnt lgkmcnt(7)
	v_mfma_f32_16x16x32_bf16 v[124:127], v[68:71], v[190:193], v[124:127]
	v_mfma_f32_16x16x32_bf16 v[28:31], v[88:91], v[190:193], v[28:31]
	s_waitcnt lgkmcnt(5)
	v_mfma_f32_16x16x32_bf16 v[120:123], v[68:71], v[198:201], v[120:123]
	v_mfma_f32_16x16x32_bf16 v[24:27], v[88:91], v[198:201], v[24:27]
	s_waitcnt lgkmcnt(3)
	v_mfma_f32_16x16x32_bf16 v[112:115], v[68:71], v[226:229], v[112:115]
	v_mfma_f32_16x16x32_bf16 v[16:19], v[88:91], v[226:229], v[16:19]
	s_waitcnt lgkmcnt(1)
	v_mfma_f32_16x16x32_bf16 v[64:67], v[68:71], v[234:237], v[64:67]
	v_mfma_f32_16x16x32_bf16 v[4:7], v[88:91], v[234:237], v[4:7]
	v_mfma_f32_16x16x32_bf16 v[80:83], v[84:87], v[140:143], v[80:83]
	v_mfma_f32_16x16x32_bf16 v[76:79], v[92:95], v[140:143], v[76:79]
	v_mfma_f32_16x16x32_bf16 v[148:151], v[84:87], v[156:159], v[148:151]
	v_mfma_f32_16x16x32_bf16 v[52:55], v[92:95], v[156:159], v[52:55]
	v_mfma_f32_16x16x32_bf16 v[144:147], v[84:87], v[178:181], v[144:147]
	v_mfma_f32_16x16x32_bf16 v[48:51], v[92:95], v[178:181], v[48:51]
	v_mfma_f32_16x16x32_bf16 v[136:139], v[84:87], v[186:189], v[136:139]
	v_mfma_f32_16x16x32_bf16 v[40:43], v[92:95], v[186:189], v[40:43]
	v_mfma_f32_16x16x32_bf16 v[124:127], v[84:87], v[194:197], v[124:127]
	v_mfma_f32_16x16x32_bf16 v[28:31], v[92:95], v[194:197], v[28:31]
	v_mfma_f32_16x16x32_bf16 v[120:123], v[84:87], v[202:205], v[120:123]
	v_mfma_f32_16x16x32_bf16 v[24:27], v[92:95], v[202:205], v[24:27]
	v_mfma_f32_16x16x32_bf16 v[112:115], v[84:87], v[230:233], v[112:115]
	v_mfma_f32_16x16x32_bf16 v[16:19], v[92:95], v[230:233], v[16:19]
	s_waitcnt lgkmcnt(0)
	v_mfma_f32_16x16x32_bf16 v[64:67], v[84:87], v[238:241], v[64:67]
	v_mfma_f32_16x16x32_bf16 v[4:7], v[92:95], v[238:241], v[4:7]
	s_barrier
; #define LAS __attribute__((address_space(3)))
; #define PG8_STAGE(bufoff, gbase, voff) do { _Pragma("unroll") for (int _i = 0; _i < 2; ++_i) { \
;         const unsigned _m0 = ldsu + (unsigned)(bufoff) + ldsw + (unsigned)(_i * 8192); \
;         asm volatile("s_mov_b32 m0, %2\n\ts_nop 0\n\tglobal_load_lds_dwordx4 %0, %1" :: "v"((voff)[_i]), "s"((const char*)(gbase)), "s"(_m0) : "memory"); } } while (0)
; #define PG8_LDB(dst, b, h) do { _Pragma("unroll") for (int n = 0; n < 2; ++n) _Pragma("unroll") for (int k = 0; k < 2; ++k) dst[n][k] = *(const LAS bf16x8*)(lds + bbase[b][h] + n * 2048 + k * 1024); } while (0)
; #define PG8_WAIT_V(n) asm volatile("s_waitcnt vmcnt(" #n ")" ::: "memory")
; #define PG8_WAIT_L(n) asm volatile("s_waitcnt lgkmcnt(" #n ")" ::: "memory")
; #define PG8_BAR __builtin_amdgcn_s_barrier()
; #define PG8_SCHED __builtin_amdgcn_sched_barrier(0)
; template <class Epi>
; __device__ __forceinline__ void gemm_phase(LAS unsigned char* lds, const Gemm g, const StaticOrder& S, const Epi& E) {
;     ...
;         for (int t = 0; t < nt; t += 2) {
;     ...
;             PG8_LDB(B0, 1, 1); PG8_STAGE(PG8_SB(1, 0), b3, voffB); PG8_STAGE(PG8_SA(1, 0), a3, voffA); PG8_STAGE(PG8_SA(1, 1), a3 + hstepA, voffA);
;             PG8_WAIT_V(8); PG8_WAIT_L(0); PG8_BAR; PG8_MMA2B(1, At, At2, B0); PG8_BAR; PG8_SCHED;
;     __device__ __forceinline__ void operator()(f32x4 (&acc)[2][2][4][2], const Unit& u, int wr, int wc, int fr, int fq) const {
;     ...
;         const int row0 = u.pm * 256 + wr * 64 + fr, colg0 = u.pn * 128 + wc * 32 + 8 * fq;
;         LAS float* rsL = hl + 2048; LAS float* cwL = hl + 2304;
;         { const int t = (wc * 4 + fq) * 16 + fr;
;           if (wr == 0) { const float* sp = ssq + ((size_t)u.pm * 256 + t) * 16; const f32x4 a = *(const f32x4*)sp, b = *(const f32x4*)(sp + 4), c = *(const f32x4*)(sp + 8), d = *(const f32x4*)(sp + 12);
;               const f32x4 q = (a + b) + (c + d); rsL[t] = rsqrtf(((q[0] + q[1]) + (q[2] + q[3])) * (1.0f / 1024.0f) + EPS); }
	s_add_u32 s10, s84, 0x80
	ds_read_b128 v[68:71], v224
	ds_read_b128 v[84:87], v224 offset:1024
	ds_read_b128 v[88:91], v224 offset:2048
	ds_read_b128 v[92:95], v224 offset:3072
	s_addc_u32 s11, s85, 0
	s_mov_b32 m0, s88
	s_nop 0
	global_load_lds_dwordx4 v217, s[10:11]
	s_mov_b32 m0, s89
	s_nop 0
	global_load_lds_dwordx4 v219, s[10:11]
	s_mov_b32 m0, s95
	s_nop 0
	global_load_lds_dwordx4 v216, s[16:17]
	s_mov_b32 m0, s37
	s_nop 0
	global_load_lds_dwordx4 v218, s[16:17]
	s_add_u32 s10, s14, 0x40080
	s_addc_u32 s11, s15, 0
	s_mov_b32 m0, s56
	s_nop 0
	global_load_lds_dwordx4 v216, s[10:11]
	s_mov_b32 m0, s57
	s_nop 0
	global_load_lds_dwordx4 v218, s[10:11]
	s_waitcnt vmcnt(8)
	s_waitcnt lgkmcnt(0)
	s_barrier
	s_waitcnt lgkmcnt(3)
	v_mfma_f32_16x16x32_bf16 v[72:75], v[68:71], v[132:135], v[72:75]
	s_waitcnt lgkmcnt(1)
	v_mfma_f32_16x16x32_bf16 v[56:59], v[88:91], v[132:135], v[56:59]
	v_mfma_f32_16x16x32_bf16 v[96:99], v[68:71], v[152:155], v[96:99]
	v_mfma_f32_16x16x32_bf16 v[72:75], v[84:87], v[140:143], v[72:75]
	s_waitcnt lgkmcnt(0)
	v_mfma_f32_16x16x32_bf16 v[56:59], v[92:95], v[140:143], v[56:59]
	v_mfma_f32_16x16x32_bf16 v[140:143], v[84:87], v[156:159], v[96:99]
	v_mfma_f32_16x16x32_bf16 v[96:99], v[68:71], v[166:169], v[100:103]
	v_mfma_f32_16x16x32_bf16 v[132:135], v[84:87], v[178:181], v[96:99]
	v_mfma_f32_16x16x32_bf16 v[96:99], v[68:71], v[182:185], v[128:131]
	v_mfma_f32_16x16x32_bf16 v[128:131], v[84:87], v[186:189], v[96:99]
	v_mfma_f32_16x16x32_bf16 v[96:99], v[68:71], v[190:193], v[116:119]
	v_mfma_f32_16x16x32_bf16 v[116:119], v[84:87], v[194:197], v[96:99]
	v_mfma_f32_16x16x32_bf16 v[96:99], v[68:71], v[198:201], v[108:111]
	v_mfma_f32_16x16x32_bf16 v[44:47], v[88:91], v[152:155], v[44:47]
	v_mfma_f32_16x16x32_bf16 v[36:39], v[88:91], v[166:169], v[36:39]
	v_mfma_f32_16x16x32_bf16 v[32:35], v[88:91], v[182:185], v[32:35]
	v_mfma_f32_16x16x32_bf16 v[20:23], v[88:91], v[190:193], v[20:23]
	v_mfma_f32_16x16x32_bf16 v[108:111], v[84:87], v[202:205], v[96:99]
	v_mfma_f32_16x16x32_bf16 v[12:15], v[88:91], v[198:201], v[12:15]
	v_mfma_f32_16x16x32_bf16 v[96:99], v[68:71], v[226:229], v[104:107]
	v_mfma_f32_16x16x32_bf16 v[8:11], v[88:91], v[226:229], v[8:11]
	v_mfma_f32_16x16x32_bf16 v[60:63], v[68:71], v[234:237], v[60:63]
	v_mfma_f32_16x16x32_bf16 v[0:3], v[88:91], v[234:237], v[0:3]
	v_mfma_f32_16x16x32_bf16 v[44:47], v[92:95], v[156:159], v[44:47]
	v_mfma_f32_16x16x32_bf16 v[36:39], v[92:95], v[178:181], v[36:39]
	v_mfma_f32_16x16x32_bf16 v[32:35], v[92:95], v[186:189], v[32:35]
	v_mfma_f32_16x16x32_bf16 v[20:23], v[92:95], v[194:197], v[20:23]
	v_mfma_f32_16x16x32_bf16 v[12:15], v[92:95], v[202:205], v[12:15]
	v_mfma_f32_16x16x32_bf16 v[104:107], v[84:87], v[230:233], v[96:99]
	v_mfma_f32_16x16x32_bf16 v[8:11], v[92:95], v[230:233], v[8:11]
	v_mfma_f32_16x16x32_bf16 v[60:63], v[84:87], v[238:241], v[60:63]
	v_mfma_f32_16x16x32_bf16 v[0:3], v[92:95], v[238:241], v[0:3]
	s_add_i32 s69, s69, 2
	s_add_u32 vcc_hi, vcc_hi, 0x100
	s_addc_u32 s68, s68, 0
	s_cmp_gt_u32 s69, 13
	s_mov_b64 s[10:11], s[12:13]
	s_barrier
	s_cbranch_scc0 .LBB0_1027
	s_and_b64 vcc, exec, s[90:91]
	s_cbranch_vccz .LBB0_1030
	v_lshlrev_b32_e32 v68, 4, v215
	v_add3_u32 v68, v214, s59, v68
	s_ashr_i32 s97, s96, 31
	s_lshl_b64 s[12:13], s[96:97], 14
	v_ashrrev_i32_e32 v69, 31, v68
	s_add_u32 s12, s18, s12
	s_addc_u32 s13, s19, s13
	v_lshlrev_b64 v[70:71], 6, v[68:69]
	v_lshl_add_u64 v[70:71], s[12:13], 0, v[70:71]
	global_load_dwordx4 v[86:89], v[70:71], off
	global_load_dwordx4 v[90:93], v[70:71], off offset:16
	global_load_dwordx4 v[94:97], v[70:71], off offset:32
	global_load_dwordx4 v[98:101], v[70:71], off offset:48
	s_barrier

; #define PG8_STAGE(bufoff, gbase, voff) do { _Pragma("unroll") for (int _i = 0; _i < 2; ++_i) { \
;         const unsigned _m0 = ldsu + (unsigned)(bufoff) + ldsw + (unsigned)(_i * 8192); \
;         asm volatile("s_mov_b32 m0, %2\n\ts_nop 0\n\tglobal_load_lds_dwordx4 %0, %1" :: "v"((voff)[_i]), "s"((const char*)(gbase)), "s"(_m0) : "memory"); } } while (0)
; #define PG8_LDA(dst, b, h) do { _Pragma("unroll") for (int m = 0; m < 4; ++m) _Pragma("unroll") for (int k = 0; k < 2; ++k) dst[m][k] = *(const LAS bf16x8*)(lds + PG8_SA(b, h) + aoff + m * 2048 + k * 1024); } while (0)
; #define PG8_LDB(dst, b, h) do { _Pragma("unroll") for (int n = 0; n < 2; ++n) _Pragma("unroll") for (int k = 0; k < 2; ++k) dst[n][k] = *(const LAS bf16x8*)(lds + bbase[b][h] + n * 2048 + k * 1024); } while (0)
; #define PG8_WAIT_V(n) asm volatile("s_waitcnt vmcnt(" #n ")" ::: "memory")
; #define PG8_WAIT_L(n) asm volatile("s_waitcnt lgkmcnt(" #n ")" ::: "memory")
; #define PG8_BAR __builtin_amdgcn_s_barrier()
; #define PG8_SCHED __builtin_amdgcn_sched_barrier(0)
; template <class Epi>
; __device__ __forceinline__ void gemm_phase(LAS unsigned char* lds, const Gemm g, const StaticOrder& S, const Epi& E) {
;     ...
;             const char* a2 = last ? nA : cA + (size_t)(t + 2) * kstep; const char* b2 = last ? nB : cB + (size_t)(t + 2) * kstep;
;             const char* a3 = a2 + kstep; const char* b3 = b2 + kstep;
;             const char* b1 = cB + (size_t)(t + 1) * kstep;
;             PG8_LDB(B0, 0, 0); PG8_SCHED; PG8_LDA(At, 0, 0); PG8_LDA(At2, 0, 1); PG8_STAGE(PG8_SB(1, 1), b1 + hstepB, voffB);
;             PG8_WAIT_V(8); PG8_WAIT_L(0); PG8_BAR; PG8_MMA2B(0, At, At2, B0); PG8_BAR; PG8_SCHED;
;             PG8_LDB(B0, 0, 1); PG8_STAGE(PG8_SB(0, 0), b2, voffB); PG8_STAGE(PG8_SA(0, 0), a2, voffA); PG8_STAGE(PG8_SA(0, 1), a2 + hstepA, voffA);
;             PG8_WAIT_V(8); PG8_WAIT_L(0); PG8_BAR; PG8_MMA2B(1, At, At2, B0); PG8_BAR; PG8_SCHED;
.LBB0_1140:
	ds_read_b128 v[128:131], v138
	ds_read_b128 v[144:147], v138 offset:1024
	ds_read_b128 v[148:151], v138 offset:2048
	ds_read_b128 v[152:155], v138 offset:3072
	s_cmp_eq_u32 s68, 40
	s_cselect_b32 s14, s4, s80
	s_cselect_b32 s15, s5, s81
	s_cselect_b32 s42, s10, s82
	s_cselect_b32 s43, s11, s83
	s_add_u32 s16, s14, 0x80
	s_addc_u32 s17, s15, 0
	s_add_u32 s38, s42, 0x80
	s_addc_u32 s39, s43, 0
	ds_read_b128 v[156:159], v139
	ds_read_b128 v[166:169], v139 offset:1024
	ds_read_b128 v[178:181], v139 offset:2048
	ds_read_b128 v[182:185], v139 offset:3072
	ds_read_b128 v[186:189], v139 offset:4096
	ds_read_b128 v[190:193], v139 offset:5120
	ds_read_b128 v[194:197], v139 offset:6144
	ds_read_b128 v[198:201], v139 offset:7168
	ds_read_b128 v[202:205], v139 offset:16384
	ds_read_b128 v[214:217], v139 offset:17408
	ds_read_b128 v[218:221], v139 offset:18432
	ds_read_b128 v[222:225], v139 offset:19456
	ds_read_b128 v[226:229], v139 offset:20480
	ds_read_b128 v[230:233], v139 offset:21504
	ds_read_b128 v[234:237], v139 offset:22528
	ds_read_b128 v[238:241], v139 offset:23552
	s_mov_b32 m0, s61
	s_nop 0
	global_load_lds_dwordx4 v133, s[12:13]
	s_mov_b32 m0, s63
	s_nop 0
	global_load_lds_dwordx4 v135, s[12:13]
	s_waitcnt vmcnt(8)
	s_waitcnt lgkmcnt(0)
	s_barrier
	s_waitcnt lgkmcnt(14)
	v_mfma_f32_16x16x32_bf16 v[124:127], v[128:131], v[156:159], v[124:127]
	v_mfma_f32_16x16x32_bf16 v[120:123], v[148:151], v[156:159], v[120:123]
	s_waitcnt lgkmcnt(13)
	v_mfma_f32_16x16x32_bf16 v[108:111], v[128:131], v[178:181], v[108:111]
	v_mfma_f32_16x16x32_bf16 v[104:107], v[148:151], v[178:181], v[104:107]
	s_waitcnt lgkmcnt(11)
	v_mfma_f32_16x16x32_bf16 v[92:95], v[128:131], v[186:189], v[92:95]
	v_mfma_f32_16x16x32_bf16 v[88:91], v[148:151], v[186:189], v[88:91]
	s_waitcnt lgkmcnt(9)
	v_mfma_f32_16x16x32_bf16 v[76:79], v[128:131], v[194:197], v[76:79]
	v_mfma_f32_16x16x32_bf16 v[72:75], v[148:151], v[194:197], v[72:75]
	s_waitcnt lgkmcnt(7)
	v_mfma_f32_16x16x32_bf16 v[60:63], v[128:131], v[202:205], v[60:63]
	v_mfma_f32_16x16x32_bf16 v[56:59], v[148:151], v[202:205], v[56:59]
	s_waitcnt lgkmcnt(5)
	v_mfma_f32_16x16x32_bf16 v[44:47], v[128:131], v[218:221], v[44:47]
	v_mfma_f32_16x16x32_bf16 v[40:43], v[148:151], v[218:221], v[40:43]
	s_waitcnt lgkmcnt(3)
	v_mfma_f32_16x16x32_bf16 v[28:31], v[128:131], v[226:229], v[28:31]
	v_mfma_f32_16x16x32_bf16 v[24:27], v[148:151], v[226:229], v[24:27]
	s_waitcnt lgkmcnt(1)
	v_mfma_f32_16x16x32_bf16 v[12:15], v[128:131], v[234:237], v[12:15]
	v_mfma_f32_16x16x32_bf16 v[8:11], v[148:151], v[234:237], v[8:11]
	v_mfma_f32_16x16x32_bf16 v[124:127], v[144:147], v[166:169], v[124:127]
	v_mfma_f32_16x16x32_bf16 v[120:123], v[152:155], v[166:169], v[120:123]
	v_mfma_f32_16x16x32_bf16 v[108:111], v[144:147], v[182:185], v[108:111]
	v_mfma_f32_16x16x32_bf16 v[104:107], v[152:155], v[182:185], v[104:107]
	v_mfma_f32_16x16x32_bf16 v[92:95], v[144:147], v[190:193], v[92:95]
	v_mfma_f32_16x16x32_bf16 v[88:91], v[152:155], v[190:193], v[88:91]
	v_mfma_f32_16x16x32_bf16 v[76:79], v[144:147], v[198:201], v[76:79]
	v_mfma_f32_16x16x32_bf16 v[72:75], v[152:155], v[198:201], v[72:75]
	v_mfma_f32_16x16x32_bf16 v[60:63], v[144:147], v[214:217], v[60:63]
	v_mfma_f32_16x16x32_bf16 v[56:59], v[152:155], v[214:217], v[56:59]
	v_mfma_f32_16x16x32_bf16 v[44:47], v[144:147], v[222:225], v[44:47]
	v_mfma_f32_16x16x32_bf16 v[40:43], v[152:155], v[222:225], v[40:43]
	v_mfma_f32_16x16x32_bf16 v[28:31], v[144:147], v[230:233], v[28:31]
	v_mfma_f32_16x16x32_bf16 v[24:27], v[152:155], v[230:233], v[24:27]
	s_waitcnt lgkmcnt(0)
	v_mfma_f32_16x16x32_bf16 v[12:15], v[144:147], v[238:241], v[12:15]
	v_mfma_f32_16x16x32_bf16 v[8:11], v[152:155], v[238:241], v[8:11]
	s_barrier
	ds_read_b128 v[128:131], v140
	ds_read_b128 v[144:147], v140 offset:1024
	ds_read_b128 v[148:151], v140 offset:2048
	ds_read_b128 v[152:155], v140 offset:3072
	s_mov_b32 m0, s48
	s_nop 0
	global_load_lds_dwordx4 v133, s[42:43]
	s_mov_b32 m0, s49
	s_nop 0
	global_load_lds_dwordx4 v135, s[42:43]
	s_mov_b32 m0, s47
	s_nop 0
	global_load_lds_dwordx4 v132, s[14:15]
	s_mov_b32 m0, s50
	s_nop 0
	global_load_lds_dwordx4 v134, s[14:15]
	s_add_u32 s84, s14, 0xb0000
	s_addc_u32 s85, s15, 0
	s_mov_b32 m0, s51
	s_nop 0
	global_load_lds_dwordx4 v132, s[84:85]
	s_mov_b32 m0, s52
	s_nop 0
	global_load_lds_dwordx4 v134, s[84:85]
	s_waitcnt vmcnt(8)
	s_waitcnt lgkmcnt(0)
	s_barrier
	s_waitcnt lgkmcnt(3)
	v_mfma_f32_16x16x32_bf16 v[116:119], v[128:131], v[156:159], v[116:119]
	s_waitcnt lgkmcnt(1)
	v_mfma_f32_16x16x32_bf16 v[112:115], v[148:151], v[156:159], v[112:115]
	v_mfma_f32_16x16x32_bf16 v[100:103], v[128:131], v[178:181], v[100:103]
	v_mfma_f32_16x16x32_bf16 v[96:99], v[148:151], v[178:181], v[96:99]
	v_mfma_f32_16x16x32_bf16 v[84:87], v[128:131], v[186:189], v[84:87]
	v_mfma_f32_16x16x32_bf16 v[80:83], v[148:151], v[186:189], v[80:83]
	v_mfma_f32_16x16x32_bf16 v[68:71], v[128:131], v[194:197], v[68:71]
	v_mfma_f32_16x16x32_bf16 v[64:67], v[148:151], v[194:197], v[64:67]
	v_mfma_f32_16x16x32_bf16 v[52:55], v[128:131], v[202:205], v[52:55]
	v_mfma_f32_16x16x32_bf16 v[48:51], v[148:151], v[202:205], v[48:51]
	v_mfma_f32_16x16x32_bf16 v[36:39], v[128:131], v[218:221], v[36:39]
	v_mfma_f32_16x16x32_bf16 v[32:35], v[148:151], v[218:221], v[32:35]
	v_mfma_f32_16x16x32_bf16 v[20:23], v[128:131], v[226:229], v[20:23]
	v_mfma_f32_16x16x32_bf16 v[16:19], v[148:151], v[226:229], v[16:19]
	v_mfma_f32_16x16x32_bf16 v[4:7], v[128:131], v[234:237], v[4:7]
	v_mfma_f32_16x16x32_bf16 v[0:3], v[148:151], v[234:237], v[0:3]
	v_mfma_f32_16x16x32_bf16 v[116:119], v[144:147], v[166:169], v[116:119]
	s_waitcnt lgkmcnt(0)
	v_mfma_f32_16x16x32_bf16 v[112:115], v[152:155], v[166:169], v[112:115]
	v_mfma_f32_16x16x32_bf16 v[100:103], v[144:147], v[182:185], v[100:103]
	v_mfma_f32_16x16x32_bf16 v[96:99], v[152:155], v[182:185], v[96:99]
	v_mfma_f32_16x16x32_bf16 v[84:87], v[144:147], v[190:193], v[84:87]
	v_mfma_f32_16x16x32_bf16 v[80:83], v[152:155], v[190:193], v[80:83]
	v_mfma_f32_16x16x32_bf16 v[68:71], v[144:147], v[198:201], v[68:71]
	v_mfma_f32_16x16x32_bf16 v[64:67], v[152:155], v[198:201], v[64:67]
	v_mfma_f32_16x16x32_bf16 v[52:55], v[144:147], v[214:217], v[52:55]
	v_mfma_f32_16x16x32_bf16 v[48:51], v[152:155], v[214:217], v[48:51]
	v_mfma_f32_16x16x32_bf16 v[36:39], v[144:147], v[222:225], v[36:39]
	v_mfma_f32_16x16x32_bf16 v[32:35], v[152:155], v[222:225], v[32:35]
	v_mfma_f32_16x16x32_bf16 v[20:23], v[144:147], v[230:233], v[20:23]
	v_mfma_f32_16x16x32_bf16 v[16:19], v[152:155], v[230:233], v[16:19]
	v_mfma_f32_16x16x32_bf16 v[4:7], v[144:147], v[238:241], v[4:7]
	v_mfma_f32_16x16x32_bf16 v[0:3], v[152:155], v[238:241], v[0:3]
	s_barrier
; #define PG8_STAGE(bufoff, gbase, voff) do { _Pragma("unroll") for (int _i = 0; _i < 2; ++_i) { \
;         const unsigned _m0 = ldsu + (unsigned)(bufoff) + ldsw + (unsigned)(_i * 8192); \
;         asm volatile("s_mov_b32 m0, %2\n\ts_nop 0\n\tglobal_load_lds_dwordx4 %0, %1" :: "v"((voff)[_i]), "s"((const char*)(gbase)), "s"(_m0) : "memory"); } } while (0)
; #define PG8_LDA(dst, b, h) do { _Pragma("unroll") for (int m = 0; m < 4; ++m) _Pragma("unroll") for (int k = 0; k < 2; ++k) dst[m][k] = *(const LAS bf16x8*)(lds + PG8_SA(b, h) + aoff + m * 2048 + k * 1024); } while (0)
; #define PG8_LDB(dst, b, h) do { _Pragma("unroll") for (int n = 0; n < 2; ++n) _Pragma("unroll") for (int k = 0; k < 2; ++k) dst[n][k] = *(const LAS bf16x8*)(lds + bbase[b][h] + n * 2048 + k * 1024); } while (0)
; #define PG8_WAIT_V(n) asm volatile("s_waitcnt vmcnt(" #n ")" ::: "memory")
; #define PG8_WAIT_L(n) asm volatile("s_waitcnt lgkmcnt(" #n ")" ::: "memory")
; #define PG8_BAR __builtin_amdgcn_s_barrier()
; #define PG8_SCHED __builtin_amdgcn_sched_barrier(0)
; template <class Epi>
; __device__ __forceinline__ void gemm_phase(LAS unsigned char* lds, const Gemm g, const StaticOrder& S, const Epi& E) {
;     ...
;         for (int t = 0; t < nt; t += 2) {
;     ...
;             PG8_LDB(B0, 1, 0); PG8_SCHED; PG8_LDA(At, 1, 0); PG8_LDA(At2, 1, 1); PG8_STAGE(PG8_SB(0, 1), b2 + hstepB, voffB);
;             PG8_WAIT_V(8); PG8_WAIT_L(0); PG8_BAR; PG8_MMA2B(0, At, At2, B0); PG8_BAR; PG8_SCHED;
;             PG8_LDB(B0, 1, 1); PG8_STAGE(PG8_SB(1, 0), b3, voffB); PG8_STAGE(PG8_SA(1, 0), a3, voffA); PG8_STAGE(PG8_SA(1, 1), a3 + hstepA, voffA);
;             PG8_WAIT_V(8); PG8_WAIT_L(0); PG8_BAR; PG8_MMA2B(1, At, At2, B0); PG8_BAR; PG8_SCHED;
;     ...
;         if (wr == 0) PG8_BAR;
	ds_read_b128 v[128:131], v141
	ds_read_b128 v[144:147], v141 offset:1024
	ds_read_b128 v[148:151], v141 offset:2048
	ds_read_b128 v[152:155], v141 offset:3072
	ds_read_b128 v[156:159], v139 offset:32768
	ds_read_b128 v[166:169], v139 offset:33792
	ds_read_b128 v[178:181], v139 offset:34816
	ds_read_b128 v[182:185], v139 offset:35840
	ds_read_b128 v[186:189], v139 offset:36864
	ds_read_b128 v[190:193], v139 offset:37888
	ds_read_b128 v[194:197], v139 offset:38912
	ds_read_b128 v[198:201], v139 offset:39936
	ds_read_b128 v[202:205], v139 offset:49152
	ds_read_b128 v[214:217], v139 offset:50176
	ds_read_b128 v[218:221], v139 offset:51200
	ds_read_b128 v[222:225], v139 offset:52224
	ds_read_b128 v[226:229], v139 offset:53248
	ds_read_b128 v[230:233], v139 offset:54272
	ds_read_b128 v[234:237], v139 offset:55296
	ds_read_b128 v[238:241], v139 offset:56320
	s_add_u32 s42, s42, 0xb0000
	s_addc_u32 s43, s43, 0
	s_mov_b32 m0, s53
	s_nop 0
	global_load_lds_dwordx4 v133, s[42:43]
	s_mov_b32 m0, s54
	s_nop 0
	global_load_lds_dwordx4 v135, s[42:43]
	s_waitcnt vmcnt(8)
	s_waitcnt lgkmcnt(0)
	s_barrier
	s_waitcnt lgkmcnt(14)
	v_mfma_f32_16x16x32_bf16 v[124:127], v[128:131], v[156:159], v[124:127]
	v_mfma_f32_16x16x32_bf16 v[120:123], v[148:151], v[156:159], v[120:123]
	s_waitcnt lgkmcnt(13)
	v_mfma_f32_16x16x32_bf16 v[108:111], v[128:131], v[178:181], v[108:111]
	v_mfma_f32_16x16x32_bf16 v[104:107], v[148:151], v[178:181], v[104:107]
	s_waitcnt lgkmcnt(11)
	v_mfma_f32_16x16x32_bf16 v[92:95], v[128:131], v[186:189], v[92:95]
	v_mfma_f32_16x16x32_bf16 v[88:91], v[148:151], v[186:189], v[88:91]
	s_waitcnt lgkmcnt(9)
	v_mfma_f32_16x16x32_bf16 v[76:79], v[128:131], v[194:197], v[76:79]
	v_mfma_f32_16x16x32_bf16 v[72:75], v[148:151], v[194:197], v[72:75]
	s_waitcnt lgkmcnt(7)
	v_mfma_f32_16x16x32_bf16 v[60:63], v[128:131], v[202:205], v[60:63]
	v_mfma_f32_16x16x32_bf16 v[56:59], v[148:151], v[202:205], v[56:59]
	s_waitcnt lgkmcnt(5)
	v_mfma_f32_16x16x32_bf16 v[44:47], v[128:131], v[218:221], v[44:47]
	v_mfma_f32_16x16x32_bf16 v[40:43], v[148:151], v[218:221], v[40:43]
	s_waitcnt lgkmcnt(3)
	v_mfma_f32_16x16x32_bf16 v[28:31], v[128:131], v[226:229], v[28:31]
	v_mfma_f32_16x16x32_bf16 v[24:27], v[148:151], v[226:229], v[24:27]
	s_waitcnt lgkmcnt(1)
	v_mfma_f32_16x16x32_bf16 v[12:15], v[128:131], v[234:237], v[12:15]
	v_mfma_f32_16x16x32_bf16 v[8:11], v[148:151], v[234:237], v[8:11]
	v_mfma_f32_16x16x32_bf16 v[124:127], v[144:147], v[166:169], v[124:127]
	v_mfma_f32_16x16x32_bf16 v[120:123], v[152:155], v[166:169], v[120:123]
	v_mfma_f32_16x16x32_bf16 v[108:111], v[144:147], v[182:185], v[108:111]
	v_mfma_f32_16x16x32_bf16 v[104:107], v[152:155], v[182:185], v[104:107]
	v_mfma_f32_16x16x32_bf16 v[92:95], v[144:147], v[190:193], v[92:95]
	v_mfma_f32_16x16x32_bf16 v[88:91], v[152:155], v[190:193], v[88:91]
	v_mfma_f32_16x16x32_bf16 v[76:79], v[144:147], v[198:201], v[76:79]
	v_mfma_f32_16x16x32_bf16 v[72:75], v[152:155], v[198:201], v[72:75]
	v_mfma_f32_16x16x32_bf16 v[60:63], v[144:147], v[214:217], v[60:63]
	v_mfma_f32_16x16x32_bf16 v[56:59], v[152:155], v[214:217], v[56:59]
	v_mfma_f32_16x16x32_bf16 v[44:47], v[144:147], v[222:225], v[44:47]
	v_mfma_f32_16x16x32_bf16 v[40:43], v[152:155], v[222:225], v[40:43]
	v_mfma_f32_16x16x32_bf16 v[28:31], v[144:147], v[230:233], v[28:31]
	v_mfma_f32_16x16x32_bf16 v[24:27], v[152:155], v[230:233], v[24:27]
	s_waitcnt lgkmcnt(0)
	v_mfma_f32_16x16x32_bf16 v[12:15], v[144:147], v[238:241], v[12:15]
	v_mfma_f32_16x16x32_bf16 v[8:11], v[152:155], v[238:241], v[8:11]
	s_barrier
	ds_read_b128 v[128:131], v142
	ds_read_b128 v[144:147], v142 offset:1024
	ds_read_b128 v[148:151], v142 offset:2048
	ds_read_b128 v[152:155], v142 offset:3072
	s_mov_b32 m0, s55
	s_nop 0
	global_load_lds_dwordx4 v133, s[38:39]
	s_mov_b32 m0, s56
	s_nop 0
	global_load_lds_dwordx4 v135, s[38:39]
	s_mov_b32 m0, s57
	s_nop 0
	global_load_lds_dwordx4 v132, s[16:17]
	s_mov_b32 m0, s58
	s_nop 0
	global_load_lds_dwordx4 v134, s[16:17]
	s_add_u32 s14, s14, 0xb0080
	s_addc_u32 s15, s15, 0
	s_mov_b32 m0, s59
	s_nop 0
	global_load_lds_dwordx4 v132, s[14:15]
	s_mov_b32 m0, s60
	s_nop 0
	global_load_lds_dwordx4 v134, s[14:15]
	s_waitcnt vmcnt(8)
	s_waitcnt lgkmcnt(0)
	s_barrier
	s_waitcnt lgkmcnt(3)
	v_mfma_f32_16x16x32_bf16 v[116:119], v[128:131], v[156:159], v[116:119]
	s_waitcnt lgkmcnt(1)
	v_mfma_f32_16x16x32_bf16 v[112:115], v[148:151], v[156:159], v[112:115]
	v_mfma_f32_16x16x32_bf16 v[100:103], v[128:131], v[178:181], v[100:103]
	v_mfma_f32_16x16x32_bf16 v[96:99], v[148:151], v[178:181], v[96:99]
	v_mfma_f32_16x16x32_bf16 v[84:87], v[128:131], v[186:189], v[84:87]
	v_mfma_f32_16x16x32_bf16 v[80:83], v[148:151], v[186:189], v[80:83]
	v_mfma_f32_16x16x32_bf16 v[68:71], v[128:131], v[194:197], v[68:71]
	v_mfma_f32_16x16x32_bf16 v[64:67], v[148:151], v[194:197], v[64:67]
	v_mfma_f32_16x16x32_bf16 v[52:55], v[128:131], v[202:205], v[52:55]
	v_mfma_f32_16x16x32_bf16 v[48:51], v[148:151], v[202:205], v[48:51]
	v_mfma_f32_16x16x32_bf16 v[36:39], v[128:131], v[218:221], v[36:39]
	v_mfma_f32_16x16x32_bf16 v[32:35], v[148:151], v[218:221], v[32:35]
	v_mfma_f32_16x16x32_bf16 v[20:23], v[128:131], v[226:229], v[20:23]
	v_mfma_f32_16x16x32_bf16 v[16:19], v[148:151], v[226:229], v[16:19]
	v_mfma_f32_16x16x32_bf16 v[4:7], v[128:131], v[234:237], v[4:7]
	v_mfma_f32_16x16x32_bf16 v[0:3], v[148:151], v[234:237], v[0:3]
	v_mfma_f32_16x16x32_bf16 v[116:119], v[144:147], v[166:169], v[116:119]
	s_waitcnt lgkmcnt(0)
	v_mfma_f32_16x16x32_bf16 v[112:115], v[152:155], v[166:169], v[112:115]
	v_mfma_f32_16x16x32_bf16 v[100:103], v[144:147], v[182:185], v[100:103]
	v_mfma_f32_16x16x32_bf16 v[96:99], v[152:155], v[182:185], v[96:99]
	v_mfma_f32_16x16x32_bf16 v[84:87], v[144:147], v[190:193], v[84:87]
	v_mfma_f32_16x16x32_bf16 v[80:83], v[152:155], v[190:193], v[80:83]
	v_mfma_f32_16x16x32_bf16 v[68:71], v[144:147], v[198:201], v[68:71]
	v_mfma_f32_16x16x32_bf16 v[64:67], v[152:155], v[198:201], v[64:67]
	v_mfma_f32_16x16x32_bf16 v[52:55], v[144:147], v[214:217], v[52:55]
	v_mfma_f32_16x16x32_bf16 v[48:51], v[152:155], v[214:217], v[48:51]
	v_mfma_f32_16x16x32_bf16 v[36:39], v[144:147], v[222:225], v[36:39]
	v_mfma_f32_16x16x32_bf16 v[32:35], v[152:155], v[222:225], v[32:35]
	v_mfma_f32_16x16x32_bf16 v[20:23], v[144:147], v[230:233], v[20:23]
	v_mfma_f32_16x16x32_bf16 v[16:19], v[152:155], v[230:233], v[16:19]
	v_mfma_f32_16x16x32_bf16 v[4:7], v[144:147], v[238:241], v[4:7]
	v_mfma_f32_16x16x32_bf16 v[0:3], v[152:155], v[238:241], v[0:3]
	s_add_i32 s68, s68, 2
	s_add_u32 s12, s12, 0x100
	s_addc_u32 s13, s13, 0
	s_add_u32 s80, s80, 0x100
	s_addc_u32 s81, s81, 0
	s_add_u32 s82, s82, 0x100
	s_addc_u32 s83, s83, 0
	s_cmp_gt_u32 s68, 41
	s_barrier
	s_cbranch_scc0 .LBB0_1140
	s_and_b64 vcc, exec, s[2:3]
	s_cbranch_vccz .LBB0_1143
	s_barrier
